# v13
# speedup vs baseline: 1.0044x; 1.0044x over previous
; #define STAGE(P, BASE, br, kt) do { const u16* _gb = (BASE) + (long)(br)*K + (long)(kt)*BK; \
;     unsigned _ld = lds0 + (unsigned)((char*)(P) - (char*)shm) + wv * 1024u; \
;     glds_s(_gb, voff0, _ld); glds_s(_gb, voff1, _ld + 8192u); } while (0)
; #define BAR __builtin_amdgcn_s_barrier()
; __device__ __forceinline__ void glds_s(const void* sbase, unsigned voff, unsigned lds_dst) {
;   unsigned keep;
;   asm volatile("s_mov_b32 %0, m0\n\ts_mov_b32 m0, %3\n\ts_nop 0\n\tglobal_load_lds_dwordx4 %2, %1\n\ts_mov_b32 m0, %0"
;                : "=&s"(keep) : "s"(sbase), "v"(voff), "s"(lds_dst) : "memory");
; }
;     ...
;     if (!staged) {
;       STAGE(SB(0, 0), ActK, bcol, 0); STAGE(SA(0, 0), WtK, brow, 0);
;       STAGE(SB(0, 1), ActK, bcol + HALF, 0); STAGE(SA(0, 1), WtK, brow + HALF, 0);
;       if (wr == 1) BAR;
.LBB0_18:
	s_xor_b64 s[22:23], s[22:23], -1
	s_andn2_b64 vcc, exec, s[22:23]
	s_mov_b64 s[34:35], -1
	s_cbranch_vccnz .LBB0_22
	s_ashr_i32 s19, s18, 31
	s_lshl_b64 s[22:23], s[18:19], 11
	s_add_u32 s24, s78, s22
	s_addc_u32 s25, s79, s23
	s_mov_b32 m0, s36
	s_nop 0
	global_load_lds_dwordx4 v198, s[24:25]
	s_nop 0
	s_mov_b32 m0, s38
	s_nop 0
	global_load_lds_dwordx4 v199, s[24:25]
	s_ashr_i32 s11, s10, 31
	s_lshl_b64 s[24:25], s[10:11], 11
	s_add_u32 s26, s52, s24
	s_addc_u32 s27, s53, s25
	s_mov_b32 m0, s37
	s_nop 0
	global_load_lds_dwordx4 v198, s[26:27]
	s_nop 0
	s_mov_b32 m0, s39
	s_nop 0
	global_load_lds_dwordx4 v199, s[26:27]
	s_add_u32 s26, s22, 0x40000
	s_addc_u32 s27, s23, 0
	s_add_u32 s30, s78, s26
	s_addc_u32 s31, s79, s27
	s_mov_b32 m0, s40
	s_nop 0
	global_load_lds_dwordx4 v198, s[30:31]
	s_nop 0
	s_mov_b32 m0, s41
	s_nop 0
	global_load_lds_dwordx4 v199, s[30:31]
	s_add_u32 s30, s24, 0x40000
	s_addc_u32 s31, s25, 0
	s_add_u32 s34, s52, s30
	s_addc_u32 s35, s53, s31
	s_mov_b32 m0, s42
	s_nop 0
	global_load_lds_dwordx4 v198, s[34:35]
	s_nop 0
	s_mov_b32 m0, s43
	s_nop 0
	global_load_lds_dwordx4 v199, s[34:35]
	s_and_saveexec_b64 s[34:35], s[54:55]
	s_cbranch_execz .LBB0_21
	s_barrier

; #define STAGE(P, BASE, br, kt) do { const u16* _gb = (BASE) + (long)(br)*K + (long)(kt)*BK; \
;     unsigned _ld = lds0 + (unsigned)((char*)(P) - (char*)shm) + wv * 1024u; \
;     glds_s(_gb, voff0, _ld); glds_s(_gb, voff1, _ld + 8192u); } while (0)
; #define LDA(dst, b, h) for (int m = 0; m < 4; ++m) for (int k = 0; k < 2; ++k) \
;     dst[m][k] = *reinterpret_cast<const bf16x8*>((char*)SA(b, h) + lds_byte(wr * 64 + m * 16 + fr, k * 32 + fq * 8))
; #define LDB(dst, b, h) for (int n = 0; n < 2; ++n) for (int k = 0; k < 2; ++k) \
;     dst[n][k] = *reinterpret_cast<const bf16x8*>((char*)SB(b, h) + lds_byte(wc * 32 + n * 16 + fr, k * 32 + fq * 8))
; #define WAIT_V(n) asm volatile("s_waitcnt vmcnt(" #n ")" ::: "memory")
; #define WAIT_L(n) asm volatile("s_waitcnt lgkmcnt(" #n ")" ::: "memory")
; #define BAR __builtin_amdgcn_s_barrier()
; #define SCHED __builtin_amdgcn_sched_barrier(0)
;     ...
;     STAGE(SB(1, 0), ActK, bcol, 1); STAGE(SA(1, 0), WtK, brow, 1); STAGE(SB(1, 1), ActK, bcol + HALF, 1);
;     WAIT_V(6); BAR;
;     for (int t = 0; t < nt - 2; t += 2) {
;       LDB(B0, 0, 0); SCHED; LDA(At, 0, 0); STAGE(SA(1, 1), WtK, brow + HALF, t + 1);
;       WAIT_L(8); BAR; WAIT_L(0); MMA(0, 0, At, B0); BAR; SCHED;
.LBB0_26:
	s_add_u32 s11, s78, s22
	s_addc_u32 s13, s79, s23
	s_add_u32 s22, s11, 0x80
	s_addc_u32 s23, s13, 0
	s_mov_b32 m0, s44
	s_nop 0
	global_load_lds_dwordx4 v198, s[22:23]
	v_mov_b32_e32 v2, 0
	s_mov_b32 m0, s45
	s_nop 0
	global_load_lds_dwordx4 v199, s[22:23]
	s_add_u32 s17, s52, s24
	s_addc_u32 s19, s53, s25
	s_add_u32 s22, s17, 0x80
	s_addc_u32 s23, s19, 0
	s_add_u32 s26, s78, s26
	s_mov_b32 m0, s46
	s_nop 0
	global_load_lds_dwordx4 v198, s[22:23]
	s_addc_u32 s27, s79, s27
	s_mov_b32 m0, s47
	s_nop 0
	global_load_lds_dwordx4 v199, s[22:23]
	s_add_u32 s22, s26, 0x80
	s_addc_u32 s23, s27, 0
	s_mov_b32 m0, s48
	s_nop 0
	global_load_lds_dwordx4 v198, s[22:23]
	s_mov_b32 s34, -2
	s_mov_b32 m0, s49
	s_nop 0
	global_load_lds_dwordx4 v199, s[22:23]
	s_add_u32 s24, s52, s30
	s_addc_u32 s25, s53, s31
	s_add_u32 s30, s24, 0x100
	s_addc_u32 s31, s25, 0
	s_mov_b64 s[22:23], 0
	v_mov_b32_e32 v3, v2
	v_mov_b32_e32 v4, v2
	v_mov_b32_e32 v5, v2
	v_mov_b32_e32 v6, v2
	v_mov_b32_e32 v7, v2
	v_mov_b32_e32 v8, v2
	v_mov_b32_e32 v9, v2
	v_mov_b32_e32 v10, v2
	v_mov_b32_e32 v11, v2
	v_mov_b32_e32 v12, v2
	v_mov_b32_e32 v13, v2
	v_mov_b32_e32 v14, v2
	v_mov_b32_e32 v15, v2
	v_mov_b32_e32 v16, v2
	v_mov_b32_e32 v17, v2
	v_mov_b32_e32 v18, v2
	v_mov_b32_e32 v19, v2
	v_mov_b32_e32 v20, v2
	v_mov_b32_e32 v21, v2
	v_mov_b32_e32 v22, v2
	v_mov_b32_e32 v23, v2
	v_mov_b32_e32 v24, v2
	v_mov_b32_e32 v25, v2
	v_mov_b32_e32 v26, v2
	v_mov_b32_e32 v27, v2
	v_mov_b32_e32 v28, v2
	v_mov_b32_e32 v29, v2
	v_mov_b32_e32 v30, v2
	v_mov_b32_e32 v31, v2
	v_mov_b32_e32 v32, v2
	v_mov_b32_e32 v33, v2
	v_mov_b32_e32 v34, v2
	v_mov_b32_e32 v35, v2
	v_mov_b32_e32 v36, v2
	v_mov_b32_e32 v37, v2
	v_mov_b32_e32 v38, v2
	v_mov_b32_e32 v39, v2
	v_mov_b32_e32 v40, v2
	v_mov_b32_e32 v41, v2
	v_mov_b32_e32 v42, v2
	v_mov_b32_e32 v43, v2
	v_mov_b32_e32 v44, v2
	v_mov_b32_e32 v45, v2
	v_mov_b32_e32 v46, v2
	v_mov_b32_e32 v47, v2
	v_mov_b32_e32 v48, v2
	v_mov_b32_e32 v49, v2
	v_mov_b32_e32 v50, v2
	v_mov_b32_e32 v51, v2
	v_mov_b32_e32 v52, v2
	v_mov_b32_e32 v53, v2
	v_mov_b32_e32 v54, v2
	v_mov_b32_e32 v55, v2
	v_mov_b32_e32 v56, v2
	v_mov_b32_e32 v57, v2
	v_mov_b32_e32 v58, v2
	v_mov_b32_e32 v59, v2
	v_mov_b32_e32 v60, v2
	v_mov_b32_e32 v61, v2
	v_mov_b32_e32 v62, v2
	v_mov_b32_e32 v63, v2
	v_mov_b32_e32 v64, v2
	v_mov_b32_e32 v65, v2
	v_mov_b32_e32 v66, v2
	v_mov_b32_e32 v67, v2
	v_mov_b32_e32 v68, v2
	v_mov_b32_e32 v69, v2
	v_mov_b32_e32 v70, v2
	v_mov_b32_e32 v71, v2
	v_mov_b32_e32 v72, v2
	v_mov_b32_e32 v73, v2
	v_mov_b32_e32 v74, v2
	v_mov_b32_e32 v75, v2
	v_mov_b32_e32 v76, v2
	v_mov_b32_e32 v77, v2
	v_mov_b32_e32 v78, v2
	v_mov_b32_e32 v79, v2
	v_mov_b32_e32 v80, v2
	v_mov_b32_e32 v81, v2
	v_mov_b32_e32 v82, v2
	v_mov_b32_e32 v83, v2
	v_mov_b32_e32 v84, v2
	v_mov_b32_e32 v85, v2
	v_mov_b32_e32 v86, v2
	v_mov_b32_e32 v87, v2
	v_mov_b32_e32 v88, v2
	v_mov_b32_e32 v89, v2
	v_mov_b32_e32 v90, v2
	v_mov_b32_e32 v91, v2
	v_mov_b32_e32 v92, v2
	v_mov_b32_e32 v93, v2
	v_mov_b32_e32 v94, v2
	v_mov_b32_e32 v95, v2
	v_mov_b32_e32 v96, v2
	v_mov_b32_e32 v97, v2
	v_mov_b32_e32 v98, v2
	v_mov_b32_e32 v99, v2
	v_mov_b32_e32 v100, v2
	v_mov_b32_e32 v101, v2
	v_mov_b32_e32 v102, v2
	v_mov_b32_e32 v103, v2
	v_mov_b32_e32 v104, v2
	v_mov_b32_e32 v105, v2
	v_mov_b32_e32 v106, v2
	v_mov_b32_e32 v107, v2
	v_mov_b32_e32 v108, v2
	v_mov_b32_e32 v109, v2
	v_mov_b32_e32 v110, v2
	v_mov_b32_e32 v111, v2
	v_mov_b32_e32 v112, v2
	v_mov_b32_e32 v113, v2
	v_mov_b32_e32 v114, v2
	v_mov_b32_e32 v115, v2
	v_mov_b32_e32 v116, v2
	v_mov_b32_e32 v117, v2
	v_mov_b32_e32 v118, v2
	v_mov_b32_e32 v119, v2
	v_mov_b32_e32 v120, v2
	v_mov_b32_e32 v121, v2
	v_mov_b32_e32 v122, v2
	v_mov_b32_e32 v123, v2
	v_mov_b32_e32 v124, v2
	v_mov_b32_e32 v125, v2
	v_mov_b32_e32 v126, v2
	v_mov_b32_e32 v127, v2
	v_mov_b32_e32 v128, v2
	v_mov_b32_e32 v129, v2
	s_waitcnt vmcnt(6)
	s_barrier
.LBB0_27:
	ds_read_b128 v[130:133], v202
	ds_read_b128 v[134:137], v202 offset:1024
	ds_read_b128 v[138:141], v202 offset:2048
	ds_read_b128 v[142:145], v202 offset:3072
	ds_read_b128 v[146:149], v203
	ds_read_b128 v[150:153], v203 offset:1024
	ds_read_b128 v[154:157], v204
	ds_read_b128 v[158:161], v204 offset:1024
	ds_read_b128 v[162:165], v205
	ds_read_b128 v[166:169], v205 offset:1024
	ds_read_b128 v[170:173], v206
	ds_read_b128 v[174:177], v206 offset:1024
	s_add_u32 s35, s24, s22
	s_addc_u32 s87, s25, s23
	s_add_u32 s86, s35, 0x80
	s_addc_u32 s87, s87, 0
	s_mov_b32 m0, s50
	s_nop 0
	global_load_lds_dwordx4 v198, s[86:87]
	s_nop 0
	s_mov_b32 m0, s51
	s_nop 0
	global_load_lds_dwordx4 v199, s[86:87]
	s_waitcnt lgkmcnt(8)
	s_barrier
	s_waitcnt lgkmcnt(0)
	s_setprio 1
	s_waitcnt lgkmcnt(7)
	v_mfma_f32_16x16x32_bf16 v[126:129], v[146:149], v[130:133], v[126:129]
	v_mfma_f32_16x16x32_bf16 v[122:125], v[146:149], v[138:141], v[122:125]
	s_waitcnt lgkmcnt(5)
	v_mfma_f32_16x16x32_bf16 v[118:121], v[154:157], v[130:133], v[118:121]
	v_mfma_f32_16x16x32_bf16 v[114:117], v[154:157], v[138:141], v[114:117]
	s_waitcnt lgkmcnt(3)
	v_mfma_f32_16x16x32_bf16 v[110:113], v[162:165], v[130:133], v[110:113]
	v_mfma_f32_16x16x32_bf16 v[106:109], v[162:165], v[138:141], v[106:109]
	s_waitcnt lgkmcnt(1)
	v_mfma_f32_16x16x32_bf16 v[102:105], v[170:173], v[130:133], v[102:105]
	v_mfma_f32_16x16x32_bf16 v[98:101], v[170:173], v[138:141], v[98:101]
	v_mfma_f32_16x16x32_bf16 v[126:129], v[150:153], v[134:137], v[126:129]
	v_mfma_f32_16x16x32_bf16 v[122:125], v[150:153], v[142:145], v[122:125]
	v_mfma_f32_16x16x32_bf16 v[118:121], v[158:161], v[134:137], v[118:121]
	v_mfma_f32_16x16x32_bf16 v[114:117], v[158:161], v[142:145], v[114:117]
	v_mfma_f32_16x16x32_bf16 v[110:113], v[166:169], v[134:137], v[110:113]
	v_mfma_f32_16x16x32_bf16 v[106:109], v[166:169], v[142:145], v[106:109]
	s_waitcnt lgkmcnt(0)
	v_mfma_f32_16x16x32_bf16 v[102:105], v[174:177], v[134:137], v[102:105]
	v_mfma_f32_16x16x32_bf16 v[98:101], v[174:177], v[142:145], v[98:101]
	s_setprio 0
	s_barrier
; #define STAGE(P, BASE, br, kt) do { const u16* _gb = (BASE) + (long)(br)*K + (long)(kt)*BK; \
;     unsigned _ld = lds0 + (unsigned)((char*)(P) - (char*)shm) + wv * 1024u; \
;     glds_s(_gb, voff0, _ld); glds_s(_gb, voff1, _ld + 8192u); } while (0)
; #define LDA(dst, b, h) for (int m = 0; m < 4; ++m) for (int k = 0; k < 2; ++k) \
;     dst[m][k] = *reinterpret_cast<const bf16x8*>((char*)SA(b, h) + lds_byte(wr * 64 + m * 16 + fr, k * 32 + fq * 8))
; #define LDB(dst, b, h) for (int n = 0; n < 2; ++n) for (int k = 0; k < 2; ++k) \
;     dst[n][k] = *reinterpret_cast<const bf16x8*>((char*)SB(b, h) + lds_byte(wc * 32 + n * 16 + fr, k * 32 + fq * 8))
; #define WAIT_V(n) asm volatile("s_waitcnt vmcnt(" #n ")" ::: "memory")
; #define WAIT_L(n) asm volatile("s_waitcnt lgkmcnt(" #n ")" ::: "memory")
; #define BAR __builtin_amdgcn_s_barrier()
; #define SCHED __builtin_amdgcn_sched_barrier(0)
;     ...
;       LDB(B1, 0, 1); STAGE(SB(0, 0), ActK, bcol, t + 2);
;       BAR; WAIT_L(0); MMA(0, 1, At, B1); BAR;
;       LDA(At, 0, 1); STAGE(SA(0, 0), WtK, brow, t + 2);
;       BAR; WAIT_L(0); MMA(1, 0, At, B0); BAR; SCHED;
;       STAGE(SB(0, 1), ActK, bcol + HALF, t + 2);
;       WAIT_V(6); BAR; MMA(1, 1, At, B1); BAR;
;       LDB(B0, 1, 0); SCHED; LDA(At, 1, 0); STAGE(SA(0, 1), WtK, brow + HALF, t + 2);
;       WAIT_L(8); BAR; WAIT_L(0); MMA(0, 0, At, B0); BAR; SCHED;
	ds_read_b128 v[178:181], v207
	ds_read_b128 v[182:185], v207 offset:1024
	ds_read_b128 v[186:189], v207 offset:2048
	ds_read_b128 v[190:193], v207 offset:3072
	s_add_u32 s35, s11, s22
	s_addc_u32 s88, s13, s23
	s_add_u32 s86, s35, 0x100
	s_addc_u32 s87, s88, 0
	s_mov_b32 m0, s36
	s_nop 0
	global_load_lds_dwordx4 v198, s[86:87]
	s_nop 0
	s_mov_b32 m0, s38
	s_nop 0
	global_load_lds_dwordx4 v199, s[86:87]
	s_barrier
	s_waitcnt lgkmcnt(0)
	s_setprio 1
	s_waitcnt lgkmcnt(3)
	v_mfma_f32_16x16x32_bf16 v[94:97], v[146:149], v[178:181], v[94:97]
	s_waitcnt lgkmcnt(1)
	v_mfma_f32_16x16x32_bf16 v[90:93], v[146:149], v[186:189], v[90:93]
	v_mfma_f32_16x16x32_bf16 v[86:89], v[154:157], v[178:181], v[86:89]
	v_mfma_f32_16x16x32_bf16 v[82:85], v[154:157], v[186:189], v[82:85]
	v_mfma_f32_16x16x32_bf16 v[78:81], v[162:165], v[178:181], v[78:81]
	v_mfma_f32_16x16x32_bf16 v[74:77], v[162:165], v[186:189], v[74:77]
	v_mfma_f32_16x16x32_bf16 v[70:73], v[170:173], v[178:181], v[70:73]
	v_mfma_f32_16x16x32_bf16 v[66:69], v[170:173], v[186:189], v[66:69]
	v_mfma_f32_16x16x32_bf16 v[94:97], v[150:153], v[182:185], v[94:97]
	s_waitcnt lgkmcnt(0)
	v_mfma_f32_16x16x32_bf16 v[90:93], v[150:153], v[190:193], v[90:93]
	v_mfma_f32_16x16x32_bf16 v[86:89], v[158:161], v[182:185], v[86:89]
	v_mfma_f32_16x16x32_bf16 v[82:85], v[158:161], v[190:193], v[82:85]
	v_mfma_f32_16x16x32_bf16 v[78:81], v[166:169], v[182:185], v[78:81]
	v_mfma_f32_16x16x32_bf16 v[74:77], v[166:169], v[190:193], v[74:77]
	v_mfma_f32_16x16x32_bf16 v[70:73], v[174:177], v[182:185], v[70:73]
	v_mfma_f32_16x16x32_bf16 v[66:69], v[174:177], v[190:193], v[66:69]
	s_setprio 0
	s_barrier
	ds_read_b128 v[146:149], v203 offset:16384
	ds_read_b128 v[150:153], v203 offset:17408
	ds_read_b128 v[154:157], v204 offset:16384
	ds_read_b128 v[158:161], v204 offset:17408
	ds_read_b128 v[162:165], v205 offset:16384
	ds_read_b128 v[166:169], v205 offset:17408
	ds_read_b128 v[170:173], v206 offset:16384
	ds_read_b128 v[174:177], v206 offset:17408
	s_add_u32 s89, s17, s22
	s_addc_u32 s90, s19, s23
	s_add_u32 s86, s89, 0x100
	s_addc_u32 s87, s90, 0
	s_mov_b32 m0, s37
	s_nop 0
	global_load_lds_dwordx4 v198, s[86:87]
	s_nop 0
	s_mov_b32 m0, s39
	s_nop 0
	global_load_lds_dwordx4 v199, s[86:87]
	s_barrier
	s_waitcnt lgkmcnt(0)
	s_setprio 1
	s_waitcnt lgkmcnt(7)
	v_mfma_f32_16x16x32_bf16 v[62:65], v[146:149], v[130:133], v[62:65]
	v_mfma_f32_16x16x32_bf16 v[58:61], v[146:149], v[138:141], v[58:61]
	s_waitcnt lgkmcnt(5)
	v_mfma_f32_16x16x32_bf16 v[54:57], v[154:157], v[130:133], v[54:57]
	v_mfma_f32_16x16x32_bf16 v[50:53], v[154:157], v[138:141], v[50:53]
	s_waitcnt lgkmcnt(3)
	v_mfma_f32_16x16x32_bf16 v[46:49], v[162:165], v[130:133], v[46:49]
	v_mfma_f32_16x16x32_bf16 v[42:45], v[162:165], v[138:141], v[42:45]
	s_waitcnt lgkmcnt(1)
	v_mfma_f32_16x16x32_bf16 v[38:41], v[170:173], v[130:133], v[38:41]
	v_mfma_f32_16x16x32_bf16 v[34:37], v[170:173], v[138:141], v[34:37]
	v_mfma_f32_16x16x32_bf16 v[62:65], v[150:153], v[134:137], v[62:65]
	v_mfma_f32_16x16x32_bf16 v[58:61], v[150:153], v[142:145], v[58:61]
	v_mfma_f32_16x16x32_bf16 v[54:57], v[158:161], v[134:137], v[54:57]
	v_mfma_f32_16x16x32_bf16 v[50:53], v[158:161], v[142:145], v[50:53]
	v_mfma_f32_16x16x32_bf16 v[46:49], v[166:169], v[134:137], v[46:49]
	v_mfma_f32_16x16x32_bf16 v[42:45], v[166:169], v[142:145], v[42:45]
	s_waitcnt lgkmcnt(0)
	v_mfma_f32_16x16x32_bf16 v[38:41], v[174:177], v[134:137], v[38:41]
	v_mfma_f32_16x16x32_bf16 v[34:37], v[174:177], v[142:145], v[34:37]
	s_setprio 0
	s_barrier
	s_add_u32 s91, s26, s22
	s_addc_u32 s92, s27, s23
	s_add_u32 s86, s91, 0x100
	s_addc_u32 s87, s92, 0
	s_mov_b32 m0, s40
	s_nop 0
	global_load_lds_dwordx4 v198, s[86:87]
	s_nop 0
	s_mov_b32 m0, s41
	s_nop 0
	global_load_lds_dwordx4 v199, s[86:87]
	s_waitcnt vmcnt(6)
	s_barrier
	s_setprio 1
	v_mfma_f32_16x16x32_bf16 v[30:33], v[146:149], v[178:181], v[30:33]
	v_mfma_f32_16x16x32_bf16 v[26:29], v[146:149], v[186:189], v[26:29]
	v_mfma_f32_16x16x32_bf16 v[22:25], v[154:157], v[178:181], v[22:25]
	v_mfma_f32_16x16x32_bf16 v[18:21], v[154:157], v[186:189], v[18:21]
	v_mfma_f32_16x16x32_bf16 v[14:17], v[162:165], v[178:181], v[14:17]
	v_mfma_f32_16x16x32_bf16 v[10:13], v[162:165], v[186:189], v[10:13]
	v_mfma_f32_16x16x32_bf16 v[6:9], v[170:173], v[178:181], v[6:9]
	v_mfma_f32_16x16x32_bf16 v[2:5], v[170:173], v[186:189], v[2:5]
	v_mfma_f32_16x16x32_bf16 v[30:33], v[150:153], v[182:185], v[30:33]
	v_mfma_f32_16x16x32_bf16 v[26:29], v[150:153], v[190:193], v[26:29]
	v_mfma_f32_16x16x32_bf16 v[22:25], v[158:161], v[182:185], v[22:25]
	v_mfma_f32_16x16x32_bf16 v[18:21], v[158:161], v[190:193], v[18:21]
	v_mfma_f32_16x16x32_bf16 v[14:17], v[166:169], v[182:185], v[14:17]
	v_mfma_f32_16x16x32_bf16 v[10:13], v[166:169], v[190:193], v[10:13]
	v_mfma_f32_16x16x32_bf16 v[6:9], v[174:177], v[182:185], v[6:9]
	v_mfma_f32_16x16x32_bf16 v[2:5], v[174:177], v[190:193], v[2:5]
	s_setprio 0
	s_barrier
	ds_read_b128 v[130:133], v208
	ds_read_b128 v[134:137], v208 offset:1024
	ds_read_b128 v[138:141], v208 offset:2048
	ds_read_b128 v[142:145], v208 offset:3072
	ds_read_b128 v[146:149], v203 offset:32768
	ds_read_b128 v[150:153], v203 offset:33792
	ds_read_b128 v[154:157], v204 offset:32768
	ds_read_b128 v[158:161], v204 offset:33792
	ds_read_b128 v[162:165], v205 offset:32768
	ds_read_b128 v[166:169], v205 offset:33792
	ds_read_b128 v[170:173], v206 offset:32768
	ds_read_b128 v[174:177], v206 offset:33792
	s_add_u32 s86, s30, s22
	s_addc_u32 s87, s31, s23
	s_mov_b32 m0, s42
	s_nop 0
	global_load_lds_dwordx4 v198, s[86:87]
	s_nop 0
	s_mov_b32 m0, s43
	s_nop 0
	global_load_lds_dwordx4 v199, s[86:87]
	s_waitcnt lgkmcnt(8)
	s_barrier
; #define STAGE(P, BASE, br, kt) do { const u16* _gb = (BASE) + (long)(br)*K + (long)(kt)*BK; \
;     unsigned _ld = lds0 + (unsigned)((char*)(P) - (char*)shm) + wv * 1024u; \
;     glds_s(_gb, voff0, _ld); glds_s(_gb, voff1, _ld + 8192u); } while (0)
; #define LDA(dst, b, h) for (int m = 0; m < 4; ++m) for (int k = 0; k < 2; ++k) \
;     dst[m][k] = *reinterpret_cast<const bf16x8*>((char*)SA(b, h) + lds_byte(wr * 64 + m * 16 + fr, k * 32 + fq * 8))
; #define LDB(dst, b, h) for (int n = 0; n < 2; ++n) for (int k = 0; k < 2; ++k) \
;     dst[n][k] = *reinterpret_cast<const bf16x8*>((char*)SB(b, h) + lds_byte(wc * 32 + n * 16 + fr, k * 32 + fq * 8))
; #define WAIT_V(n) asm volatile("s_waitcnt vmcnt(" #n ")" ::: "memory")
; #define WAIT_L(n) asm volatile("s_waitcnt lgkmcnt(" #n ")" ::: "memory")
; #define BAR __builtin_amdgcn_s_barrier()
; #define SCHED __builtin_amdgcn_sched_barrier(0)
;     ...
;       WAIT_L(8); BAR; WAIT_L(0); MMA(0, 0, At, B0); BAR; SCHED;
;       LDB(B1, 1, 1); STAGE(SB(1, 0), ActK, bcol, t + 3);
;       BAR; WAIT_L(0); MMA(0, 1, At, B1); BAR;
;       LDA(At, 1, 1); STAGE(SA(1, 0), WtK, brow, t + 3);
;       BAR; WAIT_L(0); MMA(1, 0, At, B0); BAR; SCHED;
;       STAGE(SB(1, 1), ActK, bcol + HALF, t + 3);
;       WAIT_V(6); BAR; MMA(1, 1, At, B1); BAR;
	s_waitcnt lgkmcnt(0)
	s_setprio 1
	s_waitcnt lgkmcnt(7)
	v_mfma_f32_16x16x32_bf16 v[126:129], v[146:149], v[130:133], v[126:129]
	v_mfma_f32_16x16x32_bf16 v[122:125], v[146:149], v[138:141], v[122:125]
	s_waitcnt lgkmcnt(5)
	v_mfma_f32_16x16x32_bf16 v[118:121], v[154:157], v[130:133], v[118:121]
	v_mfma_f32_16x16x32_bf16 v[114:117], v[154:157], v[138:141], v[114:117]
	s_waitcnt lgkmcnt(3)
	v_mfma_f32_16x16x32_bf16 v[110:113], v[162:165], v[130:133], v[110:113]
	v_mfma_f32_16x16x32_bf16 v[106:109], v[162:165], v[138:141], v[106:109]
	s_waitcnt lgkmcnt(1)
	v_mfma_f32_16x16x32_bf16 v[102:105], v[170:173], v[130:133], v[102:105]
	v_mfma_f32_16x16x32_bf16 v[98:101], v[170:173], v[138:141], v[98:101]
	v_mfma_f32_16x16x32_bf16 v[126:129], v[150:153], v[134:137], v[126:129]
	v_mfma_f32_16x16x32_bf16 v[122:125], v[150:153], v[142:145], v[122:125]
	v_mfma_f32_16x16x32_bf16 v[118:121], v[158:161], v[134:137], v[118:121]
	v_mfma_f32_16x16x32_bf16 v[114:117], v[158:161], v[142:145], v[114:117]
	v_mfma_f32_16x16x32_bf16 v[110:113], v[166:169], v[134:137], v[110:113]
	v_mfma_f32_16x16x32_bf16 v[106:109], v[166:169], v[142:145], v[106:109]
	s_waitcnt lgkmcnt(0)
	v_mfma_f32_16x16x32_bf16 v[102:105], v[174:177], v[134:137], v[102:105]
	v_mfma_f32_16x16x32_bf16 v[98:101], v[174:177], v[142:145], v[98:101]
	s_setprio 0
	s_barrier
	ds_read_b128 v[178:181], v209
	ds_read_b128 v[182:185], v209 offset:1024
	ds_read_b128 v[186:189], v209 offset:2048
	ds_read_b128 v[190:193], v209 offset:3072
	s_add_u32 s86, s35, 0x180
	s_addc_u32 s87, s88, 0
	s_mov_b32 m0, s44
	s_nop 0
	global_load_lds_dwordx4 v198, s[86:87]
	s_nop 0
	s_mov_b32 m0, s45
	s_nop 0
	global_load_lds_dwordx4 v199, s[86:87]
	s_barrier
	s_waitcnt lgkmcnt(0)
	s_setprio 1
	s_waitcnt lgkmcnt(3)
	v_mfma_f32_16x16x32_bf16 v[94:97], v[146:149], v[178:181], v[94:97]
	s_waitcnt lgkmcnt(1)
	v_mfma_f32_16x16x32_bf16 v[90:93], v[146:149], v[186:189], v[90:93]
	v_mfma_f32_16x16x32_bf16 v[86:89], v[154:157], v[178:181], v[86:89]
	v_mfma_f32_16x16x32_bf16 v[82:85], v[154:157], v[186:189], v[82:85]
	v_mfma_f32_16x16x32_bf16 v[78:81], v[162:165], v[178:181], v[78:81]
	v_mfma_f32_16x16x32_bf16 v[74:77], v[162:165], v[186:189], v[74:77]
	v_mfma_f32_16x16x32_bf16 v[70:73], v[170:173], v[178:181], v[70:73]
	v_mfma_f32_16x16x32_bf16 v[66:69], v[170:173], v[186:189], v[66:69]
	v_mfma_f32_16x16x32_bf16 v[94:97], v[150:153], v[182:185], v[94:97]
	s_waitcnt lgkmcnt(0)
	v_mfma_f32_16x16x32_bf16 v[90:93], v[150:153], v[190:193], v[90:93]
	v_mfma_f32_16x16x32_bf16 v[86:89], v[158:161], v[182:185], v[86:89]
	v_mfma_f32_16x16x32_bf16 v[82:85], v[158:161], v[190:193], v[82:85]
	v_mfma_f32_16x16x32_bf16 v[78:81], v[166:169], v[182:185], v[78:81]
	v_mfma_f32_16x16x32_bf16 v[74:77], v[166:169], v[190:193], v[74:77]
	v_mfma_f32_16x16x32_bf16 v[70:73], v[174:177], v[182:185], v[70:73]
	v_mfma_f32_16x16x32_bf16 v[66:69], v[174:177], v[190:193], v[66:69]
	s_setprio 0
	s_barrier
	ds_read_b128 v[146:149], v203 offset:49152
	ds_read_b128 v[150:153], v203 offset:50176
	ds_read_b128 v[154:157], v204 offset:49152
	ds_read_b128 v[158:161], v204 offset:50176
	ds_read_b128 v[162:165], v205 offset:49152
	ds_read_b128 v[166:169], v205 offset:50176
	ds_read_b128 v[170:173], v206 offset:49152
	ds_read_b128 v[174:177], v206 offset:50176
	s_add_u32 s86, s89, 0x180
	s_addc_u32 s87, s90, 0
	s_mov_b32 m0, s46
	s_nop 0
	global_load_lds_dwordx4 v198, s[86:87]
	s_nop 0
	s_mov_b32 m0, s47
	s_nop 0
	global_load_lds_dwordx4 v199, s[86:87]
	s_barrier
	s_waitcnt lgkmcnt(0)
	s_setprio 1
	s_waitcnt lgkmcnt(7)
	v_mfma_f32_16x16x32_bf16 v[62:65], v[146:149], v[130:133], v[62:65]
	v_mfma_f32_16x16x32_bf16 v[58:61], v[146:149], v[138:141], v[58:61]
	s_waitcnt lgkmcnt(5)
	v_mfma_f32_16x16x32_bf16 v[54:57], v[154:157], v[130:133], v[54:57]
	v_mfma_f32_16x16x32_bf16 v[50:53], v[154:157], v[138:141], v[50:53]
	s_waitcnt lgkmcnt(3)
	v_mfma_f32_16x16x32_bf16 v[46:49], v[162:165], v[130:133], v[46:49]
	v_mfma_f32_16x16x32_bf16 v[42:45], v[162:165], v[138:141], v[42:45]
	s_waitcnt lgkmcnt(1)
	v_mfma_f32_16x16x32_bf16 v[38:41], v[170:173], v[130:133], v[38:41]
	v_mfma_f32_16x16x32_bf16 v[34:37], v[170:173], v[138:141], v[34:37]
	v_mfma_f32_16x16x32_bf16 v[62:65], v[150:153], v[134:137], v[62:65]
	v_mfma_f32_16x16x32_bf16 v[58:61], v[150:153], v[142:145], v[58:61]
	v_mfma_f32_16x16x32_bf16 v[54:57], v[158:161], v[134:137], v[54:57]
	v_mfma_f32_16x16x32_bf16 v[50:53], v[158:161], v[142:145], v[50:53]
	v_mfma_f32_16x16x32_bf16 v[46:49], v[166:169], v[134:137], v[46:49]
	v_mfma_f32_16x16x32_bf16 v[42:45], v[166:169], v[142:145], v[42:45]
	s_waitcnt lgkmcnt(0)
	v_mfma_f32_16x16x32_bf16 v[38:41], v[174:177], v[134:137], v[38:41]
	v_mfma_f32_16x16x32_bf16 v[34:37], v[174:177], v[142:145], v[34:37]
	s_setprio 0
	s_barrier
	s_add_u32 s86, s91, 0x180
	s_addc_u32 s87, s92, 0
	s_mov_b32 m0, s48
	s_nop 0
	global_load_lds_dwordx4 v198, s[86:87]
	s_nop 0
	s_mov_b32 m0, s49
	s_nop 0
	global_load_lds_dwordx4 v199, s[86:87]
	s_waitcnt vmcnt(6)
	s_barrier
	s_setprio 1
	v_mfma_f32_16x16x32_bf16 v[30:33], v[146:149], v[178:181], v[30:33]
	v_mfma_f32_16x16x32_bf16 v[26:29], v[146:149], v[186:189], v[26:29]
	v_mfma_f32_16x16x32_bf16 v[22:25], v[154:157], v[178:181], v[22:25]
	v_mfma_f32_16x16x32_bf16 v[18:21], v[154:157], v[186:189], v[18:21]
	v_mfma_f32_16x16x32_bf16 v[14:17], v[162:165], v[178:181], v[14:17]
	v_mfma_f32_16x16x32_bf16 v[10:13], v[162:165], v[186:189], v[10:13]
	v_mfma_f32_16x16x32_bf16 v[6:9], v[170:173], v[178:181], v[6:9]
	v_mfma_f32_16x16x32_bf16 v[2:5], v[170:173], v[186:189], v[2:5]
	v_mfma_f32_16x16x32_bf16 v[30:33], v[150:153], v[182:185], v[30:33]
	v_mfma_f32_16x16x32_bf16 v[26:29], v[150:153], v[190:193], v[26:29]
	v_mfma_f32_16x16x32_bf16 v[22:25], v[158:161], v[182:185], v[22:25]
	v_mfma_f32_16x16x32_bf16 v[18:21], v[158:161], v[190:193], v[18:21]
	v_mfma_f32_16x16x32_bf16 v[14:17], v[166:169], v[182:185], v[14:17]
	v_mfma_f32_16x16x32_bf16 v[10:13], v[166:169], v[190:193], v[10:13]
	v_mfma_f32_16x16x32_bf16 v[6:9], v[174:177], v[182:185], v[6:9]
	v_mfma_f32_16x16x32_bf16 v[2:5], v[174:177], v[190:193], v[2:5]
	s_setprio 0
	s_add_u32 s22, s22, 0x100
	s_addc_u32 s23, s23, 0
	s_add_i32 s34, s34, 2
	s_cmp_lt_u32 s34, 12
	s_barrier
; #define STAGE(P, BASE, br, kt) do { const u16* _gb = (BASE) + (long)(br)*K + (long)(kt)*BK; \
;     unsigned _ld = lds0 + (unsigned)((char*)(P) - (char*)shm) + wv * 1024u; \
;     glds_s(_gb, voff0, _ld); glds_s(_gb, voff1, _ld + 8192u); } while (0)
; #define LDA(dst, b, h) for (int m = 0; m < 4; ++m) for (int k = 0; k < 2; ++k) \
;     dst[m][k] = *reinterpret_cast<const bf16x8*>((char*)SA(b, h) + lds_byte(wr * 64 + m * 16 + fr, k * 32 + fq * 8))
; #define LDB(dst, b, h) for (int n = 0; n < 2; ++n) for (int k = 0; k < 2; ++k) \
;     dst[n][k] = *reinterpret_cast<const bf16x8*>((char*)SB(b, h) + lds_byte(wc * 32 + n * 16 + fr, k * 32 + fq * 8))
; #define WAIT_V(n) asm volatile("s_waitcnt vmcnt(" #n ")" ::: "memory")
; #define WAIT_L(n) asm volatile("s_waitcnt lgkmcnt(" #n ")" ::: "memory")
; #define BAR __builtin_amdgcn_s_barrier()
;     ...
;     { LDB(B0, 0, 0); LDA(At, 0, 0); STAGE(SA(1, 1), WtK, brow + HALF, nt - 1);
;       BAR; WAIT_L(0); MMA(0, 0, At, B0); BAR;
;       LDB(B1, 0, 1); BAR; WAIT_L(0); MMA(0, 1, At, B1); BAR;
;       LDA(At, 0, 1); WAIT_V(4); BAR; WAIT_L(0); MMA(1, 0, At, B0); MMA(1, 1, At, B1); BAR; }
;     { LDB(B0, 1, 0); LDA(At, 1, 0); WAIT_V(2); BAR; WAIT_L(0); MMA(0, 0, At, B0); BAR;
	s_cbranch_scc1 .LBB0_27
	ds_read_b128 v[130:133], v202
	ds_read_b128 v[134:137], v202 offset:1024
	ds_read_b128 v[138:141], v202 offset:2048
	ds_read_b128 v[142:145], v202 offset:3072
	ds_read_b128 v[146:149], v203
	ds_read_b128 v[150:153], v203 offset:1024
	ds_read_b128 v[154:157], v204
	ds_read_b128 v[166:169], v204 offset:1024
	ds_read_b128 v[158:161], v205
	ds_read_b128 v[174:177], v205 offset:1024
	ds_read_b128 v[162:165], v206
	ds_read_b128 v[182:185], v206 offset:1024
	s_add_u32 s22, s24, 0x780
	s_addc_u32 s23, s25, 0
	s_mov_b32 m0, s50
	s_nop 0
	global_load_lds_dwordx4 v198, s[22:23]
	s_nop 0
	s_mov_b32 m0, s51
	s_nop 0
	global_load_lds_dwordx4 v199, s[22:23]
	s_barrier
	s_waitcnt lgkmcnt(0)
	s_setprio 1
	s_waitcnt lgkmcnt(7)
	v_mfma_f32_16x16x32_bf16 v[126:129], v[146:149], v[130:133], v[126:129]
	v_mfma_f32_16x16x32_bf16 v[122:125], v[146:149], v[138:141], v[122:125]
	s_waitcnt lgkmcnt(5)
	v_mfma_f32_16x16x32_bf16 v[118:121], v[154:157], v[130:133], v[118:121]
	v_mfma_f32_16x16x32_bf16 v[114:117], v[154:157], v[138:141], v[114:117]
	s_waitcnt lgkmcnt(3)
	v_mfma_f32_16x16x32_bf16 v[110:113], v[158:161], v[130:133], v[110:113]
	v_mfma_f32_16x16x32_bf16 v[106:109], v[158:161], v[138:141], v[106:109]
	s_waitcnt lgkmcnt(1)
	v_mfma_f32_16x16x32_bf16 v[102:105], v[162:165], v[130:133], v[102:105]
	v_mfma_f32_16x16x32_bf16 v[98:101], v[162:165], v[138:141], v[98:101]
	v_mfma_f32_16x16x32_bf16 v[126:129], v[150:153], v[134:137], v[126:129]
	v_mfma_f32_16x16x32_bf16 v[122:125], v[150:153], v[142:145], v[122:125]
	v_mfma_f32_16x16x32_bf16 v[118:121], v[166:169], v[134:137], v[118:121]
	v_mfma_f32_16x16x32_bf16 v[114:117], v[166:169], v[142:145], v[114:117]
	v_mfma_f32_16x16x32_bf16 v[186:189], v[174:177], v[134:137], v[110:113]
	v_mfma_f32_16x16x32_bf16 v[190:193], v[174:177], v[142:145], v[106:109]
	s_waitcnt lgkmcnt(0)
	v_mfma_f32_16x16x32_bf16 v[210:213], v[182:185], v[134:137], v[102:105]
	v_mfma_f32_16x16x32_bf16 v[214:217], v[182:185], v[142:145], v[98:101]
	s_setprio 0
	s_barrier
	s_nop 0
	ds_read_b128 v[98:101], v207
	ds_read_b128 v[102:105], v207 offset:1024
	ds_read_b128 v[106:109], v207 offset:2048
	ds_read_b128 v[194:197], v207 offset:3072
	s_barrier
	s_waitcnt lgkmcnt(0)
	s_setprio 1
	s_waitcnt lgkmcnt(3)
	v_mfma_f32_16x16x32_bf16 v[94:97], v[146:149], v[98:101], v[94:97]
	s_waitcnt lgkmcnt(1)
	v_mfma_f32_16x16x32_bf16 v[90:93], v[146:149], v[106:109], v[90:93]
	v_mfma_f32_16x16x32_bf16 v[86:89], v[154:157], v[98:101], v[86:89]
	v_mfma_f32_16x16x32_bf16 v[82:85], v[154:157], v[106:109], v[82:85]
	v_mfma_f32_16x16x32_bf16 v[78:81], v[158:161], v[98:101], v[78:81]
	v_mfma_f32_16x16x32_bf16 v[74:77], v[158:161], v[106:109], v[74:77]
	v_mfma_f32_16x16x32_bf16 v[70:73], v[162:165], v[98:101], v[70:73]
	v_mfma_f32_16x16x32_bf16 v[66:69], v[162:165], v[106:109], v[66:69]
	v_mfma_f32_16x16x32_bf16 v[110:113], v[150:153], v[102:105], v[94:97]
	s_waitcnt lgkmcnt(0)
	v_mfma_f32_16x16x32_bf16 v[158:161], v[150:153], v[194:197], v[90:93]
	v_mfma_f32_16x16x32_bf16 v[162:165], v[166:169], v[102:105], v[86:89]
	v_mfma_f32_16x16x32_bf16 v[166:169], v[166:169], v[194:197], v[82:85]
	v_mfma_f32_16x16x32_bf16 v[170:173], v[174:177], v[102:105], v[78:81]
	v_mfma_f32_16x16x32_bf16 v[174:177], v[174:177], v[194:197], v[74:77]
	v_mfma_f32_16x16x32_bf16 v[178:181], v[182:185], v[102:105], v[70:73]
	v_mfma_f32_16x16x32_bf16 v[182:185], v[182:185], v[194:197], v[66:69]
	s_setprio 0
	s_barrier
	s_nop 0
	ds_read_b128 v[66:69], v203 offset:16384
	ds_read_b128 v[70:73], v203 offset:17408
	ds_read_b128 v[74:77], v204 offset:16384
	ds_read_b128 v[82:85], v204 offset:17408
	ds_read_b128 v[146:149], v205 offset:16384
	ds_read_b128 v[150:153], v205 offset:17408
	ds_read_b128 v[154:157], v206 offset:16384
	ds_read_b128 v[218:221], v206 offset:17408
	s_waitcnt vmcnt(4)
	s_barrier
	s_waitcnt lgkmcnt(0)
	s_setprio 1
	s_waitcnt lgkmcnt(7)
	v_mfma_f32_16x16x32_bf16 v[58:61], v[66:69], v[138:141], v[58:61]
	s_waitcnt lgkmcnt(5)
	v_mfma_f32_16x16x32_bf16 v[54:57], v[74:77], v[130:133], v[54:57]
	v_mfma_f32_16x16x32_bf16 v[78:81], v[74:77], v[138:141], v[50:53]
	s_waitcnt lgkmcnt(3)
	v_mfma_f32_16x16x32_bf16 v[46:49], v[146:149], v[130:133], v[46:49]
	v_mfma_f32_16x16x32_bf16 v[86:89], v[146:149], v[138:141], v[42:45]
	s_waitcnt lgkmcnt(1)
	v_mfma_f32_16x16x32_bf16 v[38:41], v[154:157], v[130:133], v[38:41]
	v_mfma_f32_16x16x32_bf16 v[94:97], v[154:157], v[138:141], v[34:37]
	v_mfma_f32_16x16x32_bf16 v[62:65], v[66:69], v[130:133], v[62:65]
	v_mfma_f32_16x16x32_bf16 v[34:37], v[70:73], v[134:137], v[62:65]
	v_mfma_f32_16x16x32_bf16 v[42:45], v[70:73], v[142:145], v[58:61]
	v_mfma_f32_16x16x32_bf16 v[50:53], v[82:85], v[134:137], v[54:57]
	v_mfma_f32_16x16x32_bf16 v[58:61], v[82:85], v[142:145], v[78:81]
	v_mfma_f32_16x16x32_bf16 v[78:81], v[150:153], v[134:137], v[46:49]
	v_mfma_f32_16x16x32_bf16 v[86:89], v[150:153], v[142:145], v[86:89]
	s_waitcnt lgkmcnt(0)
	v_mfma_f32_16x16x32_bf16 v[90:93], v[218:221], v[134:137], v[38:41]
	v_mfma_f32_16x16x32_bf16 v[94:97], v[218:221], v[142:145], v[94:97]
	s_setprio 0
	s_setprio 1
	v_mfma_f32_16x16x32_bf16 v[30:33], v[66:69], v[98:101], v[30:33]
	v_mfma_f32_16x16x32_bf16 v[26:29], v[66:69], v[106:109], v[26:29]
	v_mfma_f32_16x16x32_bf16 v[22:25], v[74:77], v[98:101], v[22:25]
	v_mfma_f32_16x16x32_bf16 v[38:41], v[74:77], v[106:109], v[18:21]
	v_mfma_f32_16x16x32_bf16 v[14:17], v[146:149], v[98:101], v[14:17]
	v_mfma_f32_16x16x32_bf16 v[46:49], v[146:149], v[106:109], v[10:13]
	v_mfma_f32_16x16x32_bf16 v[6:9], v[154:157], v[98:101], v[6:9]
	v_mfma_f32_16x16x32_bf16 v[54:57], v[154:157], v[106:109], v[2:5]
	v_mfma_f32_16x16x32_bf16 v[2:5], v[70:73], v[102:105], v[30:33]
	v_mfma_f32_16x16x32_bf16 v[10:13], v[70:73], v[194:197], v[26:29]
	v_mfma_f32_16x16x32_bf16 v[18:21], v[82:85], v[102:105], v[22:25]
	v_mfma_f32_16x16x32_bf16 v[26:29], v[82:85], v[194:197], v[38:41]
	v_mfma_f32_16x16x32_bf16 v[130:133], v[150:153], v[102:105], v[14:17]
	v_mfma_f32_16x16x32_bf16 v[134:137], v[150:153], v[194:197], v[46:49]
	v_mfma_f32_16x16x32_bf16 v[138:141], v[218:221], v[102:105], v[6:9]
	v_mfma_f32_16x16x32_bf16 v[142:145], v[218:221], v[194:197], v[54:57]
	s_setprio 0
	s_barrier
; #define STAGE(P, BASE, br, kt) do { const u16* _gb = (BASE) + (long)(br)*K + (long)(kt)*BK; \
;     unsigned _ld = lds0 + (unsigned)((char*)(P) - (char*)shm) + wv * 1024u; \
;     glds_s(_gb, voff0, _ld); glds_s(_gb, voff1, _ld + 8192u); } while (0)
; #define LDA(dst, b, h) for (int m = 0; m < 4; ++m) for (int k = 0; k < 2; ++k) \
;     dst[m][k] = *reinterpret_cast<const bf16x8*>((char*)SA(b, h) + lds_byte(wr * 64 + m * 16 + fr, k * 32 + fq * 8))
; #define LDB(dst, b, h) for (int n = 0; n < 2; ++n) for (int k = 0; k < 2; ++k) \
;     dst[n][k] = *reinterpret_cast<const bf16x8*>((char*)SB(b, h) + lds_byte(wc * 32 + n * 16 + fr, k * 32 + fq * 8))
; #define WAIT_V(n) asm volatile("s_waitcnt vmcnt(" #n ")" ::: "memory")
; #define WAIT_L(n) asm volatile("s_waitcnt lgkmcnt(" #n ")" ::: "memory")
; #define BAR __builtin_amdgcn_s_barrier()
;     ...
;     { LDB(B0, 1, 0); LDA(At, 1, 0); WAIT_V(2); BAR; WAIT_L(0); MMA(0, 0, At, B0); BAR;
;       LDB(B1, 1, 1);
;       if (has_next) { STAGE(SB(0, 0), ActN, nbcol, 0); STAGE(SA(0, 0), WtN, nbrow, 0); WAIT_V(4); } else { WAIT_V(0); }
;       BAR; WAIT_L(0); MMA(0, 1, At, B1); BAR;
;       LDA(At, 1, 1);
;       if (has_next) { STAGE(SB(0, 1), ActN, nbcol + HALF, 0); STAGE(SA(0, 1), WtN, nbrow + HALF, 0); }
;       BAR; WAIT_L(0); MMA(1, 0, At, B0); MMA(1, 1, At, B1); BAR; }
	ds_read_b128 v[102:105], v208
	ds_read_b128 v[98:101], v208 offset:1024
	ds_read_b128 v[106:109], v208 offset:2048
	ds_read_b128 v[146:149], v208 offset:3072
	ds_read_b128 v[22:25], v203 offset:32768
	ds_read_b128 v[6:9], v203 offset:33792
	ds_read_b128 v[30:33], v204 offset:32768
	ds_read_b128 v[14:17], v204 offset:33792
	ds_read_b128 v[46:49], v205 offset:32768
	ds_read_b128 v[38:41], v205 offset:33792
	ds_read_b128 v[54:57], v206 offset:32768
	ds_read_b128 v[194:197], v206 offset:33792
	s_waitcnt vmcnt(2)
	s_barrier
	s_waitcnt lgkmcnt(0)
	s_setprio 1
	s_waitcnt lgkmcnt(7)
	v_mfma_f32_16x16x32_bf16 v[66:69], v[22:25], v[106:109], v[122:125]
	s_waitcnt lgkmcnt(5)
	v_mfma_f32_16x16x32_bf16 v[70:73], v[30:33], v[102:105], v[118:121]
	v_mfma_f32_16x16x32_bf16 v[74:77], v[30:33], v[106:109], v[114:117]
	s_waitcnt lgkmcnt(3)
	v_mfma_f32_16x16x32_bf16 v[114:117], v[46:49], v[102:105], v[186:189]
	v_mfma_f32_16x16x32_bf16 v[150:153], v[46:49], v[106:109], v[190:193]
	s_waitcnt lgkmcnt(1)
	v_mfma_f32_16x16x32_bf16 v[154:157], v[54:57], v[102:105], v[210:213]
	v_mfma_f32_16x16x32_bf16 v[186:189], v[54:57], v[106:109], v[214:217]
	v_mfma_f32_16x16x32_bf16 v[62:65], v[22:25], v[102:105], v[126:129]
	v_mfma_f32_16x16x32_bf16 v[126:129], v[6:9], v[98:101], v[62:65]
	v_mfma_f32_16x16x32_bf16 v[82:85], v[6:9], v[146:149], v[66:69]
	v_mfma_f32_16x16x32_bf16 v[122:125], v[14:17], v[98:101], v[70:73]
	v_mfma_f32_16x16x32_bf16 v[74:77], v[14:17], v[146:149], v[74:77]
	v_mfma_f32_16x16x32_bf16 v[118:121], v[38:41], v[98:101], v[114:117]
	v_mfma_f32_16x16x32_bf16 v[70:73], v[38:41], v[146:149], v[150:153]
	s_waitcnt lgkmcnt(0)
	v_mfma_f32_16x16x32_bf16 v[114:117], v[194:197], v[98:101], v[154:157]
	v_mfma_f32_16x16x32_bf16 v[66:69], v[194:197], v[146:149], v[186:189]
	s_setprio 0
	s_barrier
	s_nop 0
	ds_read_b128 v[186:189], v209
	ds_read_b128 v[150:153], v209 offset:1024
	ds_read_b128 v[190:193], v209 offset:2048
	ds_read_b128 v[154:157], v209 offset:3072
	s_mov_b64 s[22:23], -1
	s_and_b64 vcc, exec, s[4:5]
	s_cbranch_vccz .LBB0_30
	s_waitcnt vmcnt(0)
	s_mov_b64 s[22:23], 0
.LBB0_30:
	s_andn2_b64 vcc, exec, s[22:23]
	s_cbranch_vccnz .LBB0_32
	s_ashr_i32 s7, s6, 31
	s_lshl_b64 s[22:23], s[6:7], 11
	s_add_u32 s22, s78, s22
	s_addc_u32 s23, s79, s23
	s_mov_b32 m0, s36
	s_nop 0
	global_load_lds_dwordx4 v198, s[22:23]
	s_ashr_i32 s95, s94, 31
	s_mov_b32 m0, s38
	s_nop 0
	global_load_lds_dwordx4 v199, s[22:23]
	s_lshl_b64 s[22:23], s[94:95], 11
	s_add_u32 s22, s52, s22
	s_addc_u32 s23, s53, s23
	s_mov_b32 m0, s37
	s_nop 0
	global_load_lds_dwordx4 v198, s[22:23]
	s_nop 0
	s_mov_b32 m0, s39
	s_nop 0
	global_load_lds_dwordx4 v199, s[22:23]
	s_waitcnt vmcnt(4)
.LBB0_32:
	s_barrier
	s_waitcnt lgkmcnt(0)
	s_setprio 1
	s_waitcnt lgkmcnt(3)
	v_mfma_f32_16x16x32_bf16 v[62:65], v[22:25], v[186:189], v[110:113]
	s_waitcnt lgkmcnt(1)
	v_mfma_f32_16x16x32_bf16 v[22:25], v[22:25], v[190:193], v[158:161]
	v_mfma_f32_16x16x32_bf16 v[110:113], v[30:33], v[186:189], v[162:165]
	v_mfma_f32_16x16x32_bf16 v[158:161], v[30:33], v[190:193], v[166:169]
	v_mfma_f32_16x16x32_bf16 v[162:165], v[46:49], v[186:189], v[170:173]
	v_mfma_f32_16x16x32_bf16 v[166:169], v[46:49], v[190:193], v[174:177]
	v_mfma_f32_16x16x32_bf16 v[170:173], v[54:57], v[186:189], v[178:181]
	v_mfma_f32_16x16x32_bf16 v[174:177], v[54:57], v[190:193], v[182:185]
	v_mfma_f32_16x16x32_bf16 v[62:65], v[6:9], v[150:153], v[62:65]
	s_waitcnt lgkmcnt(0)
	v_mfma_f32_16x16x32_bf16 v[30:33], v[6:9], v[154:157], v[22:25]
	v_mfma_f32_16x16x32_bf16 v[54:57], v[14:17], v[150:153], v[110:113]
	v_mfma_f32_16x16x32_bf16 v[22:25], v[14:17], v[154:157], v[158:161]
	v_mfma_f32_16x16x32_bf16 v[46:49], v[38:41], v[150:153], v[162:165]
	v_mfma_f32_16x16x32_bf16 v[14:17], v[38:41], v[154:157], v[166:169]
	v_mfma_f32_16x16x32_bf16 v[38:41], v[194:197], v[150:153], v[170:173]
	v_mfma_f32_16x16x32_bf16 v[6:9], v[194:197], v[154:157], v[174:177]
	s_setprio 0
	s_barrier
	s_nop 0
	ds_read_b128 v[174:177], v203 offset:49152
	ds_read_b128 v[158:161], v203 offset:50176
	ds_read_b128 v[178:181], v204 offset:49152
	ds_read_b128 v[162:165], v204 offset:50176
	ds_read_b128 v[182:185], v205 offset:49152
	ds_read_b128 v[166:169], v205 offset:50176
	ds_read_b128 v[194:197], v206 offset:49152
	ds_read_b128 v[170:173], v206 offset:50176
	s_andn2_b64 vcc, exec, s[20:21]
	s_cbranch_vccnz .LBB0_34
	s_or_b32 s20, s6, 0x80
	s_ashr_i32 s21, s20, 31
	s_lshl_b64 s[20:21], s[20:21], 11
	s_add_u32 s20, s78, s20
	s_addc_u32 s21, s79, s21
	s_mov_b32 m0, s40
	s_nop 0
	global_load_lds_dwordx4 v198, s[20:21]
	s_ashr_i32 s95, s94, 31
	s_mov_b32 m0, s41
	s_nop 0
	global_load_lds_dwordx4 v199, s[20:21]
	s_lshl_b64 s[20:21], s[94:95], 11
	s_add_u32 s11, s52, s20
	s_addc_u32 s13, s53, s21
	s_add_u32 s20, s11, 0x40000
	s_addc_u32 s21, s13, 0
	s_mov_b32 m0, s42
	s_nop 0
	global_load_lds_dwordx4 v198, s[20:21]
	s_nop 0
	s_mov_b32 m0, s43
	s_nop 0
	global_load_lds_dwordx4 v199, s[20:21]

; #define STAGE(P, BASE, br, kt) do { const u16* _gb = (BASE) + (long)(br)*K + (long)(kt)*BK; \
;     unsigned _ld = lds0 + (unsigned)((char*)(P) - (char*)shm) + wv * 1024u; \
;     glds_s(_gb, voff0, _ld); glds_s(_gb, voff1, _ld + 8192u); } while (0)
; #define BAR __builtin_amdgcn_s_barrier()
; __device__ __forceinline__ void glds_s(const void* sbase, unsigned voff, unsigned lds_dst) {
;   unsigned keep;
;   asm volatile("s_mov_b32 %0, m0\n\ts_mov_b32 m0, %3\n\ts_nop 0\n\tglobal_load_lds_dwordx4 %2, %1\n\ts_mov_b32 m0, %0"
;                : "=&s"(keep) : "s"(sbase), "v"(voff), "s"(lds_dst) : "memory");
; }
;     ...
;     if (!staged) {
;       STAGE(SB(0, 0), ActK, bcol, 0); STAGE(SA(0, 0), WtK, brow, 0);
;       STAGE(SB(0, 1), ActK, bcol + HALF, 0); STAGE(SA(0, 1), WtK, brow + HALF, 0);
;       if (wr == 1) BAR;
.LBB0_63:
	v_readlane_b32 s40, v255, 5
	s_xor_b64 s[30:31], s[30:31], -1
	s_lshl_b64 s[34:35], s[0:1], 1
	v_readlane_b32 s42, v255, 7
	v_readlane_b32 s43, v255, 8
	s_add_u32 s39, s42, s34
	s_addc_u32 s40, s43, s35
	s_add_u32 s37, s97, s34
	s_addc_u32 s38, s56, s35
	s_andn2_b64 vcc, exec, s[30:31]
	s_mov_b64 s[30:31], -1
	v_readlane_b32 s41, v255, 6
	v_readlane_b32 s44, v255, 9
	v_readlane_b32 s45, v255, 10
	v_readlane_b32 s46, v255, 11
	v_readlane_b32 s47, v255, 12
	v_readlane_b32 s48, v255, 13
	v_readlane_b32 s49, v255, 14
	v_readlane_b32 s50, v255, 15
	v_readlane_b32 s51, v255, 16
	v_readlane_b32 s52, v255, 17
	v_readlane_b32 s53, v255, 18
	v_readlane_b32 s54, v255, 19
	v_readlane_b32 s55, v255, 20
	s_cbranch_vccnz .LBB0_67
	s_ashr_i32 s13, s12, 31
	s_lshl_b64 s[30:31], s[12:13], 11
	s_add_u32 s30, s39, s30
	s_addc_u32 s31, s40, s31
	s_ashr_i32 s5, s4, 31
	s_mov_b32 m0, s94
	s_nop 0
	global_load_lds_dwordx4 v230, s[30:31]
	s_lshl_b64 s[34:35], s[4:5], 11
	s_mov_b32 m0, s16
	s_nop 0
	global_load_lds_dwordx4 v231, s[30:31]
	s_add_u32 s30, s37, s34
	s_addc_u32 s31, s38, s35
	s_mov_b32 m0, s95
	s_nop 0
	global_load_lds_dwordx4 v230, s[30:31]
	s_nop 0
	s_mov_b32 m0, s17
	s_nop 0
	global_load_lds_dwordx4 v231, s[30:31]
	s_add_i32 s30, s12, 0x80
	s_ashr_i32 s31, s30, 31
	s_lshl_b64 s[42:43], s[30:31], 11
	s_add_u32 s42, s39, s42
	s_addc_u32 s43, s40, s43
	s_add_u32 s34, s34, 0x40000
	s_mov_b32 m0, s10
	s_nop 0
	global_load_lds_dwordx4 v230, s[42:43]
	s_addc_u32 s35, s35, 0
	s_mov_b32 m0, s11
	s_nop 0
	global_load_lds_dwordx4 v231, s[42:43]
	s_add_u32 s42, s37, s34
	s_addc_u32 s43, s38, s35
	s_mov_b32 m0, s6
	s_nop 0
	global_load_lds_dwordx4 v230, s[42:43]
	s_nop 0
	s_mov_b32 m0, s7
	s_nop 0
	global_load_lds_dwordx4 v231, s[42:43]
	s_and_saveexec_b64 s[86:87], s[58:59]
	s_cbranch_execz .LBB0_66
	s_barrier

; #define STAGE(P, BASE, br, kt) do { const u16* _gb = (BASE) + (long)(br)*K + (long)(kt)*BK; \
;     unsigned _ld = lds0 + (unsigned)((char*)(P) - (char*)shm) + wv * 1024u; \
;     glds_s(_gb, voff0, _ld); glds_s(_gb, voff1, _ld + 8192u); } while (0)
; #define LDA(dst, b, h) for (int m = 0; m < 4; ++m) for (int k = 0; k < 2; ++k) \
;     dst[m][k] = *reinterpret_cast<const bf16x8*>((char*)SA(b, h) + lds_byte(wr * 64 + m * 16 + fr, k * 32 + fq * 8))
; #define LDB(dst, b, h) for (int n = 0; n < 2; ++n) for (int k = 0; k < 2; ++k) \
;     dst[n][k] = *reinterpret_cast<const bf16x8*>((char*)SB(b, h) + lds_byte(wc * 32 + n * 16 + fr, k * 32 + fq * 8))
; #define WAIT_V(n) asm volatile("s_waitcnt vmcnt(" #n ")" ::: "memory")
; #define WAIT_L(n) asm volatile("s_waitcnt lgkmcnt(" #n ")" ::: "memory")
; #define BAR __builtin_amdgcn_s_barrier()
; #define SCHED __builtin_amdgcn_sched_barrier(0)
;     ...
;     f32x4 acc[2][2][4][2] = {};
;     bf16x8 At[4][2], B0[2][2], B1[2][2];
;     if (!staged) {
;       STAGE(SB(0, 0), ActK, bcol, 0); STAGE(SA(0, 0), WtK, brow, 0);
;       STAGE(SB(0, 1), ActK, bcol + HALF, 0); STAGE(SA(0, 1), WtK, brow + HALF, 0);
;       if (wr == 1) BAR;
;       WAIT_V(4); BAR;
;     } else {
;       if (wr == 1) BAR;
;       WAIT_V(0); BAR;
;     }
;     STAGE(SB(1, 0), ActK, bcol, 1); STAGE(SA(1, 0), WtK, brow, 1); STAGE(SB(1, 1), ActK, bcol + HALF, 1);
;     WAIT_V(6); BAR;
;     for (int t = 0; t < nt - 2; t += 2) {
;       LDB(B0, 0, 0); SCHED; LDA(At, 0, 0); STAGE(SA(1, 1), WtK, brow + HALF, t + 1);
;       WAIT_L(8); BAR; WAIT_L(0); MMA(0, 0, At, B0); BAR; SCHED;
.LBB0_71:
	s_cmpk_gt_i32 s23, 0x3ff
	s_cselect_b64 s[30:31], -1, 0
	s_cmpk_lt_i32 s23, 0x400
	s_cselect_b32 s0, 16, 8
	s_lshl_b64 s[42:43], s[90:91], 1
	s_add_u32 s13, s39, s42
	s_addc_u32 s21, s40, s43
	s_add_u32 s42, s13, 0x80
	s_addc_u32 s43, s21, 0
	s_mov_b32 m0, s8
	s_nop 0
	global_load_lds_dwordx4 v230, s[42:43]
	v_mov_b32_e32 v2, 0
	s_mov_b32 m0, s9
	s_nop 0
	global_load_lds_dwordx4 v231, s[42:43]
	s_lshl_b64 s[42:43], s[88:89], 1
	s_add_u32 s25, s37, s42
	s_addc_u32 s36, s38, s43
	s_add_u32 s42, s25, 0x80
	s_addc_u32 s43, s36, 0
	s_mov_b32 m0, s92
	s_nop 0
	global_load_lds_dwordx4 v230, s[42:43]
	v_mov_b32_e32 v3, v2
	s_mov_b32 m0, s93
	s_nop 0
	global_load_lds_dwordx4 v231, s[42:43]
	s_lshl_b64 s[42:43], s[86:87], 1
	s_add_u32 s39, s39, s42
	s_addc_u32 s40, s40, s43
	s_add_u32 s42, s39, 0x80
	s_addc_u32 s43, s40, 0
	s_mov_b32 m0, s14
	s_nop 0
	global_load_lds_dwordx4 v230, s[42:43]
	v_mov_b32_e32 v4, v2
	s_mov_b32 m0, s15
	s_nop 0
	global_load_lds_dwordx4 v231, s[42:43]
	s_add_i32 s41, s0, -2
	s_add_u32 s37, s37, s34
	s_addc_u32 s38, s38, s35
	s_mov_b32 s42, 0
	s_mov_b64 s[34:35], 0
	v_mov_b32_e32 v5, v2
	v_mov_b32_e32 v6, v2
	v_mov_b32_e32 v7, v2
	v_mov_b32_e32 v8, v2
	v_mov_b32_e32 v9, v2
	v_mov_b32_e32 v10, v2
	v_mov_b32_e32 v11, v2
	v_mov_b32_e32 v12, v2
	v_mov_b32_e32 v13, v2
	v_mov_b32_e32 v14, v2
	v_mov_b32_e32 v15, v2
	v_mov_b32_e32 v16, v2
	v_mov_b32_e32 v17, v2
	v_mov_b32_e32 v18, v2
	v_mov_b32_e32 v19, v2
	v_mov_b32_e32 v20, v2
	v_mov_b32_e32 v21, v2
	v_mov_b32_e32 v22, v2
	v_mov_b32_e32 v23, v2
	v_mov_b32_e32 v24, v2
	v_mov_b32_e32 v25, v2
	v_mov_b32_e32 v26, v2
	v_mov_b32_e32 v27, v2
	v_mov_b32_e32 v28, v2
	v_mov_b32_e32 v29, v2
	v_mov_b32_e32 v30, v2
	v_mov_b32_e32 v31, v2
	v_mov_b32_e32 v32, v2
	v_mov_b32_e32 v33, v2
	v_mov_b32_e32 v34, v2
	v_mov_b32_e32 v35, v2
	v_mov_b32_e32 v36, v2
	v_mov_b32_e32 v37, v2
	v_mov_b32_e32 v38, v2
	v_mov_b32_e32 v39, v2
	v_mov_b32_e32 v40, v2
	v_mov_b32_e32 v41, v2
	v_mov_b32_e32 v42, v2
	v_mov_b32_e32 v43, v2
	v_mov_b32_e32 v44, v2
	v_mov_b32_e32 v45, v2
	v_mov_b32_e32 v46, v2
	v_mov_b32_e32 v47, v2
	v_mov_b32_e32 v48, v2
	v_mov_b32_e32 v49, v2
	v_mov_b32_e32 v54, v2
	v_mov_b32_e32 v55, v2
	v_mov_b32_e32 v56, v2
	v_mov_b32_e32 v57, v2
	v_mov_b32_e32 v66, v2
	v_mov_b32_e32 v67, v2
	v_mov_b32_e32 v68, v2
	v_mov_b32_e32 v69, v2
	v_mov_b32_e32 v78, v2
	v_mov_b32_e32 v79, v2
	v_mov_b32_e32 v80, v2
	v_mov_b32_e32 v81, v2
	v_mov_b32_e32 v86, v2
	v_mov_b32_e32 v87, v2
	v_mov_b32_e32 v88, v2
	v_mov_b32_e32 v89, v2
	v_mov_b32_e32 v98, v2
	v_mov_b32_e32 v99, v2
	v_mov_b32_e32 v100, v2
	v_mov_b32_e32 v101, v2
	v_mov_b32_e32 v102, v2
	v_mov_b32_e32 v103, v2
	v_mov_b32_e32 v104, v2
	v_mov_b32_e32 v105, v2
	v_mov_b32_e32 v106, v2
	v_mov_b32_e32 v107, v2
	v_mov_b32_e32 v108, v2
	v_mov_b32_e32 v109, v2
	v_mov_b32_e32 v110, v2
	v_mov_b32_e32 v111, v2
	v_mov_b32_e32 v112, v2
	v_mov_b32_e32 v113, v2
	v_mov_b32_e32 v114, v2
	v_mov_b32_e32 v115, v2
	v_mov_b32_e32 v116, v2
	v_mov_b32_e32 v117, v2
	v_mov_b32_e32 v118, v2
	v_mov_b32_e32 v119, v2
	v_mov_b32_e32 v120, v2
	v_mov_b32_e32 v121, v2
	v_mov_b32_e32 v122, v2
	v_mov_b32_e32 v123, v2
	v_mov_b32_e32 v124, v2
	v_mov_b32_e32 v125, v2
	v_mov_b32_e32 v126, v2
	v_mov_b32_e32 v127, v2
	v_mov_b32_e32 v128, v2
	v_mov_b32_e32 v129, v2
	v_mov_b32_e32 v50, v2
	v_mov_b32_e32 v51, v2
	v_mov_b32_e32 v52, v2
	v_mov_b32_e32 v53, v2
	v_mov_b32_e32 v58, v2
	v_mov_b32_e32 v59, v2
	v_mov_b32_e32 v60, v2
	v_mov_b32_e32 v61, v2
	v_mov_b32_e32 v62, v2
	v_mov_b32_e32 v63, v2
	v_mov_b32_e32 v64, v2
	v_mov_b32_e32 v65, v2
	v_mov_b32_e32 v70, v2
	v_mov_b32_e32 v71, v2
	v_mov_b32_e32 v72, v2
	v_mov_b32_e32 v73, v2
	v_mov_b32_e32 v74, v2
	v_mov_b32_e32 v75, v2
	v_mov_b32_e32 v76, v2
	v_mov_b32_e32 v77, v2
	v_mov_b32_e32 v82, v2
	v_mov_b32_e32 v83, v2
	v_mov_b32_e32 v84, v2
	v_mov_b32_e32 v85, v2
	v_mov_b32_e32 v90, v2
	v_mov_b32_e32 v91, v2
	v_mov_b32_e32 v92, v2
	v_mov_b32_e32 v93, v2
	v_mov_b32_e32 v94, v2
	v_mov_b32_e32 v95, v2
	v_mov_b32_e32 v96, v2
	v_mov_b32_e32 v97, v2
	s_waitcnt vmcnt(6)
	s_barrier
.LBB0_72:
	ds_read_b128 v[130:133], v233
	ds_read_b128 v[134:137], v233 offset:1024
	ds_read_b128 v[138:141], v233 offset:2048
	ds_read_b128 v[142:145], v233 offset:3072
	ds_read_b128 v[146:149], v234
	ds_read_b128 v[150:153], v234 offset:1024
	ds_read_b128 v[154:157], v235
	ds_read_b128 v[158:161], v235 offset:1024
	ds_read_b128 v[162:165], v236
	ds_read_b128 v[166:169], v236 offset:1024
	ds_read_b128 v[170:173], v237
	ds_read_b128 v[174:177], v237 offset:1024
	s_add_u32 s43, s37, s34
	s_addc_u32 s46, s38, s35
	s_add_u32 s44, s43, 0x80
	s_addc_u32 s45, s46, 0
	s_mov_b32 m0, s18
	s_nop 0
	global_load_lds_dwordx4 v230, s[44:45]
	s_nop 0
	s_mov_b32 m0, s19
	s_nop 0
	global_load_lds_dwordx4 v231, s[44:45]
	s_waitcnt lgkmcnt(8)
	s_barrier
	s_waitcnt lgkmcnt(0)
	s_setprio 1
	s_waitcnt lgkmcnt(7)
	v_mfma_f32_16x16x32_bf16 v[126:129], v[146:149], v[130:133], v[126:129]
	v_mfma_f32_16x16x32_bf16 v[122:125], v[146:149], v[138:141], v[122:125]
	s_waitcnt lgkmcnt(5)
	v_mfma_f32_16x16x32_bf16 v[118:121], v[154:157], v[130:133], v[118:121]
	v_mfma_f32_16x16x32_bf16 v[114:117], v[154:157], v[138:141], v[114:117]
	s_waitcnt lgkmcnt(3)
	v_mfma_f32_16x16x32_bf16 v[110:113], v[162:165], v[130:133], v[110:113]
	v_mfma_f32_16x16x32_bf16 v[106:109], v[162:165], v[138:141], v[106:109]
	s_waitcnt lgkmcnt(1)
	v_mfma_f32_16x16x32_bf16 v[102:105], v[170:173], v[130:133], v[102:105]
	v_mfma_f32_16x16x32_bf16 v[98:101], v[170:173], v[138:141], v[98:101]
	v_mfma_f32_16x16x32_bf16 v[126:129], v[150:153], v[134:137], v[126:129]
	v_mfma_f32_16x16x32_bf16 v[122:125], v[150:153], v[142:145], v[122:125]
	v_mfma_f32_16x16x32_bf16 v[118:121], v[158:161], v[134:137], v[118:121]
	v_mfma_f32_16x16x32_bf16 v[114:117], v[158:161], v[142:145], v[114:117]
	v_mfma_f32_16x16x32_bf16 v[110:113], v[166:169], v[134:137], v[110:113]
	v_mfma_f32_16x16x32_bf16 v[106:109], v[166:169], v[142:145], v[106:109]
	s_waitcnt lgkmcnt(0)
	v_mfma_f32_16x16x32_bf16 v[102:105], v[174:177], v[134:137], v[102:105]
	v_mfma_f32_16x16x32_bf16 v[98:101], v[174:177], v[142:145], v[98:101]
	s_setprio 0
	s_barrier
; #define STAGE(P, BASE, br, kt) do { const u16* _gb = (BASE) + (long)(br)*K + (long)(kt)*BK; \
;     unsigned _ld = lds0 + (unsigned)((char*)(P) - (char*)shm) + wv * 1024u; \
;     glds_s(_gb, voff0, _ld); glds_s(_gb, voff1, _ld + 8192u); } while (0)
; #define LDA(dst, b, h) for (int m = 0; m < 4; ++m) for (int k = 0; k < 2; ++k) \
;     dst[m][k] = *reinterpret_cast<const bf16x8*>((char*)SA(b, h) + lds_byte(wr * 64 + m * 16 + fr, k * 32 + fq * 8))
; #define LDB(dst, b, h) for (int n = 0; n < 2; ++n) for (int k = 0; k < 2; ++k) \
;     dst[n][k] = *reinterpret_cast<const bf16x8*>((char*)SB(b, h) + lds_byte(wc * 32 + n * 16 + fr, k * 32 + fq * 8))
; #define WAIT_V(n) asm volatile("s_waitcnt vmcnt(" #n ")" ::: "memory")
; #define WAIT_L(n) asm volatile("s_waitcnt lgkmcnt(" #n ")" ::: "memory")
; #define BAR __builtin_amdgcn_s_barrier()
; #define SCHED __builtin_amdgcn_sched_barrier(0)
;     ...
;       WAIT_L(8); BAR; WAIT_L(0); MMA(0, 0, At, B0); BAR; SCHED;
;       LDB(B1, 0, 1); STAGE(SB(0, 0), ActK, bcol, t + 2);
;       BAR; WAIT_L(0); MMA(0, 1, At, B1); BAR;
;       LDA(At, 0, 1); STAGE(SA(0, 0), WtK, brow, t + 2);
;       BAR; WAIT_L(0); MMA(1, 0, At, B0); BAR; SCHED;
;       STAGE(SB(0, 1), ActK, bcol + HALF, t + 2);
;       WAIT_V(6); BAR; MMA(1, 1, At, B1); BAR;
;       LDB(B0, 1, 0); SCHED; LDA(At, 1, 0); STAGE(SA(0, 1), WtK, brow + HALF, t + 2);
;       WAIT_L(8); BAR; WAIT_L(0); MMA(0, 0, At, B0); BAR; SCHED;
	s_add_i32 s42, s42, 2
	ds_read_b128 v[178:181], v238
	ds_read_b128 v[182:185], v238 offset:1024
	ds_read_b128 v[186:189], v238 offset:2048
	ds_read_b128 v[190:193], v238 offset:3072
	s_add_u32 s47, s13, s34
	s_addc_u32 s48, s21, s35
	s_add_u32 s44, s47, 0x100
	s_addc_u32 s45, s48, 0
	s_mov_b32 m0, s94
	s_nop 0
	global_load_lds_dwordx4 v230, s[44:45]
	s_nop 0
	s_mov_b32 m0, s16
	s_nop 0
	global_load_lds_dwordx4 v231, s[44:45]
	s_barrier
	s_waitcnt lgkmcnt(0)
	s_setprio 1
	s_waitcnt lgkmcnt(3)
	v_mfma_f32_16x16x32_bf16 v[86:89], v[146:149], v[178:181], v[86:89]
	s_waitcnt lgkmcnt(1)
	v_mfma_f32_16x16x32_bf16 v[78:81], v[146:149], v[186:189], v[78:81]
	v_mfma_f32_16x16x32_bf16 v[66:69], v[154:157], v[178:181], v[66:69]
	v_mfma_f32_16x16x32_bf16 v[54:57], v[154:157], v[186:189], v[54:57]
	v_mfma_f32_16x16x32_bf16 v[46:49], v[162:165], v[178:181], v[46:49]
	v_mfma_f32_16x16x32_bf16 v[42:45], v[162:165], v[186:189], v[42:45]
	v_mfma_f32_16x16x32_bf16 v[38:41], v[170:173], v[178:181], v[38:41]
	v_mfma_f32_16x16x32_bf16 v[34:37], v[170:173], v[186:189], v[34:37]
	v_mfma_f32_16x16x32_bf16 v[86:89], v[150:153], v[182:185], v[86:89]
	s_waitcnt lgkmcnt(0)
	v_mfma_f32_16x16x32_bf16 v[78:81], v[150:153], v[190:193], v[78:81]
	v_mfma_f32_16x16x32_bf16 v[66:69], v[158:161], v[182:185], v[66:69]
	v_mfma_f32_16x16x32_bf16 v[54:57], v[158:161], v[190:193], v[54:57]
	v_mfma_f32_16x16x32_bf16 v[46:49], v[166:169], v[182:185], v[46:49]
	v_mfma_f32_16x16x32_bf16 v[42:45], v[166:169], v[190:193], v[42:45]
	v_mfma_f32_16x16x32_bf16 v[38:41], v[174:177], v[182:185], v[38:41]
	v_mfma_f32_16x16x32_bf16 v[34:37], v[174:177], v[190:193], v[34:37]
	s_setprio 0
	s_barrier
	ds_read_b128 v[146:149], v234 offset:16384
	ds_read_b128 v[150:153], v234 offset:17408
	ds_read_b128 v[154:157], v235 offset:16384
	ds_read_b128 v[158:161], v235 offset:17408
	ds_read_b128 v[162:165], v236 offset:16384
	ds_read_b128 v[166:169], v236 offset:17408
	ds_read_b128 v[170:173], v237 offset:16384
	ds_read_b128 v[174:177], v237 offset:17408
	s_add_u32 s49, s25, s34
	s_addc_u32 s50, s36, s35
	s_add_u32 s44, s49, 0x100
	s_addc_u32 s45, s50, 0
	s_mov_b32 m0, s95
	s_nop 0
	global_load_lds_dwordx4 v230, s[44:45]
	s_nop 0
	s_mov_b32 m0, s17
	s_nop 0
	global_load_lds_dwordx4 v231, s[44:45]
	s_barrier
	s_waitcnt lgkmcnt(0)
	s_setprio 1
	s_waitcnt lgkmcnt(7)
	v_mfma_f32_16x16x32_bf16 v[30:33], v[146:149], v[130:133], v[30:33]
	v_mfma_f32_16x16x32_bf16 v[26:29], v[146:149], v[138:141], v[26:29]
	s_waitcnt lgkmcnt(5)
	v_mfma_f32_16x16x32_bf16 v[22:25], v[154:157], v[130:133], v[22:25]
	v_mfma_f32_16x16x32_bf16 v[18:21], v[154:157], v[138:141], v[18:21]
	s_waitcnt lgkmcnt(3)
	v_mfma_f32_16x16x32_bf16 v[14:17], v[162:165], v[130:133], v[14:17]
	v_mfma_f32_16x16x32_bf16 v[10:13], v[162:165], v[138:141], v[10:13]
	s_waitcnt lgkmcnt(1)
	v_mfma_f32_16x16x32_bf16 v[6:9], v[170:173], v[130:133], v[6:9]
	v_mfma_f32_16x16x32_bf16 v[2:5], v[170:173], v[138:141], v[2:5]
	v_mfma_f32_16x16x32_bf16 v[30:33], v[150:153], v[134:137], v[30:33]
	v_mfma_f32_16x16x32_bf16 v[26:29], v[150:153], v[142:145], v[26:29]
	v_mfma_f32_16x16x32_bf16 v[22:25], v[158:161], v[134:137], v[22:25]
	v_mfma_f32_16x16x32_bf16 v[18:21], v[158:161], v[142:145], v[18:21]
	v_mfma_f32_16x16x32_bf16 v[14:17], v[166:169], v[134:137], v[14:17]
	v_mfma_f32_16x16x32_bf16 v[10:13], v[166:169], v[142:145], v[10:13]
	s_waitcnt lgkmcnt(0)
	v_mfma_f32_16x16x32_bf16 v[6:9], v[174:177], v[134:137], v[6:9]
	v_mfma_f32_16x16x32_bf16 v[2:5], v[174:177], v[142:145], v[2:5]
	s_setprio 0
	s_barrier
	s_add_u32 s51, s39, s34
	s_addc_u32 s86, s40, s35
	s_add_u32 s44, s51, 0x100
	s_addc_u32 s45, s86, 0
	s_mov_b32 m0, s10
	s_nop 0
	global_load_lds_dwordx4 v230, s[44:45]
	s_nop 0
	s_mov_b32 m0, s11
	s_nop 0
	global_load_lds_dwordx4 v231, s[44:45]
	s_waitcnt vmcnt(6)
	s_barrier
	s_setprio 1
	v_mfma_f32_16x16x32_bf16 v[50:53], v[146:149], v[178:181], v[50:53]
	v_mfma_f32_16x16x32_bf16 v[58:61], v[146:149], v[186:189], v[58:61]
	v_mfma_f32_16x16x32_bf16 v[62:65], v[154:157], v[178:181], v[62:65]
	v_mfma_f32_16x16x32_bf16 v[70:73], v[154:157], v[186:189], v[70:73]
	v_mfma_f32_16x16x32_bf16 v[74:77], v[162:165], v[178:181], v[74:77]
	v_mfma_f32_16x16x32_bf16 v[82:85], v[162:165], v[186:189], v[82:85]
	v_mfma_f32_16x16x32_bf16 v[90:93], v[170:173], v[178:181], v[90:93]
	v_mfma_f32_16x16x32_bf16 v[94:97], v[170:173], v[186:189], v[94:97]
	v_mfma_f32_16x16x32_bf16 v[50:53], v[150:153], v[182:185], v[50:53]
	v_mfma_f32_16x16x32_bf16 v[58:61], v[150:153], v[190:193], v[58:61]
	v_mfma_f32_16x16x32_bf16 v[62:65], v[158:161], v[182:185], v[62:65]
	v_mfma_f32_16x16x32_bf16 v[70:73], v[158:161], v[190:193], v[70:73]
	v_mfma_f32_16x16x32_bf16 v[74:77], v[166:169], v[182:185], v[74:77]
	v_mfma_f32_16x16x32_bf16 v[82:85], v[166:169], v[190:193], v[82:85]
	v_mfma_f32_16x16x32_bf16 v[90:93], v[174:177], v[182:185], v[90:93]
	v_mfma_f32_16x16x32_bf16 v[94:97], v[174:177], v[190:193], v[94:97]
	s_setprio 0
	s_barrier
	ds_read_b128 v[130:133], v239
	ds_read_b128 v[134:137], v239 offset:1024
	ds_read_b128 v[138:141], v239 offset:2048
	ds_read_b128 v[142:145], v239 offset:3072
	ds_read_b128 v[146:149], v234 offset:32768
	ds_read_b128 v[150:153], v234 offset:33792
	ds_read_b128 v[154:157], v235 offset:32768
	ds_read_b128 v[158:161], v235 offset:33792
	ds_read_b128 v[162:165], v236 offset:32768
	ds_read_b128 v[166:169], v236 offset:33792
	ds_read_b128 v[170:173], v237 offset:32768
	ds_read_b128 v[174:177], v237 offset:33792
	s_add_u32 s44, s43, 0x100
	s_addc_u32 s45, s46, 0
	s_mov_b32 m0, s6
	s_nop 0
	global_load_lds_dwordx4 v230, s[44:45]
	s_nop 0
	s_mov_b32 m0, s7
	s_nop 0
	global_load_lds_dwordx4 v231, s[44:45]
	s_waitcnt lgkmcnt(8)
	s_barrier
; #define STAGE(P, BASE, br, kt) do { const u16* _gb = (BASE) + (long)(br)*K + (long)(kt)*BK; \
;     unsigned _ld = lds0 + (unsigned)((char*)(P) - (char*)shm) + wv * 1024u; \
;     glds_s(_gb, voff0, _ld); glds_s(_gb, voff1, _ld + 8192u); } while (0)
; #define LDA(dst, b, h) for (int m = 0; m < 4; ++m) for (int k = 0; k < 2; ++k) \
;     dst[m][k] = *reinterpret_cast<const bf16x8*>((char*)SA(b, h) + lds_byte(wr * 64 + m * 16 + fr, k * 32 + fq * 8))
; #define LDB(dst, b, h) for (int n = 0; n < 2; ++n) for (int k = 0; k < 2; ++k) \
;     dst[n][k] = *reinterpret_cast<const bf16x8*>((char*)SB(b, h) + lds_byte(wc * 32 + n * 16 + fr, k * 32 + fq * 8))
; #define WAIT_V(n) asm volatile("s_waitcnt vmcnt(" #n ")" ::: "memory")
; #define WAIT_L(n) asm volatile("s_waitcnt lgkmcnt(" #n ")" ::: "memory")
; #define BAR __builtin_amdgcn_s_barrier()
; #define SCHED __builtin_amdgcn_sched_barrier(0)
;     ...
;       WAIT_L(8); BAR; WAIT_L(0); MMA(0, 0, At, B0); BAR; SCHED;
;       LDB(B1, 1, 1); STAGE(SB(1, 0), ActK, bcol, t + 3);
;       BAR; WAIT_L(0); MMA(0, 1, At, B1); BAR;
;       LDA(At, 1, 1); STAGE(SA(1, 0), WtK, brow, t + 3);
;       BAR; WAIT_L(0); MMA(1, 0, At, B0); BAR; SCHED;
;       STAGE(SB(1, 1), ActK, bcol + HALF, t + 3);
;       WAIT_V(6); BAR; MMA(1, 1, At, B1); BAR;
;     }
	s_waitcnt lgkmcnt(0)
	s_setprio 1
	s_waitcnt lgkmcnt(7)
	v_mfma_f32_16x16x32_bf16 v[126:129], v[146:149], v[130:133], v[126:129]
	v_mfma_f32_16x16x32_bf16 v[122:125], v[146:149], v[138:141], v[122:125]
	s_waitcnt lgkmcnt(5)
	v_mfma_f32_16x16x32_bf16 v[118:121], v[154:157], v[130:133], v[118:121]
	v_mfma_f32_16x16x32_bf16 v[114:117], v[154:157], v[138:141], v[114:117]
	s_waitcnt lgkmcnt(3)
	v_mfma_f32_16x16x32_bf16 v[110:113], v[162:165], v[130:133], v[110:113]
	v_mfma_f32_16x16x32_bf16 v[106:109], v[162:165], v[138:141], v[106:109]
	s_waitcnt lgkmcnt(1)
	v_mfma_f32_16x16x32_bf16 v[102:105], v[170:173], v[130:133], v[102:105]
	v_mfma_f32_16x16x32_bf16 v[98:101], v[170:173], v[138:141], v[98:101]
	v_mfma_f32_16x16x32_bf16 v[126:129], v[150:153], v[134:137], v[126:129]
	v_mfma_f32_16x16x32_bf16 v[122:125], v[150:153], v[142:145], v[122:125]
	v_mfma_f32_16x16x32_bf16 v[118:121], v[158:161], v[134:137], v[118:121]
	v_mfma_f32_16x16x32_bf16 v[114:117], v[158:161], v[142:145], v[114:117]
	v_mfma_f32_16x16x32_bf16 v[110:113], v[166:169], v[134:137], v[110:113]
	v_mfma_f32_16x16x32_bf16 v[106:109], v[166:169], v[142:145], v[106:109]
	s_waitcnt lgkmcnt(0)
	v_mfma_f32_16x16x32_bf16 v[102:105], v[174:177], v[134:137], v[102:105]
	v_mfma_f32_16x16x32_bf16 v[98:101], v[174:177], v[142:145], v[98:101]
	s_setprio 0
	s_barrier
	ds_read_b128 v[178:181], v240
	ds_read_b128 v[182:185], v240 offset:1024
	ds_read_b128 v[186:189], v240 offset:2048
	ds_read_b128 v[190:193], v240 offset:3072
	s_add_u32 s44, s47, 0x180
	s_addc_u32 s45, s48, 0
	s_mov_b32 m0, s8
	s_nop 0
	global_load_lds_dwordx4 v230, s[44:45]
	s_nop 0
	s_mov_b32 m0, s9
	s_nop 0
	global_load_lds_dwordx4 v231, s[44:45]
	s_barrier
	s_waitcnt lgkmcnt(0)
	s_setprio 1
	s_waitcnt lgkmcnt(3)
	v_mfma_f32_16x16x32_bf16 v[86:89], v[146:149], v[178:181], v[86:89]
	s_waitcnt lgkmcnt(1)
	v_mfma_f32_16x16x32_bf16 v[78:81], v[146:149], v[186:189], v[78:81]
	v_mfma_f32_16x16x32_bf16 v[66:69], v[154:157], v[178:181], v[66:69]
	v_mfma_f32_16x16x32_bf16 v[54:57], v[154:157], v[186:189], v[54:57]
	v_mfma_f32_16x16x32_bf16 v[46:49], v[162:165], v[178:181], v[46:49]
	v_mfma_f32_16x16x32_bf16 v[42:45], v[162:165], v[186:189], v[42:45]
	v_mfma_f32_16x16x32_bf16 v[38:41], v[170:173], v[178:181], v[38:41]
	v_mfma_f32_16x16x32_bf16 v[34:37], v[170:173], v[186:189], v[34:37]
	v_mfma_f32_16x16x32_bf16 v[86:89], v[150:153], v[182:185], v[86:89]
	s_waitcnt lgkmcnt(0)
	v_mfma_f32_16x16x32_bf16 v[78:81], v[150:153], v[190:193], v[78:81]
	v_mfma_f32_16x16x32_bf16 v[66:69], v[158:161], v[182:185], v[66:69]
	v_mfma_f32_16x16x32_bf16 v[54:57], v[158:161], v[190:193], v[54:57]
	v_mfma_f32_16x16x32_bf16 v[46:49], v[166:169], v[182:185], v[46:49]
	v_mfma_f32_16x16x32_bf16 v[42:45], v[166:169], v[190:193], v[42:45]
	v_mfma_f32_16x16x32_bf16 v[38:41], v[174:177], v[182:185], v[38:41]
	v_mfma_f32_16x16x32_bf16 v[34:37], v[174:177], v[190:193], v[34:37]
	s_setprio 0
	s_barrier
	ds_read_b128 v[146:149], v234 offset:49152
	ds_read_b128 v[150:153], v234 offset:50176
	ds_read_b128 v[154:157], v235 offset:49152
	ds_read_b128 v[158:161], v235 offset:50176
	ds_read_b128 v[162:165], v236 offset:49152
	ds_read_b128 v[166:169], v236 offset:50176
	ds_read_b128 v[170:173], v237 offset:49152
	ds_read_b128 v[174:177], v237 offset:50176
	s_add_u32 s44, s49, 0x180
	s_addc_u32 s45, s50, 0
	s_mov_b32 m0, s92
	s_nop 0
	global_load_lds_dwordx4 v230, s[44:45]
	s_nop 0
	s_mov_b32 m0, s93
	s_nop 0
	global_load_lds_dwordx4 v231, s[44:45]
	s_barrier
	s_waitcnt lgkmcnt(0)
	s_setprio 1
	s_waitcnt lgkmcnt(7)
	v_mfma_f32_16x16x32_bf16 v[30:33], v[146:149], v[130:133], v[30:33]
	v_mfma_f32_16x16x32_bf16 v[26:29], v[146:149], v[138:141], v[26:29]
	s_waitcnt lgkmcnt(5)
	v_mfma_f32_16x16x32_bf16 v[22:25], v[154:157], v[130:133], v[22:25]
	v_mfma_f32_16x16x32_bf16 v[18:21], v[154:157], v[138:141], v[18:21]
	s_waitcnt lgkmcnt(3)
	v_mfma_f32_16x16x32_bf16 v[14:17], v[162:165], v[130:133], v[14:17]
	v_mfma_f32_16x16x32_bf16 v[10:13], v[162:165], v[138:141], v[10:13]
	s_waitcnt lgkmcnt(1)
	v_mfma_f32_16x16x32_bf16 v[6:9], v[170:173], v[130:133], v[6:9]
	v_mfma_f32_16x16x32_bf16 v[2:5], v[170:173], v[138:141], v[2:5]
	v_mfma_f32_16x16x32_bf16 v[30:33], v[150:153], v[134:137], v[30:33]
	v_mfma_f32_16x16x32_bf16 v[26:29], v[150:153], v[142:145], v[26:29]
	v_mfma_f32_16x16x32_bf16 v[22:25], v[158:161], v[134:137], v[22:25]
	v_mfma_f32_16x16x32_bf16 v[18:21], v[158:161], v[142:145], v[18:21]
	v_mfma_f32_16x16x32_bf16 v[14:17], v[166:169], v[134:137], v[14:17]
	v_mfma_f32_16x16x32_bf16 v[10:13], v[166:169], v[142:145], v[10:13]
	s_waitcnt lgkmcnt(0)
	v_mfma_f32_16x16x32_bf16 v[6:9], v[174:177], v[134:137], v[6:9]
	v_mfma_f32_16x16x32_bf16 v[2:5], v[174:177], v[142:145], v[2:5]
	s_setprio 0
	s_barrier
	s_add_u32 s44, s51, 0x180
	s_addc_u32 s45, s86, 0
	s_mov_b32 m0, s14
	s_nop 0
	global_load_lds_dwordx4 v230, s[44:45]
	s_nop 0
	s_mov_b32 m0, s15
	s_nop 0
	global_load_lds_dwordx4 v231, s[44:45]
	s_waitcnt vmcnt(6)
	s_barrier
	s_setprio 1
	v_mfma_f32_16x16x32_bf16 v[50:53], v[146:149], v[178:181], v[50:53]
	v_mfma_f32_16x16x32_bf16 v[58:61], v[146:149], v[186:189], v[58:61]
	v_mfma_f32_16x16x32_bf16 v[62:65], v[154:157], v[178:181], v[62:65]
	v_mfma_f32_16x16x32_bf16 v[70:73], v[154:157], v[186:189], v[70:73]
	v_mfma_f32_16x16x32_bf16 v[74:77], v[162:165], v[178:181], v[74:77]
	v_mfma_f32_16x16x32_bf16 v[82:85], v[162:165], v[186:189], v[82:85]
	v_mfma_f32_16x16x32_bf16 v[90:93], v[170:173], v[178:181], v[90:93]
	v_mfma_f32_16x16x32_bf16 v[94:97], v[170:173], v[186:189], v[94:97]
	v_mfma_f32_16x16x32_bf16 v[50:53], v[150:153], v[182:185], v[50:53]
	v_mfma_f32_16x16x32_bf16 v[58:61], v[150:153], v[190:193], v[58:61]
	v_mfma_f32_16x16x32_bf16 v[62:65], v[158:161], v[182:185], v[62:65]
	v_mfma_f32_16x16x32_bf16 v[70:73], v[158:161], v[190:193], v[70:73]
	v_mfma_f32_16x16x32_bf16 v[74:77], v[166:169], v[182:185], v[74:77]
	v_mfma_f32_16x16x32_bf16 v[82:85], v[166:169], v[190:193], v[82:85]
	v_mfma_f32_16x16x32_bf16 v[90:93], v[174:177], v[182:185], v[90:93]
	v_mfma_f32_16x16x32_bf16 v[94:97], v[174:177], v[190:193], v[94:97]
	s_setprio 0
	s_add_u32 s34, s34, 0x100
	s_addc_u32 s35, s35, 0
	s_cmp_ge_i32 s42, s41
	s_barrier
; #define STAGE(P, BASE, br, kt) do { const u16* _gb = (BASE) + (long)(br)*K + (long)(kt)*BK; \
;     unsigned _ld = lds0 + (unsigned)((char*)(P) - (char*)shm) + wv * 1024u; \
;     glds_s(_gb, voff0, _ld); glds_s(_gb, voff1, _ld + 8192u); } while (0)
; #define LDA(dst, b, h) for (int m = 0; m < 4; ++m) for (int k = 0; k < 2; ++k) \
;     dst[m][k] = *reinterpret_cast<const bf16x8*>((char*)SA(b, h) + lds_byte(wr * 64 + m * 16 + fr, k * 32 + fq * 8))
; #define LDB(dst, b, h) for (int n = 0; n < 2; ++n) for (int k = 0; k < 2; ++k) \
;     dst[n][k] = *reinterpret_cast<const bf16x8*>((char*)SB(b, h) + lds_byte(wc * 32 + n * 16 + fr, k * 32 + fq * 8))
; #define WAIT_V(n) asm volatile("s_waitcnt vmcnt(" #n ")" ::: "memory")
; #define WAIT_L(n) asm volatile("s_waitcnt lgkmcnt(" #n ")" ::: "memory")
; #define BAR __builtin_amdgcn_s_barrier()
;     ...
;     { LDB(B0, 0, 0); LDA(At, 0, 0); STAGE(SA(1, 1), WtK, brow + HALF, nt - 1);
;       BAR; WAIT_L(0); MMA(0, 0, At, B0); BAR;
;       LDB(B1, 0, 1); BAR; WAIT_L(0); MMA(0, 1, At, B1); BAR;
;       LDA(At, 0, 1); WAIT_V(4); BAR; WAIT_L(0); MMA(1, 0, At, B0); MMA(1, 1, At, B1); BAR; }
;     { LDB(B0, 1, 0); LDA(At, 1, 0); WAIT_V(2); BAR; WAIT_L(0); MMA(0, 0, At, B0); BAR;
	s_cbranch_scc0 .LBB0_72
	ds_read_b128 v[130:133], v233
	ds_read_b128 v[134:137], v233 offset:1024
	ds_read_b128 v[138:141], v233 offset:2048
	ds_read_b128 v[142:145], v233 offset:3072
	ds_read_b128 v[146:149], v234
	ds_read_b128 v[150:153], v234 offset:1024
	ds_read_b128 v[154:157], v235
	ds_read_b128 v[158:161], v235 offset:1024
	ds_read_b128 v[162:165], v236
	ds_read_b128 v[166:169], v236 offset:1024
	ds_read_b128 v[170:173], v237
	ds_read_b128 v[182:185], v237 offset:1024
	s_mov_b32 s21, s1
	v_readlane_b32 s40, v255, 5
	s_lshl_b64 s[34:35], s[20:21], 1
	v_readlane_b32 s42, v255, 7
	v_readlane_b32 s43, v255, 8
	s_add_u32 s36, s42, s34
	s_addc_u32 s39, s43, s35
	s_add_u32 s13, s97, s34
	s_addc_u32 s21, s56, s35
	s_add_i32 s0, s0, -1
	s_lshl_b64 s[34:35], s[0:1], 7
	s_add_u32 s34, s37, s34
	s_addc_u32 s35, s38, s35
	s_mov_b32 m0, s18
	s_nop 0
	global_load_lds_dwordx4 v230, s[34:35]
	v_readlane_b32 s41, v255, 6
	s_mov_b32 m0, s19
	s_nop 0
	global_load_lds_dwordx4 v231, s[34:35]
	s_barrier
	s_waitcnt lgkmcnt(0)
	v_readlane_b32 s44, v255, 9
	v_readlane_b32 s45, v255, 10
	v_readlane_b32 s46, v255, 11
	v_readlane_b32 s47, v255, 12
	v_readlane_b32 s48, v255, 13
	v_readlane_b32 s49, v255, 14
	v_readlane_b32 s50, v255, 15
	v_readlane_b32 s51, v255, 16
	v_readlane_b32 s52, v255, 17
	v_readlane_b32 s53, v255, 18
	v_readlane_b32 s54, v255, 19
	v_readlane_b32 s55, v255, 20
	s_setprio 1
	s_waitcnt lgkmcnt(7)
	v_mfma_f32_16x16x32_bf16 v[126:129], v[146:149], v[130:133], v[126:129]
	v_mfma_f32_16x16x32_bf16 v[122:125], v[146:149], v[138:141], v[122:125]
	s_waitcnt lgkmcnt(5)
	v_mfma_f32_16x16x32_bf16 v[118:121], v[154:157], v[130:133], v[118:121]
	v_mfma_f32_16x16x32_bf16 v[114:117], v[154:157], v[138:141], v[114:117]
	s_waitcnt lgkmcnt(3)
	v_mfma_f32_16x16x32_bf16 v[110:113], v[162:165], v[130:133], v[110:113]
	v_mfma_f32_16x16x32_bf16 v[106:109], v[162:165], v[138:141], v[106:109]
	s_waitcnt lgkmcnt(1)
	v_mfma_f32_16x16x32_bf16 v[102:105], v[170:173], v[130:133], v[102:105]
	v_mfma_f32_16x16x32_bf16 v[98:101], v[170:173], v[138:141], v[98:101]
	v_mfma_f32_16x16x32_bf16 v[126:129], v[150:153], v[134:137], v[126:129]
	v_mfma_f32_16x16x32_bf16 v[122:125], v[150:153], v[142:145], v[122:125]
	v_mfma_f32_16x16x32_bf16 v[118:121], v[158:161], v[134:137], v[118:121]
	v_mfma_f32_16x16x32_bf16 v[186:189], v[158:161], v[142:145], v[114:117]
	v_mfma_f32_16x16x32_bf16 v[110:113], v[166:169], v[134:137], v[110:113]
	v_mfma_f32_16x16x32_bf16 v[190:193], v[166:169], v[142:145], v[106:109]
	s_waitcnt lgkmcnt(0)
	v_mfma_f32_16x16x32_bf16 v[194:197], v[182:185], v[134:137], v[102:105]
	v_mfma_f32_16x16x32_bf16 v[198:201], v[182:185], v[142:145], v[98:101]
	s_setprio 0
	s_barrier
	ds_read_b128 v[202:205], v238
	ds_read_b128 v[206:209], v238 offset:1024
	ds_read_b128 v[210:213], v238 offset:2048
	ds_read_b128 v[242:245], v238 offset:3072
	s_barrier
	s_waitcnt lgkmcnt(0)
	s_setprio 1
	s_waitcnt lgkmcnt(3)
	v_mfma_f32_16x16x32_bf16 v[86:89], v[146:149], v[202:205], v[86:89]
	s_waitcnt lgkmcnt(1)
	v_mfma_f32_16x16x32_bf16 v[78:81], v[146:149], v[210:213], v[78:81]
	v_mfma_f32_16x16x32_bf16 v[66:69], v[154:157], v[202:205], v[66:69]
	v_mfma_f32_16x16x32_bf16 v[106:109], v[154:157], v[210:213], v[54:57]
	v_mfma_f32_16x16x32_bf16 v[46:49], v[162:165], v[202:205], v[46:49]
	v_mfma_f32_16x16x32_bf16 v[42:45], v[162:165], v[210:213], v[42:45]
	v_mfma_f32_16x16x32_bf16 v[38:41], v[170:173], v[202:205], v[38:41]
	v_mfma_f32_16x16x32_bf16 v[34:37], v[170:173], v[210:213], v[34:37]
	v_mfma_f32_16x16x32_bf16 v[54:57], v[150:153], v[206:209], v[86:89]
	s_waitcnt lgkmcnt(0)
	v_mfma_f32_16x16x32_bf16 v[98:101], v[150:153], v[242:245], v[78:81]
	v_mfma_f32_16x16x32_bf16 v[102:105], v[158:161], v[206:209], v[66:69]
	v_mfma_f32_16x16x32_bf16 v[106:109], v[158:161], v[242:245], v[106:109]
	v_mfma_f32_16x16x32_bf16 v[114:117], v[166:169], v[206:209], v[46:49]
	v_mfma_f32_16x16x32_bf16 v[174:177], v[166:169], v[242:245], v[42:45]
	v_mfma_f32_16x16x32_bf16 v[178:181], v[182:185], v[206:209], v[38:41]
	v_mfma_f32_16x16x32_bf16 v[182:185], v[182:185], v[242:245], v[34:37]
	s_setprio 0
	s_barrier
	ds_read_b128 v[66:69], v234 offset:16384
	ds_read_b128 v[78:81], v234 offset:17408
	ds_read_b128 v[86:89], v235 offset:16384
	ds_read_b128 v[146:149], v235 offset:17408
	ds_read_b128 v[150:153], v236 offset:16384
	ds_read_b128 v[154:157], v236 offset:17408
	ds_read_b128 v[158:161], v237 offset:16384
	ds_read_b128 v[162:165], v237 offset:17408
	s_waitcnt vmcnt(4)
	s_barrier
; #define STAGE(P, BASE, br, kt) do { const u16* _gb = (BASE) + (long)(br)*K + (long)(kt)*BK; \
;     unsigned _ld = lds0 + (unsigned)((char*)(P) - (char*)shm) + wv * 1024u; \
;     glds_s(_gb, voff0, _ld); glds_s(_gb, voff1, _ld + 8192u); } while (0)
; #define LDA(dst, b, h) for (int m = 0; m < 4; ++m) for (int k = 0; k < 2; ++k) \
;     dst[m][k] = *reinterpret_cast<const bf16x8*>((char*)SA(b, h) + lds_byte(wr * 64 + m * 16 + fr, k * 32 + fq * 8))
; #define LDB(dst, b, h) for (int n = 0; n < 2; ++n) for (int k = 0; k < 2; ++k) \
;     dst[n][k] = *reinterpret_cast<const bf16x8*>((char*)SB(b, h) + lds_byte(wc * 32 + n * 16 + fr, k * 32 + fq * 8))
; #define WAIT_V(n) asm volatile("s_waitcnt vmcnt(" #n ")" ::: "memory")
; #define WAIT_L(n) asm volatile("s_waitcnt lgkmcnt(" #n ")" ::: "memory")
; #define BAR __builtin_amdgcn_s_barrier()
;     ...
;       LDA(At, 0, 1); WAIT_V(4); BAR; WAIT_L(0); MMA(1, 0, At, B0); MMA(1, 1, At, B1); BAR; }
;     { LDB(B0, 1, 0); LDA(At, 1, 0); WAIT_V(2); BAR; WAIT_L(0); MMA(0, 0, At, B0); BAR;
;       LDB(B1, 1, 1);
;       if (has_next) { STAGE(SB(0, 0), ActN, nbcol, 0); STAGE(SA(0, 0), WtN, nbrow, 0); WAIT_V(4); } else { WAIT_V(0); }
;       BAR; WAIT_L(0); MMA(0, 1, At, B1); BAR;
	s_waitcnt lgkmcnt(0)
	s_setprio 1
	s_waitcnt lgkmcnt(7)
	v_mfma_f32_16x16x32_bf16 v[30:33], v[66:69], v[130:133], v[30:33]
	v_mfma_f32_16x16x32_bf16 v[26:29], v[66:69], v[138:141], v[26:29]
	s_waitcnt lgkmcnt(5)
	v_mfma_f32_16x16x32_bf16 v[22:25], v[86:89], v[130:133], v[22:25]
	v_mfma_f32_16x16x32_bf16 v[18:21], v[86:89], v[138:141], v[18:21]
	s_waitcnt lgkmcnt(3)
	v_mfma_f32_16x16x32_bf16 v[34:37], v[150:153], v[130:133], v[14:17]
	v_mfma_f32_16x16x32_bf16 v[38:41], v[150:153], v[138:141], v[10:13]
	s_waitcnt lgkmcnt(1)
	v_mfma_f32_16x16x32_bf16 v[42:45], v[158:161], v[130:133], v[6:9]
	v_mfma_f32_16x16x32_bf16 v[46:49], v[158:161], v[138:141], v[2:5]
	v_mfma_f32_16x16x32_bf16 v[2:5], v[78:81], v[134:137], v[30:33]
	v_mfma_f32_16x16x32_bf16 v[6:9], v[78:81], v[142:145], v[26:29]
	v_mfma_f32_16x16x32_bf16 v[10:13], v[146:149], v[134:137], v[22:25]
	v_mfma_f32_16x16x32_bf16 v[14:17], v[146:149], v[142:145], v[18:21]
	v_mfma_f32_16x16x32_bf16 v[34:37], v[154:157], v[134:137], v[34:37]
	v_mfma_f32_16x16x32_bf16 v[38:41], v[154:157], v[142:145], v[38:41]
	s_waitcnt lgkmcnt(0)
	v_mfma_f32_16x16x32_bf16 v[42:45], v[162:165], v[134:137], v[42:45]
	v_mfma_f32_16x16x32_bf16 v[46:49], v[162:165], v[142:145], v[46:49]
	s_setprio 0
	s_setprio 1
	v_mfma_f32_16x16x32_bf16 v[18:21], v[66:69], v[202:205], v[50:53]
	v_mfma_f32_16x16x32_bf16 v[22:25], v[66:69], v[210:213], v[58:61]
	v_mfma_f32_16x16x32_bf16 v[26:29], v[86:89], v[202:205], v[62:65]
	v_mfma_f32_16x16x32_bf16 v[30:33], v[86:89], v[210:213], v[70:73]
	v_mfma_f32_16x16x32_bf16 v[50:53], v[150:153], v[202:205], v[74:77]
	v_mfma_f32_16x16x32_bf16 v[58:61], v[150:153], v[210:213], v[82:85]
	v_mfma_f32_16x16x32_bf16 v[62:65], v[158:161], v[202:205], v[90:93]
	v_mfma_f32_16x16x32_bf16 v[66:69], v[158:161], v[210:213], v[94:97]
	v_mfma_f32_16x16x32_bf16 v[130:133], v[78:81], v[206:209], v[18:21]
	v_mfma_f32_16x16x32_bf16 v[134:137], v[78:81], v[242:245], v[22:25]
	v_mfma_f32_16x16x32_bf16 v[138:141], v[146:149], v[206:209], v[26:29]
	v_mfma_f32_16x16x32_bf16 v[142:145], v[146:149], v[242:245], v[30:33]
	v_mfma_f32_16x16x32_bf16 v[146:149], v[154:157], v[206:209], v[50:53]
	v_mfma_f32_16x16x32_bf16 v[150:153], v[154:157], v[242:245], v[58:61]
	v_mfma_f32_16x16x32_bf16 v[154:157], v[162:165], v[206:209], v[62:65]
	v_mfma_f32_16x16x32_bf16 v[158:161], v[162:165], v[242:245], v[66:69]
	s_setprio 0
	s_barrier
	ds_read_b128 v[70:73], v239
	ds_read_b128 v[66:69], v239 offset:1024
	ds_read_b128 v[74:77], v239 offset:2048
	ds_read_b128 v[162:165], v239 offset:3072
	ds_read_b128 v[26:29], v234 offset:32768
	ds_read_b128 v[18:21], v234 offset:33792
	ds_read_b128 v[30:33], v235 offset:32768
	ds_read_b128 v[22:25], v235 offset:33792
	ds_read_b128 v[58:61], v236 offset:32768
	ds_read_b128 v[50:53], v236 offset:33792
	ds_read_b128 v[62:65], v237 offset:32768
	ds_read_b128 v[82:85], v237 offset:33792
	s_waitcnt vmcnt(2)
	s_barrier
	s_waitcnt lgkmcnt(0)
	s_setprio 1
	s_waitcnt lgkmcnt(7)
	v_mfma_f32_16x16x32_bf16 v[78:81], v[26:29], v[70:73], v[126:129]
	v_mfma_f32_16x16x32_bf16 v[86:89], v[26:29], v[74:77], v[122:125]
	s_waitcnt lgkmcnt(5)
	v_mfma_f32_16x16x32_bf16 v[90:93], v[30:33], v[70:73], v[118:121]
	v_mfma_f32_16x16x32_bf16 v[118:121], v[30:33], v[74:77], v[186:189]
	s_waitcnt lgkmcnt(3)
	v_mfma_f32_16x16x32_bf16 v[110:113], v[58:61], v[70:73], v[110:113]
	v_mfma_f32_16x16x32_bf16 v[166:169], v[58:61], v[74:77], v[190:193]
	s_waitcnt lgkmcnt(1)
	v_mfma_f32_16x16x32_bf16 v[170:173], v[62:65], v[70:73], v[194:197]
	v_mfma_f32_16x16x32_bf16 v[186:189], v[62:65], v[74:77], v[198:201]
	v_mfma_f32_16x16x32_bf16 v[126:129], v[18:21], v[66:69], v[78:81]
	v_mfma_f32_16x16x32_bf16 v[94:97], v[18:21], v[162:165], v[86:89]
	v_mfma_f32_16x16x32_bf16 v[122:125], v[22:25], v[66:69], v[90:93]
	v_mfma_f32_16x16x32_bf16 v[90:93], v[22:25], v[162:165], v[118:121]
	v_mfma_f32_16x16x32_bf16 v[118:121], v[50:53], v[66:69], v[110:113]
	v_mfma_f32_16x16x32_bf16 v[86:89], v[50:53], v[162:165], v[166:169]
	s_waitcnt lgkmcnt(0)
	v_mfma_f32_16x16x32_bf16 v[110:113], v[82:85], v[66:69], v[170:173]
	v_mfma_f32_16x16x32_bf16 v[78:81], v[82:85], v[162:165], v[186:189]
	s_setprio 0
	s_barrier
	s_nop 0
	ds_read_b128 v[186:189], v240
	ds_read_b128 v[166:169], v240 offset:1024
	ds_read_b128 v[190:193], v240 offset:2048
	ds_read_b128 v[170:173], v240 offset:3072
	s_mov_b64 s[34:35], -1
	s_and_b64 vcc, exec, s[64:65]
	s_cbranch_vccz .LBB0_75
	s_waitcnt vmcnt(0)
	s_mov_b64 s[34:35], 0
; #define STAGE(P, BASE, br, kt) do { const u16* _gb = (BASE) + (long)(br)*K + (long)(kt)*BK; \
;     unsigned _ld = lds0 + (unsigned)((char*)(P) - (char*)shm) + wv * 1024u; \
;     glds_s(_gb, voff0, _ld); glds_s(_gb, voff1, _ld + 8192u); } while (0)
; #define LDA(dst, b, h) for (int m = 0; m < 4; ++m) for (int k = 0; k < 2; ++k) \
;     dst[m][k] = *reinterpret_cast<const bf16x8*>((char*)SA(b, h) + lds_byte(wr * 64 + m * 16 + fr, k * 32 + fq * 8))
; #define LDB(dst, b, h) for (int n = 0; n < 2; ++n) for (int k = 0; k < 2; ++k) \
;     dst[n][k] = *reinterpret_cast<const bf16x8*>((char*)SB(b, h) + lds_byte(wc * 32 + n * 16 + fr, k * 32 + fq * 8))
; #define WAIT_V(n) asm volatile("s_waitcnt vmcnt(" #n ")" ::: "memory")
; #define WAIT_L(n) asm volatile("s_waitcnt lgkmcnt(" #n ")" ::: "memory")
; #define BAR __builtin_amdgcn_s_barrier()
;     ...
;     { LDB(B0, 1, 0); LDA(At, 1, 0); WAIT_V(2); BAR; WAIT_L(0); MMA(0, 0, At, B0); BAR;
;       LDB(B1, 1, 1);
;       if (has_next) { STAGE(SB(0, 0), ActN, nbcol, 0); STAGE(SA(0, 0), WtN, nbrow, 0); WAIT_V(4); } else { WAIT_V(0); }
;       BAR; WAIT_L(0); MMA(0, 1, At, B1); BAR;
;       LDA(At, 1, 1);
;       if (has_next) { STAGE(SB(0, 1), ActN, nbcol + HALF, 0); STAGE(SA(0, 1), WtN, nbrow + HALF, 0); }
;       BAR; WAIT_L(0); MMA(1, 0, At, B0); MMA(1, 1, At, B1); BAR; }
.LBB0_75:
	s_andn2_b64 vcc, exec, s[34:35]
	s_mov_b32 s46, 0x800000
	s_mov_b32 s40, s62
	s_cbranch_vccnz .LBB0_77
	s_ashr_i32 s25, s24, 31
	s_lshl_b64 s[34:35], s[24:25], 11
	s_add_u32 s34, s36, s34
	s_addc_u32 s35, s39, s35
	s_mov_b32 m0, s94
	s_nop 0
	global_load_lds_dwordx4 v230, s[34:35]
	s_ashr_i32 s41, s40, 31
	s_mov_b32 m0, s16
	s_nop 0
	global_load_lds_dwordx4 v231, s[34:35]
	s_lshl_b64 s[34:35], s[40:41], 11
	s_add_u32 s34, s13, s34
	s_addc_u32 s35, s21, s35
	s_mov_b32 m0, s95
	s_nop 0
	global_load_lds_dwordx4 v230, s[34:35]
	s_nop 0
	s_mov_b32 m0, s17
	s_nop 0
	global_load_lds_dwordx4 v231, s[34:35]
	s_waitcnt vmcnt(4)
.LBB0_77:
	s_barrier
	s_waitcnt lgkmcnt(0)
	s_setprio 1
	s_waitcnt lgkmcnt(3)
	v_mfma_f32_16x16x32_bf16 v[54:57], v[26:29], v[186:189], v[54:57]
	s_waitcnt lgkmcnt(1)
	v_mfma_f32_16x16x32_bf16 v[26:29], v[26:29], v[190:193], v[98:101]
	v_mfma_f32_16x16x32_bf16 v[98:101], v[30:33], v[186:189], v[102:105]
	v_mfma_f32_16x16x32_bf16 v[102:105], v[30:33], v[190:193], v[106:109]
	v_mfma_f32_16x16x32_bf16 v[106:109], v[58:61], v[186:189], v[114:117]
	v_mfma_f32_16x16x32_bf16 v[114:117], v[58:61], v[190:193], v[174:177]
	v_mfma_f32_16x16x32_bf16 v[174:177], v[62:65], v[186:189], v[178:181]
	v_mfma_f32_16x16x32_bf16 v[178:181], v[62:65], v[190:193], v[182:185]
	v_mfma_f32_16x16x32_bf16 v[62:65], v[18:21], v[166:169], v[54:57]
	s_waitcnt lgkmcnt(0)
	v_mfma_f32_16x16x32_bf16 v[30:33], v[18:21], v[170:173], v[26:29]
	v_mfma_f32_16x16x32_bf16 v[58:61], v[22:25], v[166:169], v[98:101]
	v_mfma_f32_16x16x32_bf16 v[26:29], v[22:25], v[170:173], v[102:105]
	v_mfma_f32_16x16x32_bf16 v[54:57], v[50:53], v[166:169], v[106:109]
	v_mfma_f32_16x16x32_bf16 v[22:25], v[50:53], v[170:173], v[114:117]
	v_mfma_f32_16x16x32_bf16 v[50:53], v[82:85], v[166:169], v[174:177]
	v_mfma_f32_16x16x32_bf16 v[18:21], v[82:85], v[170:173], v[178:181]
	s_setprio 0
	s_barrier
	ds_read_b128 v[198:201], v234 offset:49152
	ds_read_b128 v[174:177], v234 offset:50176
	ds_read_b128 v[202:205], v235 offset:49152
	ds_read_b128 v[178:181], v235 offset:50176
	ds_read_b128 v[206:209], v236 offset:49152
	ds_read_b128 v[182:185], v236 offset:50176
	ds_read_b128 v[210:213], v237 offset:49152
	ds_read_b128 v[194:197], v237 offset:50176
	s_andn2_b64 vcc, exec, s[26:27]
	s_cbranch_vccnz .LBB0_79
	s_ashr_i32 s25, s24, 31
	s_lshl_b64 s[26:27], s[24:25], 11
	s_add_u32 s0, s36, s26
	s_addc_u32 s25, s39, s27
	s_add_u32 s26, s0, 0x40000
	s_addc_u32 s27, s25, 0
	s_mov_b32 m0, s10
	s_nop 0
	global_load_lds_dwordx4 v230, s[26:27]
	s_ashr_i32 s41, s40, 31
	s_mov_b32 m0, s11
	s_nop 0
	global_load_lds_dwordx4 v231, s[26:27]
	s_lshl_b64 s[26:27], s[40:41], 11
	s_add_u32 s0, s13, s26
	s_addc_u32 s13, s21, s27
	s_add_u32 s26, s0, 0x40000
	s_addc_u32 s27, s13, 0
	s_mov_b32 m0, s6
	s_nop 0
	global_load_lds_dwordx4 v230, s[26:27]
	s_nop 0
	s_mov_b32 m0, s7
	s_nop 0
	global_load_lds_dwordx4 v231, s[26:27]

; #define STAGE(P, BASE, br, kt) do { const u16* _gb = (BASE) + (long)(br)*K + (long)(kt)*BK; \
;     unsigned _ld = lds0 + (unsigned)((char*)(P) - (char*)shm) + wv * 1024u; \
;     glds_s(_gb, voff0, _ld); glds_s(_gb, voff1, _ld + 8192u); } while (0)
; #define WAIT_V(n) asm volatile("s_waitcnt vmcnt(" #n ")" ::: "memory")
; #define BAR __builtin_amdgcn_s_barrier()
;     ...
;     const bool is_split = v >= nwg_reg;
;     const int nt = (is_split ? kchunk : K) / BK;
;     const u16* ActK = Act + koff; const u16* WtK = Wt + koff;
;     const u16* ActN = Act + nkoff; const u16* WtN = Wt + nkoff;
;     f32x4 acc[2][2][4][2] = {};
;     bf16x8 At[4][2], B0[2][2], B1[2][2];
;     if (!staged) {
;       STAGE(SB(0, 0), ActK, bcol, 0); STAGE(SA(0, 0), WtK, brow, 0);
;       STAGE(SB(0, 1), ActK, bcol + HALF, 0); STAGE(SA(0, 1), WtK, brow + HALF, 0);
;       if (wr == 1) BAR;
;       WAIT_V(4); BAR;
.LBB0_126:
	v_readlane_b32 s40, v255, 5
	s_xor_b64 s[30:31], s[30:31], -1
	s_lshl_b64 s[34:35], s[0:1], 1
	v_readlane_b32 s42, v255, 7
	v_readlane_b32 s43, v255, 8
	s_add_u32 s39, s42, s34
	s_addc_u32 s40, s43, s35
	s_add_u32 s37, s97, s34
	s_addc_u32 s38, s56, s35
	s_andn2_b64 vcc, exec, s[30:31]
	s_mov_b64 s[30:31], -1
	v_readlane_b32 s41, v255, 6
	v_readlane_b32 s44, v255, 9
	v_readlane_b32 s45, v255, 10
	v_readlane_b32 s46, v255, 11
	v_readlane_b32 s47, v255, 12
	v_readlane_b32 s48, v255, 13
	v_readlane_b32 s49, v255, 14
	v_readlane_b32 s50, v255, 15
	v_readlane_b32 s51, v255, 16
	v_readlane_b32 s52, v255, 17
	v_readlane_b32 s53, v255, 18
	v_readlane_b32 s54, v255, 19
	v_readlane_b32 s55, v255, 20
	s_cbranch_vccnz .LBB0_130
	s_ashr_i32 s13, s12, 31
	s_lshl_b64 s[30:31], s[12:13], 12
	s_add_u32 s30, s39, s30
	s_addc_u32 s31, s40, s31
	s_ashr_i32 s5, s4, 31
	s_mov_b32 m0, s94
	s_nop 0
	global_load_lds_dwordx4 v230, s[30:31]
	s_lshl_b64 s[34:35], s[4:5], 12
	s_mov_b32 m0, s16
	s_nop 0
	global_load_lds_dwordx4 v231, s[30:31]
	s_add_u32 s30, s37, s34
	s_addc_u32 s31, s38, s35
	s_mov_b32 m0, s95
	s_nop 0
	global_load_lds_dwordx4 v230, s[30:31]
	s_nop 0
	s_mov_b32 m0, s17
	s_nop 0
	global_load_lds_dwordx4 v231, s[30:31]
	s_add_i32 s30, s12, 0x80
	s_ashr_i32 s31, s30, 31
	s_lshl_b64 s[42:43], s[30:31], 12
	s_add_u32 s42, s39, s42
	s_addc_u32 s43, s40, s43
	s_add_u32 s34, s34, 0x80000
	s_mov_b32 m0, s10
	s_nop 0
	global_load_lds_dwordx4 v230, s[42:43]
	s_addc_u32 s35, s35, 0
	s_mov_b32 m0, s11
	s_nop 0
	global_load_lds_dwordx4 v231, s[42:43]
	s_add_u32 s42, s37, s34
	s_addc_u32 s43, s38, s35
	s_mov_b32 m0, s6
	s_nop 0
	global_load_lds_dwordx4 v230, s[42:43]
	s_nop 0
	s_mov_b32 m0, s7
	s_nop 0
	global_load_lds_dwordx4 v231, s[42:43]
	s_and_saveexec_b64 s[86:87], s[58:59]
	s_cbranch_execz .LBB0_129
	s_barrier

; #define STAGE(P, BASE, br, kt) do { const u16* _gb = (BASE) + (long)(br)*K + (long)(kt)*BK; \
;     unsigned _ld = lds0 + (unsigned)((char*)(P) - (char*)shm) + wv * 1024u; \
;     glds_s(_gb, voff0, _ld); glds_s(_gb, voff1, _ld + 8192u); } while (0)
; #define WAIT_V(n) asm volatile("s_waitcnt vmcnt(" #n ")" ::: "memory")
; #define BAR __builtin_amdgcn_s_barrier()
;     ...
;     f32x4 acc[2][2][4][2] = {};
;     bf16x8 At[4][2], B0[2][2], B1[2][2];
;     if (!staged) {
;       STAGE(SB(0, 0), ActK, bcol, 0); STAGE(SA(0, 0), WtK, brow, 0);
;       STAGE(SB(0, 1), ActK, bcol + HALF, 0); STAGE(SA(0, 1), WtK, brow + HALF, 0);
;       if (wr == 1) BAR;
;       WAIT_V(4); BAR;
;     } else {
;       if (wr == 1) BAR;
;       WAIT_V(0); BAR;
;     }
;     STAGE(SB(1, 0), ActK, bcol, 1); STAGE(SA(1, 0), WtK, brow, 1); STAGE(SB(1, 1), ActK, bcol + HALF, 1);
;     WAIT_V(6); BAR;
.LBB0_134:
	s_cmpk_gt_i32 s23, 0x3ff
	s_cselect_b64 s[30:31], -1, 0
	s_cmpk_lt_i32 s23, 0x400
	s_cselect_b32 s0, 32, 16
	s_lshl_b64 s[42:43], s[90:91], 1
	s_add_u32 s13, s39, s42
	s_addc_u32 s21, s40, s43
	s_add_u32 s42, s13, 0x80
	s_addc_u32 s43, s21, 0
	s_mov_b32 m0, s8
	s_nop 0
	global_load_lds_dwordx4 v230, s[42:43]
	v_mov_b32_e32 v2, 0
	s_mov_b32 m0, s9
	s_nop 0
	global_load_lds_dwordx4 v231, s[42:43]
	s_lshl_b64 s[42:43], s[88:89], 1
	s_add_u32 s25, s37, s42
	s_addc_u32 s36, s38, s43
	s_add_u32 s42, s25, 0x80
	s_addc_u32 s43, s36, 0
	s_mov_b32 m0, s92
	s_nop 0
	global_load_lds_dwordx4 v230, s[42:43]
	v_mov_b32_e32 v3, v2
	s_mov_b32 m0, s93
	s_nop 0
	global_load_lds_dwordx4 v231, s[42:43]
	s_lshl_b64 s[42:43], s[86:87], 1
	s_add_u32 s39, s39, s42
	s_addc_u32 s40, s40, s43
	s_add_u32 s42, s39, 0x80
	s_addc_u32 s43, s40, 0
	s_mov_b32 m0, s14
	s_nop 0
	global_load_lds_dwordx4 v230, s[42:43]
	v_mov_b32_e32 v4, v2
	s_mov_b32 m0, s15
	s_nop 0
	global_load_lds_dwordx4 v231, s[42:43]
	s_add_i32 s41, s0, -2
	s_add_u32 s37, s37, s34
	s_addc_u32 s38, s38, s35
	s_mov_b32 s42, 0
	s_mov_b64 s[34:35], 0
	v_mov_b32_e32 v5, v2
	v_mov_b32_e32 v6, v2
	v_mov_b32_e32 v7, v2
	v_mov_b32_e32 v8, v2
	v_mov_b32_e32 v9, v2
	v_mov_b32_e32 v10, v2
	v_mov_b32_e32 v11, v2
	v_mov_b32_e32 v12, v2
	v_mov_b32_e32 v13, v2
	v_mov_b32_e32 v14, v2
	v_mov_b32_e32 v15, v2
	v_mov_b32_e32 v16, v2
	v_mov_b32_e32 v17, v2
	v_mov_b32_e32 v18, v2
	v_mov_b32_e32 v19, v2
	v_mov_b32_e32 v20, v2
	v_mov_b32_e32 v21, v2
	v_mov_b32_e32 v22, v2
	v_mov_b32_e32 v23, v2
	v_mov_b32_e32 v24, v2
	v_mov_b32_e32 v25, v2
	v_mov_b32_e32 v26, v2
	v_mov_b32_e32 v27, v2
	v_mov_b32_e32 v28, v2
	v_mov_b32_e32 v29, v2
	v_mov_b32_e32 v30, v2
	v_mov_b32_e32 v31, v2
	v_mov_b32_e32 v32, v2
	v_mov_b32_e32 v33, v2
	v_mov_b32_e32 v34, v2
	v_mov_b32_e32 v35, v2
	v_mov_b32_e32 v36, v2
	v_mov_b32_e32 v37, v2
	v_mov_b32_e32 v38, v2
	v_mov_b32_e32 v39, v2
	v_mov_b32_e32 v40, v2
	v_mov_b32_e32 v41, v2
	v_mov_b32_e32 v42, v2
	v_mov_b32_e32 v43, v2
	v_mov_b32_e32 v44, v2
	v_mov_b32_e32 v45, v2
	v_mov_b32_e32 v46, v2
	v_mov_b32_e32 v47, v2
	v_mov_b32_e32 v48, v2
	v_mov_b32_e32 v49, v2
	v_mov_b32_e32 v54, v2
	v_mov_b32_e32 v55, v2
	v_mov_b32_e32 v56, v2
	v_mov_b32_e32 v57, v2
	v_mov_b32_e32 v66, v2
	v_mov_b32_e32 v67, v2
	v_mov_b32_e32 v68, v2
	v_mov_b32_e32 v69, v2
	v_mov_b32_e32 v78, v2
	v_mov_b32_e32 v79, v2
	v_mov_b32_e32 v80, v2
	v_mov_b32_e32 v81, v2
	v_mov_b32_e32 v86, v2
	v_mov_b32_e32 v87, v2
	v_mov_b32_e32 v88, v2
	v_mov_b32_e32 v89, v2
	v_mov_b32_e32 v98, v2
	v_mov_b32_e32 v99, v2
	v_mov_b32_e32 v100, v2
	v_mov_b32_e32 v101, v2
	v_mov_b32_e32 v102, v2
	v_mov_b32_e32 v103, v2
	v_mov_b32_e32 v104, v2
	v_mov_b32_e32 v105, v2
	v_mov_b32_e32 v106, v2
	v_mov_b32_e32 v107, v2
	v_mov_b32_e32 v108, v2
	v_mov_b32_e32 v109, v2
	v_mov_b32_e32 v110, v2
	v_mov_b32_e32 v111, v2
	v_mov_b32_e32 v112, v2
	v_mov_b32_e32 v113, v2
	v_mov_b32_e32 v114, v2
	v_mov_b32_e32 v115, v2
	v_mov_b32_e32 v116, v2
	v_mov_b32_e32 v117, v2
	v_mov_b32_e32 v118, v2
	v_mov_b32_e32 v119, v2
	v_mov_b32_e32 v120, v2
	v_mov_b32_e32 v121, v2
	v_mov_b32_e32 v122, v2
	v_mov_b32_e32 v123, v2
	v_mov_b32_e32 v124, v2
	v_mov_b32_e32 v125, v2
	v_mov_b32_e32 v126, v2
	v_mov_b32_e32 v127, v2
	v_mov_b32_e32 v128, v2
	v_mov_b32_e32 v129, v2
	v_mov_b32_e32 v50, v2
	v_mov_b32_e32 v51, v2
	v_mov_b32_e32 v52, v2
	v_mov_b32_e32 v53, v2
	v_mov_b32_e32 v58, v2
	v_mov_b32_e32 v59, v2
	v_mov_b32_e32 v60, v2
	v_mov_b32_e32 v61, v2
	v_mov_b32_e32 v62, v2
	v_mov_b32_e32 v63, v2
	v_mov_b32_e32 v64, v2
	v_mov_b32_e32 v65, v2
	v_mov_b32_e32 v70, v2
	v_mov_b32_e32 v71, v2
	v_mov_b32_e32 v72, v2
	v_mov_b32_e32 v73, v2
	v_mov_b32_e32 v74, v2
	v_mov_b32_e32 v75, v2
	v_mov_b32_e32 v76, v2
	v_mov_b32_e32 v77, v2
	v_mov_b32_e32 v82, v2
	v_mov_b32_e32 v83, v2
	v_mov_b32_e32 v84, v2
	v_mov_b32_e32 v85, v2
	v_mov_b32_e32 v90, v2
	v_mov_b32_e32 v91, v2
	v_mov_b32_e32 v92, v2
	v_mov_b32_e32 v93, v2
	v_mov_b32_e32 v94, v2
	v_mov_b32_e32 v95, v2
	v_mov_b32_e32 v96, v2
	v_mov_b32_e32 v97, v2
	s_waitcnt vmcnt(6)
	s_barrier

; #define STAGE(P, BASE, br, kt) do { const u16* _gb = (BASE) + (long)(br)*K + (long)(kt)*BK; \
;     unsigned _ld = lds0 + (unsigned)((char*)(P) - (char*)shm) + wv * 1024u; \
;     glds_s(_gb, voff0, _ld); glds_s(_gb, voff1, _ld + 8192u); } while (0)
; #define LDA(dst, b, h) for (int m = 0; m < 4; ++m) for (int k = 0; k < 2; ++k) \
;     dst[m][k] = *reinterpret_cast<const bf16x8*>((char*)SA(b, h) + lds_byte(wr * 64 + m * 16 + fr, k * 32 + fq * 8))
; #define LDB(dst, b, h) for (int n = 0; n < 2; ++n) for (int k = 0; k < 2; ++k) \
;     dst[n][k] = *reinterpret_cast<const bf16x8*>((char*)SB(b, h) + lds_byte(wc * 32 + n * 16 + fr, k * 32 + fq * 8))
; #define WAIT_V(n) asm volatile("s_waitcnt vmcnt(" #n ")" ::: "memory")
; #define WAIT_L(n) asm volatile("s_waitcnt lgkmcnt(" #n ")" ::: "memory")
; #define BAR __builtin_amdgcn_s_barrier()
;     ...
;     { LDB(B0, 1, 0); LDA(At, 1, 0); WAIT_V(2); BAR; WAIT_L(0); MMA(0, 0, At, B0); BAR;
;       LDB(B1, 1, 1);
;       if (has_next) { STAGE(SB(0, 0), ActN, nbcol, 0); STAGE(SA(0, 0), WtN, nbrow, 0); WAIT_V(4); } else { WAIT_V(0); }
;       BAR; WAIT_L(0); MMA(0, 1, At, B1); BAR;
;       LDA(At, 1, 1);
;       if (has_next) { STAGE(SB(0, 1), ActN, nbcol + HALF, 0); STAGE(SA(0, 1), WtN, nbrow + HALF, 0); }
;       BAR; WAIT_L(0); MMA(1, 0, At, B0); MMA(1, 1, At, B1); BAR; }
.LBB0_138:
	s_andn2_b64 vcc, exec, s[34:35]
	s_mov_b32 s46, 0x800000
	s_mov_b32 s42, s62
	s_cbranch_vccnz .LBB0_140
	s_ashr_i32 s25, s24, 31
	s_lshl_b64 s[34:35], s[24:25], 12
	s_add_u32 s34, s36, s34
	s_addc_u32 s35, s39, s35
	s_mov_b32 m0, s94
	s_nop 0
	global_load_lds_dwordx4 v230, s[34:35]
	s_ashr_i32 s43, s42, 31
	s_mov_b32 m0, s16
	s_nop 0
	global_load_lds_dwordx4 v231, s[34:35]
	s_lshl_b64 s[34:35], s[42:43], 12
	s_add_u32 s34, s13, s34
	s_addc_u32 s35, s21, s35
	s_mov_b32 m0, s95
	s_nop 0
	global_load_lds_dwordx4 v230, s[34:35]
	s_nop 0
	s_mov_b32 m0, s17
	s_nop 0
	global_load_lds_dwordx4 v231, s[34:35]
	s_waitcnt vmcnt(4)
.LBB0_140:
	s_barrier
	s_waitcnt lgkmcnt(0)
	s_setprio 1
	s_waitcnt lgkmcnt(3)
	v_mfma_f32_16x16x32_bf16 v[54:57], v[26:29], v[186:189], v[54:57]
	s_waitcnt lgkmcnt(1)
	v_mfma_f32_16x16x32_bf16 v[26:29], v[26:29], v[190:193], v[98:101]
	v_mfma_f32_16x16x32_bf16 v[98:101], v[30:33], v[186:189], v[102:105]
	v_mfma_f32_16x16x32_bf16 v[102:105], v[30:33], v[190:193], v[106:109]
	v_mfma_f32_16x16x32_bf16 v[106:109], v[58:61], v[186:189], v[114:117]
	v_mfma_f32_16x16x32_bf16 v[114:117], v[58:61], v[190:193], v[174:177]
	v_mfma_f32_16x16x32_bf16 v[174:177], v[62:65], v[186:189], v[178:181]
	v_mfma_f32_16x16x32_bf16 v[178:181], v[62:65], v[190:193], v[182:185]
	v_mfma_f32_16x16x32_bf16 v[62:65], v[18:21], v[166:169], v[54:57]
	s_waitcnt lgkmcnt(0)
	v_mfma_f32_16x16x32_bf16 v[30:33], v[18:21], v[170:173], v[26:29]
	v_mfma_f32_16x16x32_bf16 v[58:61], v[22:25], v[166:169], v[98:101]
	v_mfma_f32_16x16x32_bf16 v[26:29], v[22:25], v[170:173], v[102:105]
	v_mfma_f32_16x16x32_bf16 v[54:57], v[50:53], v[166:169], v[106:109]
	v_mfma_f32_16x16x32_bf16 v[22:25], v[50:53], v[170:173], v[114:117]
	v_mfma_f32_16x16x32_bf16 v[50:53], v[82:85], v[166:169], v[174:177]
	v_mfma_f32_16x16x32_bf16 v[18:21], v[82:85], v[170:173], v[178:181]
	s_setprio 0
	s_barrier
	ds_read_b128 v[198:201], v234 offset:49152
	ds_read_b128 v[174:177], v234 offset:50176
	ds_read_b128 v[202:205], v235 offset:49152
	ds_read_b128 v[178:181], v235 offset:50176
	ds_read_b128 v[206:209], v236 offset:49152
	ds_read_b128 v[182:185], v236 offset:50176
	ds_read_b128 v[210:213], v237 offset:49152
	ds_read_b128 v[194:197], v237 offset:50176
	s_andn2_b64 vcc, exec, s[26:27]
	s_cbranch_vccnz .LBB0_142
	s_ashr_i32 s25, s24, 31
	s_lshl_b64 s[26:27], s[24:25], 12
	s_add_u32 s0, s36, s26
	s_addc_u32 s25, s39, s27
	s_add_u32 s26, s0, 0x80000
	s_addc_u32 s27, s25, 0
	s_mov_b32 m0, s10
	s_nop 0
	global_load_lds_dwordx4 v230, s[26:27]
	s_ashr_i32 s43, s42, 31
	s_mov_b32 m0, s11
	s_nop 0
	global_load_lds_dwordx4 v231, s[26:27]
	s_lshl_b64 s[26:27], s[42:43], 12
	s_add_u32 s0, s13, s26
	s_addc_u32 s13, s21, s27
	s_add_u32 s26, s0, 0x80000
	s_addc_u32 s27, s13, 0
	s_mov_b32 m0, s6
	s_nop 0
	global_load_lds_dwordx4 v230, s[26:27]
	s_nop 0
	s_mov_b32 m0, s7
	s_nop 0
	global_load_lds_dwordx4 v231, s[26:27]

; #define STAGE(P, BASE, br, kt) do { const u16* _gb = (BASE) + (long)(br)*K + (long)(kt)*BK; \
;     unsigned _ld = lds0 + (unsigned)((char*)(P) - (char*)shm) + wv * 1024u; \
;     glds_s(_gb, voff0, _ld); glds_s(_gb, voff1, _ld + 8192u); } while (0)
; #define WAIT_V(n) asm volatile("s_waitcnt vmcnt(" #n ")" ::: "memory")
; #define BAR __builtin_amdgcn_s_barrier()
;     ...
;     const bool is_split = v >= nwg_reg;
;     const int nt = (is_split ? kchunk : K) / BK;
;     const u16* ActK = Act + koff; const u16* WtK = Wt + koff;
;     const u16* ActN = Act + nkoff; const u16* WtN = Wt + nkoff;
;     f32x4 acc[2][2][4][2] = {};
;     bf16x8 At[4][2], B0[2][2], B1[2][2];
;     if (!staged) {
;       STAGE(SB(0, 0), ActK, bcol, 0); STAGE(SA(0, 0), WtK, brow, 0);
;       STAGE(SB(0, 1), ActK, bcol + HALF, 0); STAGE(SA(0, 1), WtK, brow + HALF, 0);
;       if (wr == 1) BAR;
;       WAIT_V(4); BAR;
.LBB0_451:
	v_readlane_b32 s44, v255, 5
	s_xor_b64 s[30:31], s[30:31], -1
	s_lshl_b64 s[34:35], s[0:1], 1
	v_readlane_b32 s48, v255, 9
	v_readlane_b32 s49, v255, 10
	s_add_u32 s42, s48, s34
	v_readlane_b32 s45, v255, 6
	s_addc_u32 s43, s49, s35
	v_readlane_b32 s46, v255, 7
	s_add_u32 s45, s90, s34
	s_addc_u32 s46, s91, s35
	s_andn2_b64 vcc, exec, s[30:31]
	s_mov_b64 s[30:31], -1
	v_readlane_b32 s47, v255, 8
	v_readlane_b32 s50, v255, 11
	v_readlane_b32 s51, v255, 12
	v_readlane_b32 s52, v255, 13
	v_readlane_b32 s53, v255, 14
	v_readlane_b32 s54, v255, 15
	v_readlane_b32 s55, v255, 16
	v_readlane_b32 s56, v255, 17
	v_readlane_b32 s57, v255, 18
	v_readlane_b32 s58, v255, 19
	v_readlane_b32 s59, v255, 20
	s_cbranch_vccnz .LBB0_455
	s_ashr_i32 s13, s12, 31
	s_lshl_b64 s[30:31], s[12:13], 13
	s_add_u32 s30, s42, s30
	s_addc_u32 s31, s43, s31
	s_ashr_i32 s27, s26, 31
	s_mov_b32 m0, s92
	s_nop 0
	global_load_lds_dwordx4 v230, s[30:31]
	s_lshl_b64 s[34:35], s[26:27], 13
	s_mov_b32 m0, s94
	s_nop 0
	global_load_lds_dwordx4 v231, s[30:31]
	s_add_u32 s30, s45, s34
	s_addc_u32 s31, s46, s35
	s_mov_b32 m0, s93
	s_nop 0
	global_load_lds_dwordx4 v230, s[30:31]
	s_nop 0
	s_mov_b32 m0, s95
	s_nop 0
	global_load_lds_dwordx4 v231, s[30:31]
	s_add_i32 s30, s12, 0x80
	s_ashr_i32 s31, s30, 31
	s_lshl_b64 s[38:39], s[30:31], 13
	s_add_u32 s38, s42, s38
	s_addc_u32 s39, s43, s39
	s_add_u32 s34, s34, 0x100000
	s_mov_b32 m0, s97
	s_nop 0
	global_load_lds_dwordx4 v230, s[38:39]
	s_addc_u32 s35, s35, 0
	s_mov_b32 m0, s16
	s_nop 0
	global_load_lds_dwordx4 v231, s[38:39]
	s_add_u32 s38, s45, s34
	s_addc_u32 s39, s46, s35
	s_mov_b32 m0, s17
	s_nop 0
	global_load_lds_dwordx4 v230, s[38:39]
	s_nop 0
	s_mov_b32 m0, s10
	s_nop 0
	global_load_lds_dwordx4 v231, s[38:39]
	s_and_saveexec_b64 s[38:39], s[66:67]
	s_cbranch_execz .LBB0_454
	s_barrier

; #define STAGE(P, BASE, br, kt) do { const u16* _gb = (BASE) + (long)(br)*K + (long)(kt)*BK; \
;     unsigned _ld = lds0 + (unsigned)((char*)(P) - (char*)shm) + wv * 1024u; \
;     glds_s(_gb, voff0, _ld); glds_s(_gb, voff1, _ld + 8192u); } while (0)
; #define LDA(dst, b, h) for (int m = 0; m < 4; ++m) for (int k = 0; k < 2; ++k) \
;     dst[m][k] = *reinterpret_cast<const bf16x8*>((char*)SA(b, h) + lds_byte(wr * 64 + m * 16 + fr, k * 32 + fq * 8))
; #define LDB(dst, b, h) for (int n = 0; n < 2; ++n) for (int k = 0; k < 2; ++k) \
;     dst[n][k] = *reinterpret_cast<const bf16x8*>((char*)SB(b, h) + lds_byte(wc * 32 + n * 16 + fr, k * 32 + fq * 8))
; #define WAIT_V(n) asm volatile("s_waitcnt vmcnt(" #n ")" ::: "memory")
; #define WAIT_L(n) asm volatile("s_waitcnt lgkmcnt(" #n ")" ::: "memory")
; #define BAR __builtin_amdgcn_s_barrier()
; #define SCHED __builtin_amdgcn_sched_barrier(0)
;     ...
;     f32x4 acc[2][2][4][2] = {};
;     bf16x8 At[4][2], B0[2][2], B1[2][2];
;     if (!staged) {
;       STAGE(SB(0, 0), ActK, bcol, 0); STAGE(SA(0, 0), WtK, brow, 0);
;       STAGE(SB(0, 1), ActK, bcol + HALF, 0); STAGE(SA(0, 1), WtK, brow + HALF, 0);
;       if (wr == 1) BAR;
;       WAIT_V(4); BAR;
;     } else {
;       if (wr == 1) BAR;
;       WAIT_V(0); BAR;
;     }
;     STAGE(SB(1, 0), ActK, bcol, 1); STAGE(SA(1, 0), WtK, brow, 1); STAGE(SB(1, 1), ActK, bcol + HALF, 1);
;     WAIT_V(6); BAR;
;     for (int t = 0; t < nt - 2; t += 2) {
;       LDB(B0, 0, 0); SCHED; LDA(At, 0, 0); STAGE(SA(1, 1), WtK, brow + HALF, t + 1);
;       WAIT_L(8); BAR; WAIT_L(0); MMA(0, 0, At, B0); BAR; SCHED;
.LBB0_459:
	s_cmpk_gt_i32 s41, 0x3ff
	s_cselect_b64 s[30:31], -1, 0
	s_cmpk_lt_i32 s41, 0x400
	s_cselect_b32 s0, 64, 16
	s_lshl_b64 s[48:49], s[88:89], 1
	s_add_u32 s13, s42, s48
	s_addc_u32 s21, s43, s49
	s_add_u32 s48, s13, 0x80
	s_addc_u32 s49, s21, 0
	s_mov_b32 m0, s11
	s_nop 0
	global_load_lds_dwordx4 v230, s[48:49]
	v_mov_b32_e32 v2, 0
	s_mov_b32 m0, s6
	s_nop 0
	global_load_lds_dwordx4 v231, s[48:49]
	s_lshl_b64 s[48:49], s[86:87], 1
	s_add_u32 s23, s45, s48
	s_addc_u32 s25, s46, s49
	s_add_u32 s48, s23, 0x80
	s_addc_u32 s49, s25, 0
	s_lshl_b64 s[38:39], s[38:39], 1
	s_add_u32 s42, s42, s38
	s_mov_b32 m0, s7
	s_nop 0
	global_load_lds_dwordx4 v230, s[48:49]
	s_addc_u32 s43, s43, s39
	s_mov_b32 m0, s8
	s_nop 0
	global_load_lds_dwordx4 v231, s[48:49]
	s_add_u32 s38, s42, 0x80
	s_addc_u32 s39, s43, 0
	s_mov_b32 m0, s9
	s_nop 0
	global_load_lds_dwordx4 v230, s[38:39]
	v_mov_b32_e32 v3, v2
	s_mov_b32 m0, s96
	s_nop 0
	global_load_lds_dwordx4 v231, s[38:39]
	s_add_i32 s44, s0, -2
	s_add_u32 s38, s45, s34
	s_addc_u32 s39, s46, s35
	s_mov_b32 s45, 0
	s_mov_b64 s[34:35], 0
	v_mov_b32_e32 v4, v2
	v_mov_b32_e32 v5, v2
	v_mov_b32_e32 v6, v2
	v_mov_b32_e32 v7, v2
	v_mov_b32_e32 v8, v2
	v_mov_b32_e32 v9, v2
	v_mov_b32_e32 v10, v2
	v_mov_b32_e32 v11, v2
	v_mov_b32_e32 v12, v2
	v_mov_b32_e32 v13, v2
	v_mov_b32_e32 v14, v2
	v_mov_b32_e32 v15, v2
	v_mov_b32_e32 v16, v2
	v_mov_b32_e32 v17, v2
	v_mov_b32_e32 v18, v2
	v_mov_b32_e32 v19, v2
	v_mov_b32_e32 v20, v2
	v_mov_b32_e32 v21, v2
	v_mov_b32_e32 v22, v2
	v_mov_b32_e32 v23, v2
	v_mov_b32_e32 v24, v2
	v_mov_b32_e32 v25, v2
	v_mov_b32_e32 v26, v2
	v_mov_b32_e32 v27, v2
	v_mov_b32_e32 v28, v2
	v_mov_b32_e32 v29, v2
	v_mov_b32_e32 v30, v2
	v_mov_b32_e32 v31, v2
	v_mov_b32_e32 v32, v2
	v_mov_b32_e32 v33, v2
	v_mov_b32_e32 v34, v2
	v_mov_b32_e32 v35, v2
	v_mov_b32_e32 v36, v2
	v_mov_b32_e32 v37, v2
	v_mov_b32_e32 v38, v2
	v_mov_b32_e32 v39, v2
	v_mov_b32_e32 v40, v2
	v_mov_b32_e32 v41, v2
	v_mov_b32_e32 v42, v2
	v_mov_b32_e32 v43, v2
	v_mov_b32_e32 v44, v2
	v_mov_b32_e32 v45, v2
	v_mov_b32_e32 v46, v2
	v_mov_b32_e32 v47, v2
	v_mov_b32_e32 v48, v2
	v_mov_b32_e32 v49, v2
	v_mov_b32_e32 v54, v2
	v_mov_b32_e32 v55, v2
	v_mov_b32_e32 v56, v2
	v_mov_b32_e32 v57, v2
	v_mov_b32_e32 v66, v2
	v_mov_b32_e32 v67, v2
	v_mov_b32_e32 v68, v2
	v_mov_b32_e32 v69, v2
	v_mov_b32_e32 v78, v2
	v_mov_b32_e32 v79, v2
	v_mov_b32_e32 v80, v2
	v_mov_b32_e32 v81, v2
	v_mov_b32_e32 v86, v2
	v_mov_b32_e32 v87, v2
	v_mov_b32_e32 v88, v2
	v_mov_b32_e32 v89, v2
	v_mov_b32_e32 v98, v2
	v_mov_b32_e32 v99, v2
	v_mov_b32_e32 v100, v2
	v_mov_b32_e32 v101, v2
	v_mov_b32_e32 v102, v2
	v_mov_b32_e32 v103, v2
	v_mov_b32_e32 v104, v2
	v_mov_b32_e32 v105, v2
	v_mov_b32_e32 v106, v2
	v_mov_b32_e32 v107, v2
	v_mov_b32_e32 v108, v2
	v_mov_b32_e32 v109, v2
	v_mov_b32_e32 v110, v2
	v_mov_b32_e32 v111, v2
	v_mov_b32_e32 v112, v2
	v_mov_b32_e32 v113, v2
	v_mov_b32_e32 v114, v2
	v_mov_b32_e32 v115, v2
	v_mov_b32_e32 v116, v2
	v_mov_b32_e32 v117, v2
	v_mov_b32_e32 v118, v2
	v_mov_b32_e32 v119, v2
	v_mov_b32_e32 v120, v2
	v_mov_b32_e32 v121, v2
	v_mov_b32_e32 v122, v2
	v_mov_b32_e32 v123, v2
	v_mov_b32_e32 v124, v2
	v_mov_b32_e32 v125, v2
	v_mov_b32_e32 v126, v2
	v_mov_b32_e32 v127, v2
	v_mov_b32_e32 v128, v2
	v_mov_b32_e32 v129, v2
	v_mov_b32_e32 v50, v2
	v_mov_b32_e32 v51, v2
	v_mov_b32_e32 v52, v2
	v_mov_b32_e32 v53, v2
	v_mov_b32_e32 v58, v2
	v_mov_b32_e32 v59, v2
	v_mov_b32_e32 v60, v2
	v_mov_b32_e32 v61, v2
	v_mov_b32_e32 v62, v2
	v_mov_b32_e32 v63, v2
	v_mov_b32_e32 v64, v2
	v_mov_b32_e32 v65, v2
	v_mov_b32_e32 v70, v2
	v_mov_b32_e32 v71, v2
	v_mov_b32_e32 v72, v2
	v_mov_b32_e32 v73, v2
	v_mov_b32_e32 v74, v2
	v_mov_b32_e32 v75, v2
	v_mov_b32_e32 v76, v2
	v_mov_b32_e32 v77, v2
	v_mov_b32_e32 v82, v2
	v_mov_b32_e32 v83, v2
	v_mov_b32_e32 v84, v2
	v_mov_b32_e32 v85, v2
	v_mov_b32_e32 v90, v2
	v_mov_b32_e32 v91, v2
	v_mov_b32_e32 v92, v2
	v_mov_b32_e32 v93, v2
	v_mov_b32_e32 v94, v2
	v_mov_b32_e32 v95, v2
	v_mov_b32_e32 v96, v2
	v_mov_b32_e32 v97, v2
	s_waitcnt vmcnt(6)
	s_barrier
.LBB0_460:
	ds_read_b128 v[130:133], v233
	ds_read_b128 v[134:137], v233 offset:1024
	ds_read_b128 v[138:141], v233 offset:2048
	ds_read_b128 v[142:145], v233 offset:3072
	ds_read_b128 v[146:149], v234
	ds_read_b128 v[150:153], v234 offset:1024
	ds_read_b128 v[154:157], v235
	ds_read_b128 v[158:161], v235 offset:1024
	ds_read_b128 v[162:165], v236
	ds_read_b128 v[166:169], v236 offset:1024
	ds_read_b128 v[170:173], v237
	ds_read_b128 v[174:177], v237 offset:1024
	s_add_u32 s48, s38, s34
	s_addc_u32 s49, s39, s35
	s_add_u32 s46, s48, 0x80
	s_addc_u32 s47, s49, 0
	s_mov_b32 m0, s36
	s_nop 0
	global_load_lds_dwordx4 v230, s[46:47]
	s_nop 0
	s_mov_b32 m0, s37
	s_nop 0
	global_load_lds_dwordx4 v231, s[46:47]
	s_waitcnt lgkmcnt(8)
	s_barrier
	s_waitcnt lgkmcnt(0)
	s_setprio 1
	s_waitcnt lgkmcnt(7)
	v_mfma_f32_16x16x32_bf16 v[126:129], v[146:149], v[130:133], v[126:129]
	v_mfma_f32_16x16x32_bf16 v[122:125], v[146:149], v[138:141], v[122:125]
	s_waitcnt lgkmcnt(5)
	v_mfma_f32_16x16x32_bf16 v[118:121], v[154:157], v[130:133], v[118:121]
	v_mfma_f32_16x16x32_bf16 v[114:117], v[154:157], v[138:141], v[114:117]
	s_waitcnt lgkmcnt(3)
	v_mfma_f32_16x16x32_bf16 v[110:113], v[162:165], v[130:133], v[110:113]
	v_mfma_f32_16x16x32_bf16 v[106:109], v[162:165], v[138:141], v[106:109]
	s_waitcnt lgkmcnt(1)
	v_mfma_f32_16x16x32_bf16 v[102:105], v[170:173], v[130:133], v[102:105]
	v_mfma_f32_16x16x32_bf16 v[98:101], v[170:173], v[138:141], v[98:101]
	v_mfma_f32_16x16x32_bf16 v[126:129], v[150:153], v[134:137], v[126:129]
	v_mfma_f32_16x16x32_bf16 v[122:125], v[150:153], v[142:145], v[122:125]
	v_mfma_f32_16x16x32_bf16 v[118:121], v[158:161], v[134:137], v[118:121]
	v_mfma_f32_16x16x32_bf16 v[114:117], v[158:161], v[142:145], v[114:117]
	v_mfma_f32_16x16x32_bf16 v[110:113], v[166:169], v[134:137], v[110:113]
	v_mfma_f32_16x16x32_bf16 v[106:109], v[166:169], v[142:145], v[106:109]
	s_waitcnt lgkmcnt(0)
	v_mfma_f32_16x16x32_bf16 v[102:105], v[174:177], v[134:137], v[102:105]
	v_mfma_f32_16x16x32_bf16 v[98:101], v[174:177], v[142:145], v[98:101]
	s_setprio 0
	s_barrier
; #define STAGE(P, BASE, br, kt) do { const u16* _gb = (BASE) + (long)(br)*K + (long)(kt)*BK; \
;     unsigned _ld = lds0 + (unsigned)((char*)(P) - (char*)shm) + wv * 1024u; \
;     glds_s(_gb, voff0, _ld); glds_s(_gb, voff1, _ld + 8192u); } while (0)
; #define LDA(dst, b, h) for (int m = 0; m < 4; ++m) for (int k = 0; k < 2; ++k) \
;     dst[m][k] = *reinterpret_cast<const bf16x8*>((char*)SA(b, h) + lds_byte(wr * 64 + m * 16 + fr, k * 32 + fq * 8))
; #define LDB(dst, b, h) for (int n = 0; n < 2; ++n) for (int k = 0; k < 2; ++k) \
;     dst[n][k] = *reinterpret_cast<const bf16x8*>((char*)SB(b, h) + lds_byte(wc * 32 + n * 16 + fr, k * 32 + fq * 8))
; #define WAIT_V(n) asm volatile("s_waitcnt vmcnt(" #n ")" ::: "memory")
; #define WAIT_L(n) asm volatile("s_waitcnt lgkmcnt(" #n ")" ::: "memory")
; #define BAR __builtin_amdgcn_s_barrier()
; #define SCHED __builtin_amdgcn_sched_barrier(0)
;     ...
;       WAIT_L(8); BAR; WAIT_L(0); MMA(0, 0, At, B0); BAR; SCHED;
;       LDB(B1, 0, 1); STAGE(SB(0, 0), ActK, bcol, t + 2);
;       BAR; WAIT_L(0); MMA(0, 1, At, B1); BAR;
;       LDA(At, 0, 1); STAGE(SA(0, 0), WtK, brow, t + 2);
;       BAR; WAIT_L(0); MMA(1, 0, At, B0); BAR; SCHED;
;       STAGE(SB(0, 1), ActK, bcol + HALF, t + 2);
;       WAIT_V(6); BAR; MMA(1, 1, At, B1); BAR;
;       LDB(B0, 1, 0); SCHED; LDA(At, 1, 0); STAGE(SA(0, 1), WtK, brow + HALF, t + 2);
;       WAIT_L(8); BAR; WAIT_L(0); MMA(0, 0, At, B0); BAR; SCHED;
	s_add_i32 s45, s45, 2
	ds_read_b128 v[178:181], v238
	ds_read_b128 v[182:185], v238 offset:1024
	ds_read_b128 v[186:189], v238 offset:2048
	ds_read_b128 v[190:193], v238 offset:3072
	s_add_u32 s50, s13, s34
	s_addc_u32 s51, s21, s35
	s_add_u32 s46, s50, 0x100
	s_addc_u32 s47, s51, 0
	s_mov_b32 m0, s92
	s_nop 0
	global_load_lds_dwordx4 v230, s[46:47]
	s_nop 0
	s_mov_b32 m0, s94
	s_nop 0
	global_load_lds_dwordx4 v231, s[46:47]
	s_barrier
	s_waitcnt lgkmcnt(0)
	s_setprio 1
	s_waitcnt lgkmcnt(3)
	v_mfma_f32_16x16x32_bf16 v[86:89], v[146:149], v[178:181], v[86:89]
	s_waitcnt lgkmcnt(1)
	v_mfma_f32_16x16x32_bf16 v[78:81], v[146:149], v[186:189], v[78:81]
	v_mfma_f32_16x16x32_bf16 v[66:69], v[154:157], v[178:181], v[66:69]
	v_mfma_f32_16x16x32_bf16 v[54:57], v[154:157], v[186:189], v[54:57]
	v_mfma_f32_16x16x32_bf16 v[46:49], v[162:165], v[178:181], v[46:49]
	v_mfma_f32_16x16x32_bf16 v[42:45], v[162:165], v[186:189], v[42:45]
	v_mfma_f32_16x16x32_bf16 v[38:41], v[170:173], v[178:181], v[38:41]
	v_mfma_f32_16x16x32_bf16 v[34:37], v[170:173], v[186:189], v[34:37]
	v_mfma_f32_16x16x32_bf16 v[86:89], v[150:153], v[182:185], v[86:89]
	s_waitcnt lgkmcnt(0)
	v_mfma_f32_16x16x32_bf16 v[78:81], v[150:153], v[190:193], v[78:81]
	v_mfma_f32_16x16x32_bf16 v[66:69], v[158:161], v[182:185], v[66:69]
	v_mfma_f32_16x16x32_bf16 v[54:57], v[158:161], v[190:193], v[54:57]
	v_mfma_f32_16x16x32_bf16 v[46:49], v[166:169], v[182:185], v[46:49]
	v_mfma_f32_16x16x32_bf16 v[42:45], v[166:169], v[190:193], v[42:45]
	v_mfma_f32_16x16x32_bf16 v[38:41], v[174:177], v[182:185], v[38:41]
	v_mfma_f32_16x16x32_bf16 v[34:37], v[174:177], v[190:193], v[34:37]
	s_setprio 0
	s_barrier
	ds_read_b128 v[146:149], v234 offset:16384
	ds_read_b128 v[150:153], v234 offset:17408
	ds_read_b128 v[154:157], v235 offset:16384
	ds_read_b128 v[158:161], v235 offset:17408
	ds_read_b128 v[162:165], v236 offset:16384
	ds_read_b128 v[166:169], v236 offset:17408
	ds_read_b128 v[170:173], v237 offset:16384
	ds_read_b128 v[174:177], v237 offset:17408
	s_add_u32 s86, s23, s34
	s_addc_u32 s87, s25, s35
	s_add_u32 s46, s86, 0x100
	s_addc_u32 s47, s87, 0
	s_mov_b32 m0, s93
	s_nop 0
	global_load_lds_dwordx4 v230, s[46:47]
	s_nop 0
	s_mov_b32 m0, s95
	s_nop 0
	global_load_lds_dwordx4 v231, s[46:47]
	s_barrier
	s_waitcnt lgkmcnt(0)
	s_setprio 1
	s_waitcnt lgkmcnt(7)
	v_mfma_f32_16x16x32_bf16 v[30:33], v[146:149], v[130:133], v[30:33]
	v_mfma_f32_16x16x32_bf16 v[26:29], v[146:149], v[138:141], v[26:29]
	s_waitcnt lgkmcnt(5)
	v_mfma_f32_16x16x32_bf16 v[22:25], v[154:157], v[130:133], v[22:25]
	v_mfma_f32_16x16x32_bf16 v[18:21], v[154:157], v[138:141], v[18:21]
	s_waitcnt lgkmcnt(3)
	v_mfma_f32_16x16x32_bf16 v[14:17], v[162:165], v[130:133], v[14:17]
	v_mfma_f32_16x16x32_bf16 v[10:13], v[162:165], v[138:141], v[10:13]
	s_waitcnt lgkmcnt(1)
	v_mfma_f32_16x16x32_bf16 v[6:9], v[170:173], v[130:133], v[6:9]
	v_mfma_f32_16x16x32_bf16 v[2:5], v[170:173], v[138:141], v[2:5]
	v_mfma_f32_16x16x32_bf16 v[30:33], v[150:153], v[134:137], v[30:33]
	v_mfma_f32_16x16x32_bf16 v[26:29], v[150:153], v[142:145], v[26:29]
	v_mfma_f32_16x16x32_bf16 v[22:25], v[158:161], v[134:137], v[22:25]
	v_mfma_f32_16x16x32_bf16 v[18:21], v[158:161], v[142:145], v[18:21]
	v_mfma_f32_16x16x32_bf16 v[14:17], v[166:169], v[134:137], v[14:17]
	v_mfma_f32_16x16x32_bf16 v[10:13], v[166:169], v[142:145], v[10:13]
	s_waitcnt lgkmcnt(0)
	v_mfma_f32_16x16x32_bf16 v[6:9], v[174:177], v[134:137], v[6:9]
	v_mfma_f32_16x16x32_bf16 v[2:5], v[174:177], v[142:145], v[2:5]
	s_setprio 0
	s_barrier
	s_add_u32 s88, s42, s34
	s_addc_u32 s89, s43, s35
	s_add_u32 s46, s88, 0x100
	s_addc_u32 s47, s89, 0
	s_mov_b32 m0, s97
	s_nop 0
	global_load_lds_dwordx4 v230, s[46:47]
	s_nop 0
	s_mov_b32 m0, s16
	s_nop 0
	global_load_lds_dwordx4 v231, s[46:47]
	s_waitcnt vmcnt(6)
	s_barrier
	s_setprio 1
	v_mfma_f32_16x16x32_bf16 v[50:53], v[146:149], v[178:181], v[50:53]
	v_mfma_f32_16x16x32_bf16 v[58:61], v[146:149], v[186:189], v[58:61]
	v_mfma_f32_16x16x32_bf16 v[62:65], v[154:157], v[178:181], v[62:65]
	v_mfma_f32_16x16x32_bf16 v[70:73], v[154:157], v[186:189], v[70:73]
	v_mfma_f32_16x16x32_bf16 v[74:77], v[162:165], v[178:181], v[74:77]
	v_mfma_f32_16x16x32_bf16 v[82:85], v[162:165], v[186:189], v[82:85]
	v_mfma_f32_16x16x32_bf16 v[90:93], v[170:173], v[178:181], v[90:93]
	v_mfma_f32_16x16x32_bf16 v[94:97], v[170:173], v[186:189], v[94:97]
	v_mfma_f32_16x16x32_bf16 v[50:53], v[150:153], v[182:185], v[50:53]
	v_mfma_f32_16x16x32_bf16 v[58:61], v[150:153], v[190:193], v[58:61]
	v_mfma_f32_16x16x32_bf16 v[62:65], v[158:161], v[182:185], v[62:65]
	v_mfma_f32_16x16x32_bf16 v[70:73], v[158:161], v[190:193], v[70:73]
	v_mfma_f32_16x16x32_bf16 v[74:77], v[166:169], v[182:185], v[74:77]
	v_mfma_f32_16x16x32_bf16 v[82:85], v[166:169], v[190:193], v[82:85]
	v_mfma_f32_16x16x32_bf16 v[90:93], v[174:177], v[182:185], v[90:93]
	v_mfma_f32_16x16x32_bf16 v[94:97], v[174:177], v[190:193], v[94:97]
	s_setprio 0
	s_barrier
	ds_read_b128 v[130:133], v239
	ds_read_b128 v[134:137], v239 offset:1024
	ds_read_b128 v[138:141], v239 offset:2048
	ds_read_b128 v[142:145], v239 offset:3072
	ds_read_b128 v[146:149], v234 offset:32768
	ds_read_b128 v[150:153], v234 offset:33792
	ds_read_b128 v[154:157], v235 offset:32768
	ds_read_b128 v[158:161], v235 offset:33792
	ds_read_b128 v[162:165], v236 offset:32768
	ds_read_b128 v[166:169], v236 offset:33792
	ds_read_b128 v[170:173], v237 offset:32768
	ds_read_b128 v[174:177], v237 offset:33792
	s_add_u32 s46, s48, 0x100
	s_addc_u32 s47, s49, 0
	s_mov_b32 m0, s17
	s_nop 0
	global_load_lds_dwordx4 v230, s[46:47]
	s_nop 0
	s_mov_b32 m0, s10
	s_nop 0
	global_load_lds_dwordx4 v231, s[46:47]
	s_waitcnt lgkmcnt(8)
	s_barrier
; #define STAGE(P, BASE, br, kt) do { const u16* _gb = (BASE) + (long)(br)*K + (long)(kt)*BK; \
;     unsigned _ld = lds0 + (unsigned)((char*)(P) - (char*)shm) + wv * 1024u; \
;     glds_s(_gb, voff0, _ld); glds_s(_gb, voff1, _ld + 8192u); } while (0)
; #define LDA(dst, b, h) for (int m = 0; m < 4; ++m) for (int k = 0; k < 2; ++k) \
;     dst[m][k] = *reinterpret_cast<const bf16x8*>((char*)SA(b, h) + lds_byte(wr * 64 + m * 16 + fr, k * 32 + fq * 8))
; #define LDB(dst, b, h) for (int n = 0; n < 2; ++n) for (int k = 0; k < 2; ++k) \
;     dst[n][k] = *reinterpret_cast<const bf16x8*>((char*)SB(b, h) + lds_byte(wc * 32 + n * 16 + fr, k * 32 + fq * 8))
; #define WAIT_V(n) asm volatile("s_waitcnt vmcnt(" #n ")" ::: "memory")
; #define WAIT_L(n) asm volatile("s_waitcnt lgkmcnt(" #n ")" ::: "memory")
; #define BAR __builtin_amdgcn_s_barrier()
; #define SCHED __builtin_amdgcn_sched_barrier(0)
;     ...
;       WAIT_L(8); BAR; WAIT_L(0); MMA(0, 0, At, B0); BAR; SCHED;
;       LDB(B1, 1, 1); STAGE(SB(1, 0), ActK, bcol, t + 3);
;       BAR; WAIT_L(0); MMA(0, 1, At, B1); BAR;
;       LDA(At, 1, 1); STAGE(SA(1, 0), WtK, brow, t + 3);
;       BAR; WAIT_L(0); MMA(1, 0, At, B0); BAR; SCHED;
;       STAGE(SB(1, 1), ActK, bcol + HALF, t + 3);
;       WAIT_V(6); BAR; MMA(1, 1, At, B1); BAR;
;     }
	s_waitcnt lgkmcnt(0)
	s_setprio 1
	s_waitcnt lgkmcnt(7)
	v_mfma_f32_16x16x32_bf16 v[126:129], v[146:149], v[130:133], v[126:129]
	v_mfma_f32_16x16x32_bf16 v[122:125], v[146:149], v[138:141], v[122:125]
	s_waitcnt lgkmcnt(5)
	v_mfma_f32_16x16x32_bf16 v[118:121], v[154:157], v[130:133], v[118:121]
	v_mfma_f32_16x16x32_bf16 v[114:117], v[154:157], v[138:141], v[114:117]
	s_waitcnt lgkmcnt(3)
	v_mfma_f32_16x16x32_bf16 v[110:113], v[162:165], v[130:133], v[110:113]
	v_mfma_f32_16x16x32_bf16 v[106:109], v[162:165], v[138:141], v[106:109]
	s_waitcnt lgkmcnt(1)
	v_mfma_f32_16x16x32_bf16 v[102:105], v[170:173], v[130:133], v[102:105]
	v_mfma_f32_16x16x32_bf16 v[98:101], v[170:173], v[138:141], v[98:101]
	v_mfma_f32_16x16x32_bf16 v[126:129], v[150:153], v[134:137], v[126:129]
	v_mfma_f32_16x16x32_bf16 v[122:125], v[150:153], v[142:145], v[122:125]
	v_mfma_f32_16x16x32_bf16 v[118:121], v[158:161], v[134:137], v[118:121]
	v_mfma_f32_16x16x32_bf16 v[114:117], v[158:161], v[142:145], v[114:117]
	v_mfma_f32_16x16x32_bf16 v[110:113], v[166:169], v[134:137], v[110:113]
	v_mfma_f32_16x16x32_bf16 v[106:109], v[166:169], v[142:145], v[106:109]
	s_waitcnt lgkmcnt(0)
	v_mfma_f32_16x16x32_bf16 v[102:105], v[174:177], v[134:137], v[102:105]
	v_mfma_f32_16x16x32_bf16 v[98:101], v[174:177], v[142:145], v[98:101]
	s_setprio 0
	s_barrier
	ds_read_b128 v[178:181], v240
	ds_read_b128 v[182:185], v240 offset:1024
	ds_read_b128 v[186:189], v240 offset:2048
	ds_read_b128 v[190:193], v240 offset:3072
	s_add_u32 s46, s50, 0x180
	s_addc_u32 s47, s51, 0
	s_mov_b32 m0, s11
	s_nop 0
	global_load_lds_dwordx4 v230, s[46:47]
	s_nop 0
	s_mov_b32 m0, s6
	s_nop 0
	global_load_lds_dwordx4 v231, s[46:47]
	s_barrier
	s_waitcnt lgkmcnt(0)
	s_setprio 1
	s_waitcnt lgkmcnt(3)
	v_mfma_f32_16x16x32_bf16 v[86:89], v[146:149], v[178:181], v[86:89]
	s_waitcnt lgkmcnt(1)
	v_mfma_f32_16x16x32_bf16 v[78:81], v[146:149], v[186:189], v[78:81]
	v_mfma_f32_16x16x32_bf16 v[66:69], v[154:157], v[178:181], v[66:69]
	v_mfma_f32_16x16x32_bf16 v[54:57], v[154:157], v[186:189], v[54:57]
	v_mfma_f32_16x16x32_bf16 v[46:49], v[162:165], v[178:181], v[46:49]
	v_mfma_f32_16x16x32_bf16 v[42:45], v[162:165], v[186:189], v[42:45]
	v_mfma_f32_16x16x32_bf16 v[38:41], v[170:173], v[178:181], v[38:41]
	v_mfma_f32_16x16x32_bf16 v[34:37], v[170:173], v[186:189], v[34:37]
	v_mfma_f32_16x16x32_bf16 v[86:89], v[150:153], v[182:185], v[86:89]
	s_waitcnt lgkmcnt(0)
	v_mfma_f32_16x16x32_bf16 v[78:81], v[150:153], v[190:193], v[78:81]
	v_mfma_f32_16x16x32_bf16 v[66:69], v[158:161], v[182:185], v[66:69]
	v_mfma_f32_16x16x32_bf16 v[54:57], v[158:161], v[190:193], v[54:57]
	v_mfma_f32_16x16x32_bf16 v[46:49], v[166:169], v[182:185], v[46:49]
	v_mfma_f32_16x16x32_bf16 v[42:45], v[166:169], v[190:193], v[42:45]
	v_mfma_f32_16x16x32_bf16 v[38:41], v[174:177], v[182:185], v[38:41]
	v_mfma_f32_16x16x32_bf16 v[34:37], v[174:177], v[190:193], v[34:37]
	s_setprio 0
	s_barrier
	ds_read_b128 v[146:149], v234 offset:49152
	ds_read_b128 v[150:153], v234 offset:50176
	ds_read_b128 v[154:157], v235 offset:49152
	ds_read_b128 v[158:161], v235 offset:50176
	ds_read_b128 v[162:165], v236 offset:49152
	ds_read_b128 v[166:169], v236 offset:50176
	ds_read_b128 v[170:173], v237 offset:49152
	ds_read_b128 v[174:177], v237 offset:50176
	s_add_u32 s46, s86, 0x180
	s_addc_u32 s47, s87, 0
	s_mov_b32 m0, s7
	s_nop 0
	global_load_lds_dwordx4 v230, s[46:47]
	s_nop 0
	s_mov_b32 m0, s8
	s_nop 0
	global_load_lds_dwordx4 v231, s[46:47]
	s_barrier
	s_waitcnt lgkmcnt(0)
	s_setprio 1
	s_waitcnt lgkmcnt(7)
	v_mfma_f32_16x16x32_bf16 v[30:33], v[146:149], v[130:133], v[30:33]
	v_mfma_f32_16x16x32_bf16 v[26:29], v[146:149], v[138:141], v[26:29]
	s_waitcnt lgkmcnt(5)
	v_mfma_f32_16x16x32_bf16 v[22:25], v[154:157], v[130:133], v[22:25]
	v_mfma_f32_16x16x32_bf16 v[18:21], v[154:157], v[138:141], v[18:21]
	s_waitcnt lgkmcnt(3)
	v_mfma_f32_16x16x32_bf16 v[14:17], v[162:165], v[130:133], v[14:17]
	v_mfma_f32_16x16x32_bf16 v[10:13], v[162:165], v[138:141], v[10:13]
	s_waitcnt lgkmcnt(1)
	v_mfma_f32_16x16x32_bf16 v[6:9], v[170:173], v[130:133], v[6:9]
	v_mfma_f32_16x16x32_bf16 v[2:5], v[170:173], v[138:141], v[2:5]
	v_mfma_f32_16x16x32_bf16 v[30:33], v[150:153], v[134:137], v[30:33]
	v_mfma_f32_16x16x32_bf16 v[26:29], v[150:153], v[142:145], v[26:29]
	v_mfma_f32_16x16x32_bf16 v[22:25], v[158:161], v[134:137], v[22:25]
	v_mfma_f32_16x16x32_bf16 v[18:21], v[158:161], v[142:145], v[18:21]
	v_mfma_f32_16x16x32_bf16 v[14:17], v[166:169], v[134:137], v[14:17]
	v_mfma_f32_16x16x32_bf16 v[10:13], v[166:169], v[142:145], v[10:13]
	s_waitcnt lgkmcnt(0)
	v_mfma_f32_16x16x32_bf16 v[6:9], v[174:177], v[134:137], v[6:9]
	v_mfma_f32_16x16x32_bf16 v[2:5], v[174:177], v[142:145], v[2:5]
	s_setprio 0
	s_barrier
	s_add_u32 s46, s88, 0x180
	s_addc_u32 s47, s89, 0
	s_mov_b32 m0, s9
	s_nop 0
	global_load_lds_dwordx4 v230, s[46:47]
	s_nop 0
	s_mov_b32 m0, s96
	s_nop 0
	global_load_lds_dwordx4 v231, s[46:47]
	s_waitcnt vmcnt(6)
	s_barrier
	s_setprio 1
	v_mfma_f32_16x16x32_bf16 v[50:53], v[146:149], v[178:181], v[50:53]
	v_mfma_f32_16x16x32_bf16 v[58:61], v[146:149], v[186:189], v[58:61]
	v_mfma_f32_16x16x32_bf16 v[62:65], v[154:157], v[178:181], v[62:65]
	v_mfma_f32_16x16x32_bf16 v[70:73], v[154:157], v[186:189], v[70:73]
	v_mfma_f32_16x16x32_bf16 v[74:77], v[162:165], v[178:181], v[74:77]
	v_mfma_f32_16x16x32_bf16 v[82:85], v[162:165], v[186:189], v[82:85]
	v_mfma_f32_16x16x32_bf16 v[90:93], v[170:173], v[178:181], v[90:93]
	v_mfma_f32_16x16x32_bf16 v[94:97], v[170:173], v[186:189], v[94:97]
	v_mfma_f32_16x16x32_bf16 v[50:53], v[150:153], v[182:185], v[50:53]
	v_mfma_f32_16x16x32_bf16 v[58:61], v[150:153], v[190:193], v[58:61]
	v_mfma_f32_16x16x32_bf16 v[62:65], v[158:161], v[182:185], v[62:65]
	v_mfma_f32_16x16x32_bf16 v[70:73], v[158:161], v[190:193], v[70:73]
	v_mfma_f32_16x16x32_bf16 v[74:77], v[166:169], v[182:185], v[74:77]
	v_mfma_f32_16x16x32_bf16 v[82:85], v[166:169], v[190:193], v[82:85]
	v_mfma_f32_16x16x32_bf16 v[90:93], v[174:177], v[182:185], v[90:93]
	v_mfma_f32_16x16x32_bf16 v[94:97], v[174:177], v[190:193], v[94:97]
	s_setprio 0
	s_add_u32 s34, s34, 0x100
	s_addc_u32 s35, s35, 0
	s_cmp_ge_i32 s45, s44
	s_barrier
; #define STAGE(P, BASE, br, kt) do { const u16* _gb = (BASE) + (long)(br)*K + (long)(kt)*BK; \
;     unsigned _ld = lds0 + (unsigned)((char*)(P) - (char*)shm) + wv * 1024u; \
;     glds_s(_gb, voff0, _ld); glds_s(_gb, voff1, _ld + 8192u); } while (0)
; #define LDA(dst, b, h) for (int m = 0; m < 4; ++m) for (int k = 0; k < 2; ++k) \
;     dst[m][k] = *reinterpret_cast<const bf16x8*>((char*)SA(b, h) + lds_byte(wr * 64 + m * 16 + fr, k * 32 + fq * 8))
; #define LDB(dst, b, h) for (int n = 0; n < 2; ++n) for (int k = 0; k < 2; ++k) \
;     dst[n][k] = *reinterpret_cast<const bf16x8*>((char*)SB(b, h) + lds_byte(wc * 32 + n * 16 + fr, k * 32 + fq * 8))
; #define WAIT_V(n) asm volatile("s_waitcnt vmcnt(" #n ")" ::: "memory")
; #define WAIT_L(n) asm volatile("s_waitcnt lgkmcnt(" #n ")" ::: "memory")
; #define BAR __builtin_amdgcn_s_barrier()
;     ...
;     { LDB(B0, 0, 0); LDA(At, 0, 0); STAGE(SA(1, 1), WtK, brow + HALF, nt - 1);
;       BAR; WAIT_L(0); MMA(0, 0, At, B0); BAR;
;       LDB(B1, 0, 1); BAR; WAIT_L(0); MMA(0, 1, At, B1); BAR;
;       LDA(At, 0, 1); WAIT_V(4); BAR; WAIT_L(0); MMA(1, 0, At, B0); MMA(1, 1, At, B1); BAR; }
;     { LDB(B0, 1, 0); LDA(At, 1, 0); WAIT_V(2); BAR; WAIT_L(0); MMA(0, 0, At, B0); BAR;
	s_cbranch_scc0 .LBB0_460
	ds_read_b128 v[130:133], v233
	ds_read_b128 v[134:137], v233 offset:1024
	ds_read_b128 v[138:141], v233 offset:2048
	ds_read_b128 v[142:145], v233 offset:3072
	ds_read_b128 v[146:149], v234
	ds_read_b128 v[150:153], v234 offset:1024
	ds_read_b128 v[154:157], v235
	ds_read_b128 v[158:161], v235 offset:1024
	ds_read_b128 v[162:165], v236
	ds_read_b128 v[166:169], v236 offset:1024
	ds_read_b128 v[170:173], v237
	ds_read_b128 v[182:185], v237 offset:1024
	s_mov_b32 s21, s1
	v_readlane_b32 s44, v255, 5
	s_lshl_b64 s[34:35], s[20:21], 1
	v_readlane_b32 s48, v255, 9
	v_readlane_b32 s49, v255, 10
	s_add_u32 s42, s48, s34
	s_addc_u32 s43, s49, s35
	s_add_u32 s13, s90, s34
	s_addc_u32 s21, s91, s35
	s_add_i32 s0, s0, -1
	s_lshl_b64 s[34:35], s[0:1], 7
	s_add_u32 s34, s38, s34
	s_addc_u32 s35, s39, s35
	s_mov_b32 m0, s36
	s_nop 0
	global_load_lds_dwordx4 v230, s[34:35]
	v_readlane_b32 s45, v255, 6
	s_mov_b32 m0, s37
	s_nop 0
	global_load_lds_dwordx4 v231, s[34:35]
	s_barrier
	s_waitcnt lgkmcnt(0)
	v_readlane_b32 s46, v255, 7
	v_readlane_b32 s47, v255, 8
	v_readlane_b32 s50, v255, 11
	v_readlane_b32 s51, v255, 12
	v_readlane_b32 s52, v255, 13
	v_readlane_b32 s53, v255, 14
	v_readlane_b32 s54, v255, 15
	v_readlane_b32 s55, v255, 16
	v_readlane_b32 s56, v255, 17
	v_readlane_b32 s57, v255, 18
	v_readlane_b32 s58, v255, 19
	v_readlane_b32 s59, v255, 20
	s_setprio 1
	s_waitcnt lgkmcnt(7)
	v_mfma_f32_16x16x32_bf16 v[126:129], v[146:149], v[130:133], v[126:129]
	v_mfma_f32_16x16x32_bf16 v[122:125], v[146:149], v[138:141], v[122:125]
	s_waitcnt lgkmcnt(5)
	v_mfma_f32_16x16x32_bf16 v[118:121], v[154:157], v[130:133], v[118:121]
	v_mfma_f32_16x16x32_bf16 v[114:117], v[154:157], v[138:141], v[114:117]
	s_waitcnt lgkmcnt(3)
	v_mfma_f32_16x16x32_bf16 v[110:113], v[162:165], v[130:133], v[110:113]
	v_mfma_f32_16x16x32_bf16 v[106:109], v[162:165], v[138:141], v[106:109]
	s_waitcnt lgkmcnt(1)
	v_mfma_f32_16x16x32_bf16 v[102:105], v[170:173], v[130:133], v[102:105]
	v_mfma_f32_16x16x32_bf16 v[98:101], v[170:173], v[138:141], v[98:101]
	v_mfma_f32_16x16x32_bf16 v[126:129], v[150:153], v[134:137], v[126:129]
	v_mfma_f32_16x16x32_bf16 v[122:125], v[150:153], v[142:145], v[122:125]
	v_mfma_f32_16x16x32_bf16 v[118:121], v[158:161], v[134:137], v[118:121]
	v_mfma_f32_16x16x32_bf16 v[186:189], v[158:161], v[142:145], v[114:117]
	v_mfma_f32_16x16x32_bf16 v[110:113], v[166:169], v[134:137], v[110:113]
	v_mfma_f32_16x16x32_bf16 v[190:193], v[166:169], v[142:145], v[106:109]
	s_waitcnt lgkmcnt(0)
	v_mfma_f32_16x16x32_bf16 v[194:197], v[182:185], v[134:137], v[102:105]
	v_mfma_f32_16x16x32_bf16 v[198:201], v[182:185], v[142:145], v[98:101]
	s_setprio 0
	s_barrier
	ds_read_b128 v[202:205], v238
	ds_read_b128 v[206:209], v238 offset:1024
	ds_read_b128 v[210:213], v238 offset:2048
	ds_read_b128 v[242:245], v238 offset:3072
	s_barrier
	s_waitcnt lgkmcnt(0)
	s_setprio 1
	s_waitcnt lgkmcnt(3)
	v_mfma_f32_16x16x32_bf16 v[86:89], v[146:149], v[202:205], v[86:89]
	s_waitcnt lgkmcnt(1)
	v_mfma_f32_16x16x32_bf16 v[78:81], v[146:149], v[210:213], v[78:81]
	v_mfma_f32_16x16x32_bf16 v[66:69], v[154:157], v[202:205], v[66:69]
	v_mfma_f32_16x16x32_bf16 v[106:109], v[154:157], v[210:213], v[54:57]
	v_mfma_f32_16x16x32_bf16 v[46:49], v[162:165], v[202:205], v[46:49]
	v_mfma_f32_16x16x32_bf16 v[42:45], v[162:165], v[210:213], v[42:45]
	v_mfma_f32_16x16x32_bf16 v[38:41], v[170:173], v[202:205], v[38:41]
	v_mfma_f32_16x16x32_bf16 v[34:37], v[170:173], v[210:213], v[34:37]
	v_mfma_f32_16x16x32_bf16 v[54:57], v[150:153], v[206:209], v[86:89]
	s_waitcnt lgkmcnt(0)
	v_mfma_f32_16x16x32_bf16 v[98:101], v[150:153], v[242:245], v[78:81]
	v_mfma_f32_16x16x32_bf16 v[102:105], v[158:161], v[206:209], v[66:69]
	v_mfma_f32_16x16x32_bf16 v[106:109], v[158:161], v[242:245], v[106:109]
	v_mfma_f32_16x16x32_bf16 v[114:117], v[166:169], v[206:209], v[46:49]
	v_mfma_f32_16x16x32_bf16 v[174:177], v[166:169], v[242:245], v[42:45]
	v_mfma_f32_16x16x32_bf16 v[178:181], v[182:185], v[206:209], v[38:41]
	v_mfma_f32_16x16x32_bf16 v[182:185], v[182:185], v[242:245], v[34:37]
	s_setprio 0
	s_barrier
	ds_read_b128 v[66:69], v234 offset:16384
	ds_read_b128 v[78:81], v234 offset:17408
	ds_read_b128 v[86:89], v235 offset:16384
	ds_read_b128 v[146:149], v235 offset:17408
	ds_read_b128 v[150:153], v236 offset:16384
	ds_read_b128 v[154:157], v236 offset:17408
	ds_read_b128 v[158:161], v237 offset:16384
	ds_read_b128 v[162:165], v237 offset:17408
	s_waitcnt vmcnt(4)
	s_barrier
; #define STAGE(P, BASE, br, kt) do { const u16* _gb = (BASE) + (long)(br)*K + (long)(kt)*BK; \
;     unsigned _ld = lds0 + (unsigned)((char*)(P) - (char*)shm) + wv * 1024u; \
;     glds_s(_gb, voff0, _ld); glds_s(_gb, voff1, _ld + 8192u); } while (0)
; #define LDA(dst, b, h) for (int m = 0; m < 4; ++m) for (int k = 0; k < 2; ++k) \
;     dst[m][k] = *reinterpret_cast<const bf16x8*>((char*)SA(b, h) + lds_byte(wr * 64 + m * 16 + fr, k * 32 + fq * 8))
; #define LDB(dst, b, h) for (int n = 0; n < 2; ++n) for (int k = 0; k < 2; ++k) \
;     dst[n][k] = *reinterpret_cast<const bf16x8*>((char*)SB(b, h) + lds_byte(wc * 32 + n * 16 + fr, k * 32 + fq * 8))
; #define WAIT_V(n) asm volatile("s_waitcnt vmcnt(" #n ")" ::: "memory")
; #define WAIT_L(n) asm volatile("s_waitcnt lgkmcnt(" #n ")" ::: "memory")
; #define BAR __builtin_amdgcn_s_barrier()
;     ...
;       LDA(At, 0, 1); WAIT_V(4); BAR; WAIT_L(0); MMA(1, 0, At, B0); MMA(1, 1, At, B1); BAR; }
;     { LDB(B0, 1, 0); LDA(At, 1, 0); WAIT_V(2); BAR; WAIT_L(0); MMA(0, 0, At, B0); BAR;
;       LDB(B1, 1, 1);
;       if (has_next) { STAGE(SB(0, 0), ActN, nbcol, 0); STAGE(SA(0, 0), WtN, nbrow, 0); WAIT_V(4); } else { WAIT_V(0); }
;       BAR; WAIT_L(0); MMA(0, 1, At, B1); BAR;
	s_waitcnt lgkmcnt(0)
	s_setprio 1
	s_waitcnt lgkmcnt(7)
	v_mfma_f32_16x16x32_bf16 v[30:33], v[66:69], v[130:133], v[30:33]
	v_mfma_f32_16x16x32_bf16 v[26:29], v[66:69], v[138:141], v[26:29]
	s_waitcnt lgkmcnt(5)
	v_mfma_f32_16x16x32_bf16 v[22:25], v[86:89], v[130:133], v[22:25]
	v_mfma_f32_16x16x32_bf16 v[18:21], v[86:89], v[138:141], v[18:21]
	s_waitcnt lgkmcnt(3)
	v_mfma_f32_16x16x32_bf16 v[34:37], v[150:153], v[130:133], v[14:17]
	v_mfma_f32_16x16x32_bf16 v[38:41], v[150:153], v[138:141], v[10:13]
	s_waitcnt lgkmcnt(1)
	v_mfma_f32_16x16x32_bf16 v[42:45], v[158:161], v[130:133], v[6:9]
	v_mfma_f32_16x16x32_bf16 v[46:49], v[158:161], v[138:141], v[2:5]
	v_mfma_f32_16x16x32_bf16 v[2:5], v[78:81], v[134:137], v[30:33]
	v_mfma_f32_16x16x32_bf16 v[6:9], v[78:81], v[142:145], v[26:29]
	v_mfma_f32_16x16x32_bf16 v[10:13], v[146:149], v[134:137], v[22:25]
	v_mfma_f32_16x16x32_bf16 v[14:17], v[146:149], v[142:145], v[18:21]
	v_mfma_f32_16x16x32_bf16 v[34:37], v[154:157], v[134:137], v[34:37]
	v_mfma_f32_16x16x32_bf16 v[38:41], v[154:157], v[142:145], v[38:41]
	s_waitcnt lgkmcnt(0)
	v_mfma_f32_16x16x32_bf16 v[42:45], v[162:165], v[134:137], v[42:45]
	v_mfma_f32_16x16x32_bf16 v[46:49], v[162:165], v[142:145], v[46:49]
	s_setprio 0
	s_setprio 1
	v_mfma_f32_16x16x32_bf16 v[18:21], v[66:69], v[202:205], v[50:53]
	v_mfma_f32_16x16x32_bf16 v[22:25], v[66:69], v[210:213], v[58:61]
	v_mfma_f32_16x16x32_bf16 v[26:29], v[86:89], v[202:205], v[62:65]
	v_mfma_f32_16x16x32_bf16 v[30:33], v[86:89], v[210:213], v[70:73]
	v_mfma_f32_16x16x32_bf16 v[50:53], v[150:153], v[202:205], v[74:77]
	v_mfma_f32_16x16x32_bf16 v[58:61], v[150:153], v[210:213], v[82:85]
	v_mfma_f32_16x16x32_bf16 v[62:65], v[158:161], v[202:205], v[90:93]
	v_mfma_f32_16x16x32_bf16 v[66:69], v[158:161], v[210:213], v[94:97]
	v_mfma_f32_16x16x32_bf16 v[130:133], v[78:81], v[206:209], v[18:21]
	v_mfma_f32_16x16x32_bf16 v[134:137], v[78:81], v[242:245], v[22:25]
	v_mfma_f32_16x16x32_bf16 v[138:141], v[146:149], v[206:209], v[26:29]
	v_mfma_f32_16x16x32_bf16 v[142:145], v[146:149], v[242:245], v[30:33]
	v_mfma_f32_16x16x32_bf16 v[146:149], v[154:157], v[206:209], v[50:53]
	v_mfma_f32_16x16x32_bf16 v[150:153], v[154:157], v[242:245], v[58:61]
	v_mfma_f32_16x16x32_bf16 v[154:157], v[162:165], v[206:209], v[62:65]
	v_mfma_f32_16x16x32_bf16 v[158:161], v[162:165], v[242:245], v[66:69]
	s_setprio 0
	s_barrier
	ds_read_b128 v[70:73], v239
	ds_read_b128 v[66:69], v239 offset:1024
	ds_read_b128 v[74:77], v239 offset:2048
	ds_read_b128 v[162:165], v239 offset:3072
	ds_read_b128 v[26:29], v234 offset:32768
	ds_read_b128 v[18:21], v234 offset:33792
	ds_read_b128 v[30:33], v235 offset:32768
	ds_read_b128 v[22:25], v235 offset:33792
	ds_read_b128 v[58:61], v236 offset:32768
	ds_read_b128 v[50:53], v236 offset:33792
	ds_read_b128 v[62:65], v237 offset:32768
	ds_read_b128 v[82:85], v237 offset:33792
	s_waitcnt vmcnt(2)
	s_barrier
	s_waitcnt lgkmcnt(0)
	s_setprio 1
	s_waitcnt lgkmcnt(7)
	v_mfma_f32_16x16x32_bf16 v[78:81], v[26:29], v[70:73], v[126:129]
	v_mfma_f32_16x16x32_bf16 v[86:89], v[26:29], v[74:77], v[122:125]
	s_waitcnt lgkmcnt(5)
	v_mfma_f32_16x16x32_bf16 v[90:93], v[30:33], v[70:73], v[118:121]
	v_mfma_f32_16x16x32_bf16 v[118:121], v[30:33], v[74:77], v[186:189]
	s_waitcnt lgkmcnt(3)
	v_mfma_f32_16x16x32_bf16 v[110:113], v[58:61], v[70:73], v[110:113]
	v_mfma_f32_16x16x32_bf16 v[166:169], v[58:61], v[74:77], v[190:193]
	s_waitcnt lgkmcnt(1)
	v_mfma_f32_16x16x32_bf16 v[170:173], v[62:65], v[70:73], v[194:197]
	v_mfma_f32_16x16x32_bf16 v[186:189], v[62:65], v[74:77], v[198:201]
	v_mfma_f32_16x16x32_bf16 v[126:129], v[18:21], v[66:69], v[78:81]
	v_mfma_f32_16x16x32_bf16 v[94:97], v[18:21], v[162:165], v[86:89]
	v_mfma_f32_16x16x32_bf16 v[122:125], v[22:25], v[66:69], v[90:93]
	v_mfma_f32_16x16x32_bf16 v[90:93], v[22:25], v[162:165], v[118:121]
	v_mfma_f32_16x16x32_bf16 v[118:121], v[50:53], v[66:69], v[110:113]
	v_mfma_f32_16x16x32_bf16 v[86:89], v[50:53], v[162:165], v[166:169]
	s_waitcnt lgkmcnt(0)
	v_mfma_f32_16x16x32_bf16 v[110:113], v[82:85], v[66:69], v[170:173]
	v_mfma_f32_16x16x32_bf16 v[78:81], v[82:85], v[162:165], v[186:189]
	s_setprio 0
	s_barrier
	s_nop 0
	ds_read_b128 v[186:189], v240
	ds_read_b128 v[166:169], v240 offset:1024
	ds_read_b128 v[190:193], v240 offset:2048
	ds_read_b128 v[170:173], v240 offset:3072
	s_mov_b64 s[34:35], -1
	s_and_b64 vcc, exec, s[18:19]
	s_cbranch_vccz .LBB0_463
	s_waitcnt vmcnt(0)
	s_mov_b64 s[34:35], 0
; #define STAGE(P, BASE, br, kt) do { const u16* _gb = (BASE) + (long)(br)*K + (long)(kt)*BK; \
;     unsigned _ld = lds0 + (unsigned)((char*)(P) - (char*)shm) + wv * 1024u; \
;     glds_s(_gb, voff0, _ld); glds_s(_gb, voff1, _ld + 8192u); } while (0)
; #define LDA(dst, b, h) for (int m = 0; m < 4; ++m) for (int k = 0; k < 2; ++k) \
;     dst[m][k] = *reinterpret_cast<const bf16x8*>((char*)SA(b, h) + lds_byte(wr * 64 + m * 16 + fr, k * 32 + fq * 8))
; #define LDB(dst, b, h) for (int n = 0; n < 2; ++n) for (int k = 0; k < 2; ++k) \
;     dst[n][k] = *reinterpret_cast<const bf16x8*>((char*)SB(b, h) + lds_byte(wc * 32 + n * 16 + fr, k * 32 + fq * 8))
; #define WAIT_V(n) asm volatile("s_waitcnt vmcnt(" #n ")" ::: "memory")
; #define WAIT_L(n) asm volatile("s_waitcnt lgkmcnt(" #n ")" ::: "memory")
; #define BAR __builtin_amdgcn_s_barrier()
;     ...
;     { LDB(B0, 1, 0); LDA(At, 1, 0); WAIT_V(2); BAR; WAIT_L(0); MMA(0, 0, At, B0); BAR;
;       LDB(B1, 1, 1);
;       if (has_next) { STAGE(SB(0, 0), ActN, nbcol, 0); STAGE(SA(0, 0), WtN, nbrow, 0); WAIT_V(4); } else { WAIT_V(0); }
;       BAR; WAIT_L(0); MMA(0, 1, At, B1); BAR;
;       LDA(At, 1, 1);
;       if (has_next) { STAGE(SB(0, 1), ActN, nbcol + HALF, 0); STAGE(SA(0, 1), WtN, nbrow + HALF, 0); }
;       BAR; WAIT_L(0); MMA(1, 0, At, B0); MMA(1, 1, At, B1); BAR; }
.LBB0_463:
	s_andn2_b64 vcc, exec, s[34:35]
	s_mov_b32 s46, 0x800000
	s_cbranch_vccnz .LBB0_465
	s_ashr_i32 s23, s22, 31
	s_lshl_b64 s[34:35], s[22:23], 13
	s_add_u32 s34, s42, s34
	s_addc_u32 s35, s43, s35
	s_mov_b32 m0, s92
	s_nop 0
	global_load_lds_dwordx4 v230, s[34:35]
	s_ashr_i32 s25, s24, 31
	s_mov_b32 m0, s94
	s_nop 0
	global_load_lds_dwordx4 v231, s[34:35]
	s_lshl_b64 s[34:35], s[24:25], 13
	s_add_u32 s34, s13, s34
	s_addc_u32 s35, s21, s35
	s_mov_b32 m0, s93
	s_nop 0
	global_load_lds_dwordx4 v230, s[34:35]
	s_nop 0
	s_mov_b32 m0, s95
	s_nop 0
	global_load_lds_dwordx4 v231, s[34:35]
	s_waitcnt vmcnt(4)
.LBB0_465:
	s_barrier
	s_waitcnt lgkmcnt(0)
	s_setprio 1
	s_waitcnt lgkmcnt(3)
	v_mfma_f32_16x16x32_bf16 v[54:57], v[26:29], v[186:189], v[54:57]
	s_waitcnt lgkmcnt(1)
	v_mfma_f32_16x16x32_bf16 v[26:29], v[26:29], v[190:193], v[98:101]
	v_mfma_f32_16x16x32_bf16 v[98:101], v[30:33], v[186:189], v[102:105]
	v_mfma_f32_16x16x32_bf16 v[102:105], v[30:33], v[190:193], v[106:109]
	v_mfma_f32_16x16x32_bf16 v[106:109], v[58:61], v[186:189], v[114:117]
	v_mfma_f32_16x16x32_bf16 v[114:117], v[58:61], v[190:193], v[174:177]
	v_mfma_f32_16x16x32_bf16 v[174:177], v[62:65], v[186:189], v[178:181]
	v_mfma_f32_16x16x32_bf16 v[178:181], v[62:65], v[190:193], v[182:185]
	v_mfma_f32_16x16x32_bf16 v[62:65], v[18:21], v[166:169], v[54:57]
	s_waitcnt lgkmcnt(0)
	v_mfma_f32_16x16x32_bf16 v[30:33], v[18:21], v[170:173], v[26:29]
	v_mfma_f32_16x16x32_bf16 v[58:61], v[22:25], v[166:169], v[98:101]
	v_mfma_f32_16x16x32_bf16 v[26:29], v[22:25], v[170:173], v[102:105]
	v_mfma_f32_16x16x32_bf16 v[54:57], v[50:53], v[166:169], v[106:109]
	v_mfma_f32_16x16x32_bf16 v[22:25], v[50:53], v[170:173], v[114:117]
	v_mfma_f32_16x16x32_bf16 v[50:53], v[82:85], v[166:169], v[174:177]
	v_mfma_f32_16x16x32_bf16 v[18:21], v[82:85], v[170:173], v[178:181]
	s_setprio 0
	s_barrier
	ds_read_b128 v[198:201], v234 offset:49152
	ds_read_b128 v[174:177], v234 offset:50176
	ds_read_b128 v[202:205], v235 offset:49152
	ds_read_b128 v[178:181], v235 offset:50176
	ds_read_b128 v[206:209], v236 offset:49152
	ds_read_b128 v[182:185], v236 offset:50176
	ds_read_b128 v[210:213], v237 offset:49152
	ds_read_b128 v[194:197], v237 offset:50176
	s_andn2_b64 vcc, exec, s[14:15]
	s_cbranch_vccnz .LBB0_467
	s_ashr_i32 s23, s22, 31
	s_lshl_b64 s[14:15], s[22:23], 13
	s_add_u32 s0, s42, s14
	s_addc_u32 s15, s43, s15
	s_add_u32 s14, s0, 0x100000
	s_addc_u32 s15, s15, 0
	s_mov_b32 m0, s97
	s_nop 0
	global_load_lds_dwordx4 v230, s[14:15]
	s_ashr_i32 s25, s24, 31
	s_mov_b32 m0, s16
	s_nop 0
	global_load_lds_dwordx4 v231, s[14:15]
	s_lshl_b64 s[14:15], s[24:25], 13
	s_add_u32 s0, s13, s14
	s_addc_u32 s13, s21, s15
	s_add_u32 s14, s0, 0x100000
	s_addc_u32 s15, s13, 0
	s_mov_b32 m0, s17
	s_nop 0
	global_load_lds_dwordx4 v230, s[14:15]
	s_nop 0
	s_mov_b32 m0, s10
	s_nop 0
	global_load_lds_dwordx4 v231, s[14:15]

; #define STAGE(P, BASE, br, kt) do { const u16* _gb = (BASE) + (long)(br)*K + (long)(kt)*BK; \
;     unsigned _ld = lds0 + (unsigned)((char*)(P) - (char*)shm) + wv * 1024u; \
;     glds_s(_gb, voff0, _ld); glds_s(_gb, voff1, _ld + 8192u); } while (0)
; #define WAIT_V(n) asm volatile("s_waitcnt vmcnt(" #n ")" ::: "memory")
; #define BAR __builtin_amdgcn_s_barrier()
;     ...
;     if (!staged) {
;       STAGE(SB(0, 0), ActK, bcol, 0); STAGE(SA(0, 0), WtK, brow, 0);
;       STAGE(SB(0, 1), ActK, bcol + HALF, 0); STAGE(SA(0, 1), WtK, brow + HALF, 0);
;       if (wr == 1) BAR;
;       WAIT_V(4); BAR;
.LBB0_639:
	s_xor_b64 s[14:15], s[14:15], -1
	s_andn2_b64 vcc, exec, s[14:15]
	s_mov_b64 s[88:89], -1
	s_cbranch_vccnz .LBB0_643
	s_ashr_i32 s11, s10, 31
	s_lshl_b64 s[14:15], s[10:11], 11
	s_add_u32 s16, s78, s14
	s_addc_u32 s17, s79, s15
	s_mov_b32 m0, s8
	s_nop 0
	global_load_lds_dwordx4 v198, s[16:17]
	s_nop 0
	s_mov_b32 m0, s40
	s_nop 0
	global_load_lds_dwordx4 v199, s[16:17]
	s_ashr_i32 s5, s4, 31
	s_lshl_b64 s[16:17], s[4:5], 11
	s_add_u32 s18, s91, s16
	s_addc_u32 s19, s93, s17
	s_mov_b32 m0, s9
	s_nop 0
	global_load_lds_dwordx4 v198, s[18:19]
	s_nop 0
	s_mov_b32 m0, s41
	s_nop 0
	global_load_lds_dwordx4 v199, s[18:19]
	s_add_u32 s18, s14, 0x40000
	s_addc_u32 s19, s15, 0
	s_add_u32 s36, s78, s18
	s_addc_u32 s37, s79, s19
	s_add_u32 s86, s16, 0x40000
	s_mov_b32 m0, s97
	s_nop 0
	global_load_lds_dwordx4 v198, s[36:37]
	s_addc_u32 s87, s17, 0
	s_mov_b32 m0, s6
	s_nop 0
	global_load_lds_dwordx4 v199, s[36:37]
	s_add_u32 s36, s91, s86
	s_addc_u32 s37, s93, s87
	s_mov_b32 m0, s7
	s_nop 0
	global_load_lds_dwordx4 v198, s[36:37]
	s_nop 0
	s_mov_b32 m0, s34
	s_nop 0
	global_load_lds_dwordx4 v199, s[36:37]
	s_mov_b64 s[88:89], exec
	v_readlane_b32 s36, v255, 36
	v_readlane_b32 s37, v255, 37
	s_and_b64 s[36:37], s[88:89], s[36:37]
	s_mov_b64 exec, s[36:37]
	s_cbranch_execz .LBB0_642
	s_barrier

; #define STAGE(P, BASE, br, kt) do { const u16* _gb = (BASE) + (long)(br)*K + (long)(kt)*BK; \
;     unsigned _ld = lds0 + (unsigned)((char*)(P) - (char*)shm) + wv * 1024u; \
;     glds_s(_gb, voff0, _ld); glds_s(_gb, voff1, _ld + 8192u); } while (0)
; #define LDA(dst, b, h) for (int m = 0; m < 4; ++m) for (int k = 0; k < 2; ++k) \
;     dst[m][k] = *reinterpret_cast<const bf16x8*>((char*)SA(b, h) + lds_byte(wr * 64 + m * 16 + fr, k * 32 + fq * 8))
; #define LDB(dst, b, h) for (int n = 0; n < 2; ++n) for (int k = 0; k < 2; ++k) \
;     dst[n][k] = *reinterpret_cast<const bf16x8*>((char*)SB(b, h) + lds_byte(wc * 32 + n * 16 + fr, k * 32 + fq * 8))
; #define WAIT_V(n) asm volatile("s_waitcnt vmcnt(" #n ")" ::: "memory")
; #define WAIT_L(n) asm volatile("s_waitcnt lgkmcnt(" #n ")" ::: "memory")
; #define BAR __builtin_amdgcn_s_barrier()
; #define SCHED __builtin_amdgcn_sched_barrier(0)
;     ...
;     f32x4 acc[2][2][4][2] = {};
;     bf16x8 At[4][2], B0[2][2], B1[2][2];
;     if (!staged) {
;       STAGE(SB(0, 0), ActK, bcol, 0); STAGE(SA(0, 0), WtK, brow, 0);
;       STAGE(SB(0, 1), ActK, bcol + HALF, 0); STAGE(SA(0, 1), WtK, brow + HALF, 0);
;       if (wr == 1) BAR;
;       WAIT_V(4); BAR;
;     } else {
;       if (wr == 1) BAR;
;       WAIT_V(0); BAR;
;     }
;     STAGE(SB(1, 0), ActK, bcol, 1); STAGE(SA(1, 0), WtK, brow, 1); STAGE(SB(1, 1), ActK, bcol + HALF, 1);
;     WAIT_V(6); BAR;
;     for (int t = 0; t < nt - 2; t += 2) {
;       LDB(B0, 0, 0); SCHED; LDA(At, 0, 0); STAGE(SA(1, 1), WtK, brow + HALF, t + 1);
;       WAIT_L(8); BAR; WAIT_L(0); MMA(0, 0, At, B0); BAR; SCHED;
.LBB0_647:
	s_add_u32 s5, s78, s14
	s_addc_u32 s11, s79, s15
	s_add_u32 s14, s5, 0x80
	s_addc_u32 s15, s11, 0
	s_add_u32 s16, s91, s16
	s_mov_b32 m0, s35
	s_nop 0
	global_load_lds_dwordx4 v198, s[14:15]
	s_addc_u32 s17, s93, s17
	s_mov_b32 m0, s94
	s_nop 0
	global_load_lds_dwordx4 v199, s[14:15]
	s_add_u32 s14, s16, 0x80
	s_addc_u32 s15, s17, 0
	s_mov_b32 m0, s95
	s_nop 0
	global_load_lds_dwordx4 v198, s[14:15]
	v_mov_b32_e32 v2, 0
	s_mov_b32 m0, s22
	s_nop 0
	global_load_lds_dwordx4 v199, s[14:15]
	s_add_u32 s27, s78, s18
	s_addc_u32 s36, s79, s19
	s_add_u32 s14, s27, 0x80
	s_addc_u32 s15, s36, 0
	s_mov_b32 m0, s23
	s_nop 0
	global_load_lds_dwordx4 v198, s[14:15]
	s_mov_b32 s43, -2
	s_mov_b32 m0, s24
	s_nop 0
	global_load_lds_dwordx4 v199, s[14:15]
	s_add_u32 s18, s91, s86
	s_addc_u32 s19, s93, s87
	s_add_u32 s37, s18, 0x100
	s_addc_u32 s42, s19, 0
	s_mov_b64 s[14:15], 0
	v_mov_b32_e32 v3, v2
	v_mov_b32_e32 v4, v2
	v_mov_b32_e32 v5, v2
	v_mov_b32_e32 v6, v2
	v_mov_b32_e32 v7, v2
	v_mov_b32_e32 v8, v2
	v_mov_b32_e32 v9, v2
	v_mov_b32_e32 v10, v2
	v_mov_b32_e32 v11, v2
	v_mov_b32_e32 v12, v2
	v_mov_b32_e32 v13, v2
	v_mov_b32_e32 v14, v2
	v_mov_b32_e32 v15, v2
	v_mov_b32_e32 v16, v2
	v_mov_b32_e32 v17, v2
	v_mov_b32_e32 v18, v2
	v_mov_b32_e32 v19, v2
	v_mov_b32_e32 v20, v2
	v_mov_b32_e32 v21, v2
	v_mov_b32_e32 v22, v2
	v_mov_b32_e32 v23, v2
	v_mov_b32_e32 v24, v2
	v_mov_b32_e32 v25, v2
	v_mov_b32_e32 v26, v2
	v_mov_b32_e32 v27, v2
	v_mov_b32_e32 v28, v2
	v_mov_b32_e32 v29, v2
	v_mov_b32_e32 v30, v2
	v_mov_b32_e32 v31, v2
	v_mov_b32_e32 v32, v2
	v_mov_b32_e32 v33, v2
	v_mov_b32_e32 v34, v2
	v_mov_b32_e32 v35, v2
	v_mov_b32_e32 v36, v2
	v_mov_b32_e32 v37, v2
	v_mov_b32_e32 v38, v2
	v_mov_b32_e32 v39, v2
	v_mov_b32_e32 v40, v2
	v_mov_b32_e32 v41, v2
	v_mov_b32_e32 v42, v2
	v_mov_b32_e32 v43, v2
	v_mov_b32_e32 v44, v2
	v_mov_b32_e32 v45, v2
	v_mov_b32_e32 v46, v2
	v_mov_b32_e32 v47, v2
	v_mov_b32_e32 v48, v2
	v_mov_b32_e32 v49, v2
	v_mov_b32_e32 v50, v2
	v_mov_b32_e32 v51, v2
	v_mov_b32_e32 v52, v2
	v_mov_b32_e32 v53, v2
	v_mov_b32_e32 v54, v2
	v_mov_b32_e32 v55, v2
	v_mov_b32_e32 v56, v2
	v_mov_b32_e32 v57, v2
	v_mov_b32_e32 v58, v2
	v_mov_b32_e32 v59, v2
	v_mov_b32_e32 v60, v2
	v_mov_b32_e32 v61, v2
	v_mov_b32_e32 v62, v2
	v_mov_b32_e32 v63, v2
	v_mov_b32_e32 v64, v2
	v_mov_b32_e32 v65, v2
	v_mov_b32_e32 v66, v2
	v_mov_b32_e32 v67, v2
	v_mov_b32_e32 v68, v2
	v_mov_b32_e32 v69, v2
	v_mov_b32_e32 v70, v2
	v_mov_b32_e32 v71, v2
	v_mov_b32_e32 v72, v2
	v_mov_b32_e32 v73, v2
	v_mov_b32_e32 v74, v2
	v_mov_b32_e32 v75, v2
	v_mov_b32_e32 v76, v2
	v_mov_b32_e32 v77, v2
	v_mov_b32_e32 v78, v2
	v_mov_b32_e32 v79, v2
	v_mov_b32_e32 v80, v2
	v_mov_b32_e32 v81, v2
	v_mov_b32_e32 v82, v2
	v_mov_b32_e32 v83, v2
	v_mov_b32_e32 v84, v2
	v_mov_b32_e32 v85, v2
	v_mov_b32_e32 v86, v2
	v_mov_b32_e32 v87, v2
	v_mov_b32_e32 v88, v2
	v_mov_b32_e32 v89, v2
	v_mov_b32_e32 v90, v2
	v_mov_b32_e32 v91, v2
	v_mov_b32_e32 v92, v2
	v_mov_b32_e32 v93, v2
	v_mov_b32_e32 v94, v2
	v_mov_b32_e32 v95, v2
	v_mov_b32_e32 v96, v2
	v_mov_b32_e32 v97, v2
	v_mov_b32_e32 v98, v2
	v_mov_b32_e32 v99, v2
	v_mov_b32_e32 v100, v2
	v_mov_b32_e32 v101, v2
	v_mov_b32_e32 v102, v2
	v_mov_b32_e32 v103, v2
	v_mov_b32_e32 v104, v2
	v_mov_b32_e32 v105, v2
	v_mov_b32_e32 v106, v2
	v_mov_b32_e32 v107, v2
	v_mov_b32_e32 v108, v2
	v_mov_b32_e32 v109, v2
	v_mov_b32_e32 v110, v2
	v_mov_b32_e32 v111, v2
	v_mov_b32_e32 v112, v2
	v_mov_b32_e32 v113, v2
	v_mov_b32_e32 v114, v2
	v_mov_b32_e32 v115, v2
	v_mov_b32_e32 v116, v2
	v_mov_b32_e32 v117, v2
	v_mov_b32_e32 v118, v2
	v_mov_b32_e32 v119, v2
	v_mov_b32_e32 v120, v2
	v_mov_b32_e32 v121, v2
	v_mov_b32_e32 v122, v2
	v_mov_b32_e32 v123, v2
	v_mov_b32_e32 v124, v2
	v_mov_b32_e32 v125, v2
	v_mov_b32_e32 v126, v2
	v_mov_b32_e32 v127, v2
	v_mov_b32_e32 v128, v2
	v_mov_b32_e32 v129, v2
	s_waitcnt vmcnt(6)
	s_barrier
.LBB0_648:
	ds_read_b128 v[130:133], v202
	ds_read_b128 v[134:137], v202 offset:1024
	ds_read_b128 v[138:141], v202 offset:2048
	ds_read_b128 v[142:145], v202 offset:3072
	ds_read_b128 v[146:149], v203
	ds_read_b128 v[150:153], v203 offset:1024
	ds_read_b128 v[154:157], v204
	ds_read_b128 v[158:161], v204 offset:1024
	ds_read_b128 v[162:165], v205
	ds_read_b128 v[166:169], v205 offset:1024
	ds_read_b128 v[170:173], v206
	ds_read_b128 v[174:177], v206 offset:1024
	s_add_u32 s44, s18, s14
	s_addc_u32 s45, s19, s15
	s_add_u32 s44, s44, 0x80
	s_addc_u32 s45, s45, 0
	s_mov_b32 m0, s25
	s_nop 0
	global_load_lds_dwordx4 v198, s[44:45]
	s_nop 0
	s_mov_b32 m0, s26
	s_nop 0
	global_load_lds_dwordx4 v199, s[44:45]
	s_waitcnt lgkmcnt(8)
	s_barrier
	s_waitcnt lgkmcnt(0)
	s_setprio 1
	s_waitcnt lgkmcnt(7)
	v_mfma_f32_16x16x32_bf16 v[126:129], v[146:149], v[130:133], v[126:129]
	v_mfma_f32_16x16x32_bf16 v[122:125], v[146:149], v[138:141], v[122:125]
	s_waitcnt lgkmcnt(5)
	v_mfma_f32_16x16x32_bf16 v[118:121], v[154:157], v[130:133], v[118:121]
	v_mfma_f32_16x16x32_bf16 v[114:117], v[154:157], v[138:141], v[114:117]
	s_waitcnt lgkmcnt(3)
	v_mfma_f32_16x16x32_bf16 v[110:113], v[162:165], v[130:133], v[110:113]
	v_mfma_f32_16x16x32_bf16 v[106:109], v[162:165], v[138:141], v[106:109]
	s_waitcnt lgkmcnt(1)
	v_mfma_f32_16x16x32_bf16 v[102:105], v[170:173], v[130:133], v[102:105]
	v_mfma_f32_16x16x32_bf16 v[98:101], v[170:173], v[138:141], v[98:101]
	v_mfma_f32_16x16x32_bf16 v[126:129], v[150:153], v[134:137], v[126:129]
	v_mfma_f32_16x16x32_bf16 v[122:125], v[150:153], v[142:145], v[122:125]
	v_mfma_f32_16x16x32_bf16 v[118:121], v[158:161], v[134:137], v[118:121]
	v_mfma_f32_16x16x32_bf16 v[114:117], v[158:161], v[142:145], v[114:117]
	v_mfma_f32_16x16x32_bf16 v[110:113], v[166:169], v[134:137], v[110:113]
	v_mfma_f32_16x16x32_bf16 v[106:109], v[166:169], v[142:145], v[106:109]
	s_waitcnt lgkmcnt(0)
	v_mfma_f32_16x16x32_bf16 v[102:105], v[174:177], v[134:137], v[102:105]
	v_mfma_f32_16x16x32_bf16 v[98:101], v[174:177], v[142:145], v[98:101]
	s_setprio 0
	s_barrier
; #define STAGE(P, BASE, br, kt) do { const u16* _gb = (BASE) + (long)(br)*K + (long)(kt)*BK; \
;     unsigned _ld = lds0 + (unsigned)((char*)(P) - (char*)shm) + wv * 1024u; \
;     glds_s(_gb, voff0, _ld); glds_s(_gb, voff1, _ld + 8192u); } while (0)
; #define LDA(dst, b, h) for (int m = 0; m < 4; ++m) for (int k = 0; k < 2; ++k) \
;     dst[m][k] = *reinterpret_cast<const bf16x8*>((char*)SA(b, h) + lds_byte(wr * 64 + m * 16 + fr, k * 32 + fq * 8))
; #define LDB(dst, b, h) for (int n = 0; n < 2; ++n) for (int k = 0; k < 2; ++k) \
;     dst[n][k] = *reinterpret_cast<const bf16x8*>((char*)SB(b, h) + lds_byte(wc * 32 + n * 16 + fr, k * 32 + fq * 8))
; #define WAIT_V(n) asm volatile("s_waitcnt vmcnt(" #n ")" ::: "memory")
; #define WAIT_L(n) asm volatile("s_waitcnt lgkmcnt(" #n ")" ::: "memory")
; #define BAR __builtin_amdgcn_s_barrier()
; #define SCHED __builtin_amdgcn_sched_barrier(0)
;     ...
;       WAIT_L(8); BAR; WAIT_L(0); MMA(0, 0, At, B0); BAR; SCHED;
;       LDB(B1, 0, 1); STAGE(SB(0, 0), ActK, bcol, t + 2);
;       BAR; WAIT_L(0); MMA(0, 1, At, B1); BAR;
;       LDA(At, 0, 1); STAGE(SA(0, 0), WtK, brow, t + 2);
;       BAR; WAIT_L(0); MMA(1, 0, At, B0); BAR; SCHED;
;       STAGE(SB(0, 1), ActK, bcol + HALF, t + 2);
;       WAIT_V(6); BAR; MMA(1, 1, At, B1); BAR;
;       LDB(B0, 1, 0); SCHED; LDA(At, 1, 0); STAGE(SA(0, 1), WtK, brow + HALF, t + 2);
;       WAIT_L(8); BAR; WAIT_L(0); MMA(0, 0, At, B0); BAR; SCHED;
	ds_read_b128 v[178:181], v207
	ds_read_b128 v[182:185], v207 offset:1024
	ds_read_b128 v[186:189], v207 offset:2048
	ds_read_b128 v[190:193], v207 offset:3072
	s_add_u32 s46, s5, s14
	s_addc_u32 s47, s11, s15
	s_add_u32 s44, s46, 0x100
	s_addc_u32 s45, s47, 0
	s_mov_b32 m0, s8
	s_nop 0
	global_load_lds_dwordx4 v198, s[44:45]
	s_nop 0
	s_mov_b32 m0, s40
	s_nop 0
	global_load_lds_dwordx4 v199, s[44:45]
	s_barrier
	s_waitcnt lgkmcnt(0)
	s_setprio 1
	s_waitcnt lgkmcnt(3)
	v_mfma_f32_16x16x32_bf16 v[94:97], v[146:149], v[178:181], v[94:97]
	s_waitcnt lgkmcnt(1)
	v_mfma_f32_16x16x32_bf16 v[90:93], v[146:149], v[186:189], v[90:93]
	v_mfma_f32_16x16x32_bf16 v[86:89], v[154:157], v[178:181], v[86:89]
	v_mfma_f32_16x16x32_bf16 v[82:85], v[154:157], v[186:189], v[82:85]
	v_mfma_f32_16x16x32_bf16 v[78:81], v[162:165], v[178:181], v[78:81]
	v_mfma_f32_16x16x32_bf16 v[74:77], v[162:165], v[186:189], v[74:77]
	v_mfma_f32_16x16x32_bf16 v[70:73], v[170:173], v[178:181], v[70:73]
	v_mfma_f32_16x16x32_bf16 v[66:69], v[170:173], v[186:189], v[66:69]
	v_mfma_f32_16x16x32_bf16 v[94:97], v[150:153], v[182:185], v[94:97]
	s_waitcnt lgkmcnt(0)
	v_mfma_f32_16x16x32_bf16 v[90:93], v[150:153], v[190:193], v[90:93]
	v_mfma_f32_16x16x32_bf16 v[86:89], v[158:161], v[182:185], v[86:89]
	v_mfma_f32_16x16x32_bf16 v[82:85], v[158:161], v[190:193], v[82:85]
	v_mfma_f32_16x16x32_bf16 v[78:81], v[166:169], v[182:185], v[78:81]
	v_mfma_f32_16x16x32_bf16 v[74:77], v[166:169], v[190:193], v[74:77]
	v_mfma_f32_16x16x32_bf16 v[70:73], v[174:177], v[182:185], v[70:73]
	v_mfma_f32_16x16x32_bf16 v[66:69], v[174:177], v[190:193], v[66:69]
	s_setprio 0
	s_barrier
	ds_read_b128 v[146:149], v203 offset:16384
	ds_read_b128 v[150:153], v203 offset:17408
	ds_read_b128 v[154:157], v204 offset:16384
	ds_read_b128 v[158:161], v204 offset:17408
	ds_read_b128 v[162:165], v205 offset:16384
	ds_read_b128 v[166:169], v205 offset:17408
	ds_read_b128 v[170:173], v206 offset:16384
	ds_read_b128 v[174:177], v206 offset:17408
	s_add_u32 s48, s16, s14
	s_addc_u32 s49, s17, s15
	s_add_u32 s44, s48, 0x100
	s_addc_u32 s45, s49, 0
	s_mov_b32 m0, s9
	s_nop 0
	global_load_lds_dwordx4 v198, s[44:45]
	s_nop 0
	s_mov_b32 m0, s41
	s_nop 0
	global_load_lds_dwordx4 v199, s[44:45]
	s_barrier
	s_waitcnt lgkmcnt(0)
	s_setprio 1
	s_waitcnt lgkmcnt(7)
	v_mfma_f32_16x16x32_bf16 v[62:65], v[146:149], v[130:133], v[62:65]
	v_mfma_f32_16x16x32_bf16 v[58:61], v[146:149], v[138:141], v[58:61]
	s_waitcnt lgkmcnt(5)
	v_mfma_f32_16x16x32_bf16 v[54:57], v[154:157], v[130:133], v[54:57]
	v_mfma_f32_16x16x32_bf16 v[50:53], v[154:157], v[138:141], v[50:53]
	s_waitcnt lgkmcnt(3)
	v_mfma_f32_16x16x32_bf16 v[46:49], v[162:165], v[130:133], v[46:49]
	v_mfma_f32_16x16x32_bf16 v[42:45], v[162:165], v[138:141], v[42:45]
	s_waitcnt lgkmcnt(1)
	v_mfma_f32_16x16x32_bf16 v[38:41], v[170:173], v[130:133], v[38:41]
	v_mfma_f32_16x16x32_bf16 v[34:37], v[170:173], v[138:141], v[34:37]
	v_mfma_f32_16x16x32_bf16 v[62:65], v[150:153], v[134:137], v[62:65]
	v_mfma_f32_16x16x32_bf16 v[58:61], v[150:153], v[142:145], v[58:61]
	v_mfma_f32_16x16x32_bf16 v[54:57], v[158:161], v[134:137], v[54:57]
	v_mfma_f32_16x16x32_bf16 v[50:53], v[158:161], v[142:145], v[50:53]
	v_mfma_f32_16x16x32_bf16 v[46:49], v[166:169], v[134:137], v[46:49]
	v_mfma_f32_16x16x32_bf16 v[42:45], v[166:169], v[142:145], v[42:45]
	s_waitcnt lgkmcnt(0)
	v_mfma_f32_16x16x32_bf16 v[38:41], v[174:177], v[134:137], v[38:41]
	v_mfma_f32_16x16x32_bf16 v[34:37], v[174:177], v[142:145], v[34:37]
	s_setprio 0
	s_barrier
	s_add_u32 s50, s27, s14
	s_addc_u32 s51, s36, s15
	s_add_u32 s44, s50, 0x100
	s_addc_u32 s45, s51, 0
	s_mov_b32 m0, s97
	s_nop 0
	global_load_lds_dwordx4 v198, s[44:45]
	s_nop 0
	s_mov_b32 m0, s6
	s_nop 0
	global_load_lds_dwordx4 v199, s[44:45]
	s_waitcnt vmcnt(6)
	s_barrier
	s_setprio 1
	v_mfma_f32_16x16x32_bf16 v[30:33], v[146:149], v[178:181], v[30:33]
	v_mfma_f32_16x16x32_bf16 v[26:29], v[146:149], v[186:189], v[26:29]
	v_mfma_f32_16x16x32_bf16 v[22:25], v[154:157], v[178:181], v[22:25]
	v_mfma_f32_16x16x32_bf16 v[18:21], v[154:157], v[186:189], v[18:21]
	v_mfma_f32_16x16x32_bf16 v[14:17], v[162:165], v[178:181], v[14:17]
	v_mfma_f32_16x16x32_bf16 v[10:13], v[162:165], v[186:189], v[10:13]
	v_mfma_f32_16x16x32_bf16 v[6:9], v[170:173], v[178:181], v[6:9]
	v_mfma_f32_16x16x32_bf16 v[2:5], v[170:173], v[186:189], v[2:5]
	v_mfma_f32_16x16x32_bf16 v[30:33], v[150:153], v[182:185], v[30:33]
	v_mfma_f32_16x16x32_bf16 v[26:29], v[150:153], v[190:193], v[26:29]
	v_mfma_f32_16x16x32_bf16 v[22:25], v[158:161], v[182:185], v[22:25]
	v_mfma_f32_16x16x32_bf16 v[18:21], v[158:161], v[190:193], v[18:21]
	v_mfma_f32_16x16x32_bf16 v[14:17], v[166:169], v[182:185], v[14:17]
	v_mfma_f32_16x16x32_bf16 v[10:13], v[166:169], v[190:193], v[10:13]
	v_mfma_f32_16x16x32_bf16 v[6:9], v[174:177], v[182:185], v[6:9]
	v_mfma_f32_16x16x32_bf16 v[2:5], v[174:177], v[190:193], v[2:5]
	s_setprio 0
	s_barrier
	ds_read_b128 v[130:133], v208
	ds_read_b128 v[134:137], v208 offset:1024
	ds_read_b128 v[138:141], v208 offset:2048
	ds_read_b128 v[142:145], v208 offset:3072
	ds_read_b128 v[146:149], v203 offset:32768
	ds_read_b128 v[150:153], v203 offset:33792
	ds_read_b128 v[154:157], v204 offset:32768
	ds_read_b128 v[158:161], v204 offset:33792
	ds_read_b128 v[162:165], v205 offset:32768
	ds_read_b128 v[166:169], v205 offset:33792
	ds_read_b128 v[170:173], v206 offset:32768
	ds_read_b128 v[174:177], v206 offset:33792
	s_add_u32 s44, s37, s14
	s_addc_u32 s45, s42, s15
	s_mov_b32 m0, s7
	s_nop 0
	global_load_lds_dwordx4 v198, s[44:45]
	s_nop 0
	s_mov_b32 m0, s34
	s_nop 0
	global_load_lds_dwordx4 v199, s[44:45]
	s_waitcnt lgkmcnt(8)
	s_barrier
; #define STAGE(P, BASE, br, kt) do { const u16* _gb = (BASE) + (long)(br)*K + (long)(kt)*BK; \
;     unsigned _ld = lds0 + (unsigned)((char*)(P) - (char*)shm) + wv * 1024u; \
;     glds_s(_gb, voff0, _ld); glds_s(_gb, voff1, _ld + 8192u); } while (0)
; #define LDA(dst, b, h) for (int m = 0; m < 4; ++m) for (int k = 0; k < 2; ++k) \
;     dst[m][k] = *reinterpret_cast<const bf16x8*>((char*)SA(b, h) + lds_byte(wr * 64 + m * 16 + fr, k * 32 + fq * 8))
; #define LDB(dst, b, h) for (int n = 0; n < 2; ++n) for (int k = 0; k < 2; ++k) \
;     dst[n][k] = *reinterpret_cast<const bf16x8*>((char*)SB(b, h) + lds_byte(wc * 32 + n * 16 + fr, k * 32 + fq * 8))
; #define WAIT_V(n) asm volatile("s_waitcnt vmcnt(" #n ")" ::: "memory")
; #define WAIT_L(n) asm volatile("s_waitcnt lgkmcnt(" #n ")" ::: "memory")
; #define BAR __builtin_amdgcn_s_barrier()
; #define SCHED __builtin_amdgcn_sched_barrier(0)
;     ...
;       WAIT_L(8); BAR; WAIT_L(0); MMA(0, 0, At, B0); BAR; SCHED;
;       LDB(B1, 1, 1); STAGE(SB(1, 0), ActK, bcol, t + 3);
;       BAR; WAIT_L(0); MMA(0, 1, At, B1); BAR;
;       LDA(At, 1, 1); STAGE(SA(1, 0), WtK, brow, t + 3);
;       BAR; WAIT_L(0); MMA(1, 0, At, B0); BAR; SCHED;
;       STAGE(SB(1, 1), ActK, bcol + HALF, t + 3);
;       WAIT_V(6); BAR; MMA(1, 1, At, B1); BAR;
;     }
	s_waitcnt lgkmcnt(0)
	s_setprio 1
	s_waitcnt lgkmcnt(7)
	v_mfma_f32_16x16x32_bf16 v[126:129], v[146:149], v[130:133], v[126:129]
	v_mfma_f32_16x16x32_bf16 v[122:125], v[146:149], v[138:141], v[122:125]
	s_waitcnt lgkmcnt(5)
	v_mfma_f32_16x16x32_bf16 v[118:121], v[154:157], v[130:133], v[118:121]
	v_mfma_f32_16x16x32_bf16 v[114:117], v[154:157], v[138:141], v[114:117]
	s_waitcnt lgkmcnt(3)
	v_mfma_f32_16x16x32_bf16 v[110:113], v[162:165], v[130:133], v[110:113]
	v_mfma_f32_16x16x32_bf16 v[106:109], v[162:165], v[138:141], v[106:109]
	s_waitcnt lgkmcnt(1)
	v_mfma_f32_16x16x32_bf16 v[102:105], v[170:173], v[130:133], v[102:105]
	v_mfma_f32_16x16x32_bf16 v[98:101], v[170:173], v[138:141], v[98:101]
	v_mfma_f32_16x16x32_bf16 v[126:129], v[150:153], v[134:137], v[126:129]
	v_mfma_f32_16x16x32_bf16 v[122:125], v[150:153], v[142:145], v[122:125]
	v_mfma_f32_16x16x32_bf16 v[118:121], v[158:161], v[134:137], v[118:121]
	v_mfma_f32_16x16x32_bf16 v[114:117], v[158:161], v[142:145], v[114:117]
	v_mfma_f32_16x16x32_bf16 v[110:113], v[166:169], v[134:137], v[110:113]
	v_mfma_f32_16x16x32_bf16 v[106:109], v[166:169], v[142:145], v[106:109]
	s_waitcnt lgkmcnt(0)
	v_mfma_f32_16x16x32_bf16 v[102:105], v[174:177], v[134:137], v[102:105]
	v_mfma_f32_16x16x32_bf16 v[98:101], v[174:177], v[142:145], v[98:101]
	s_setprio 0
	s_barrier
	ds_read_b128 v[178:181], v209
	ds_read_b128 v[182:185], v209 offset:1024
	ds_read_b128 v[186:189], v209 offset:2048
	ds_read_b128 v[190:193], v209 offset:3072
	s_add_u32 s44, s46, 0x180
	s_addc_u32 s45, s47, 0
	s_mov_b32 m0, s35
	s_nop 0
	global_load_lds_dwordx4 v198, s[44:45]
	s_nop 0
	s_mov_b32 m0, s94
	s_nop 0
	global_load_lds_dwordx4 v199, s[44:45]
	s_barrier
	s_waitcnt lgkmcnt(0)
	s_setprio 1
	s_waitcnt lgkmcnt(3)
	v_mfma_f32_16x16x32_bf16 v[94:97], v[146:149], v[178:181], v[94:97]
	s_waitcnt lgkmcnt(1)
	v_mfma_f32_16x16x32_bf16 v[90:93], v[146:149], v[186:189], v[90:93]
	v_mfma_f32_16x16x32_bf16 v[86:89], v[154:157], v[178:181], v[86:89]
	v_mfma_f32_16x16x32_bf16 v[82:85], v[154:157], v[186:189], v[82:85]
	v_mfma_f32_16x16x32_bf16 v[78:81], v[162:165], v[178:181], v[78:81]
	v_mfma_f32_16x16x32_bf16 v[74:77], v[162:165], v[186:189], v[74:77]
	v_mfma_f32_16x16x32_bf16 v[70:73], v[170:173], v[178:181], v[70:73]
	v_mfma_f32_16x16x32_bf16 v[66:69], v[170:173], v[186:189], v[66:69]
	v_mfma_f32_16x16x32_bf16 v[94:97], v[150:153], v[182:185], v[94:97]
	s_waitcnt lgkmcnt(0)
	v_mfma_f32_16x16x32_bf16 v[90:93], v[150:153], v[190:193], v[90:93]
	v_mfma_f32_16x16x32_bf16 v[86:89], v[158:161], v[182:185], v[86:89]
	v_mfma_f32_16x16x32_bf16 v[82:85], v[158:161], v[190:193], v[82:85]
	v_mfma_f32_16x16x32_bf16 v[78:81], v[166:169], v[182:185], v[78:81]
	v_mfma_f32_16x16x32_bf16 v[74:77], v[166:169], v[190:193], v[74:77]
	v_mfma_f32_16x16x32_bf16 v[70:73], v[174:177], v[182:185], v[70:73]
	v_mfma_f32_16x16x32_bf16 v[66:69], v[174:177], v[190:193], v[66:69]
	s_setprio 0
	s_barrier
	ds_read_b128 v[146:149], v203 offset:49152
	ds_read_b128 v[150:153], v203 offset:50176
	ds_read_b128 v[154:157], v204 offset:49152
	ds_read_b128 v[158:161], v204 offset:50176
	ds_read_b128 v[162:165], v205 offset:49152
	ds_read_b128 v[166:169], v205 offset:50176
	ds_read_b128 v[170:173], v206 offset:49152
	ds_read_b128 v[174:177], v206 offset:50176
	s_add_u32 s44, s48, 0x180
	s_addc_u32 s45, s49, 0
	s_mov_b32 m0, s95
	s_nop 0
	global_load_lds_dwordx4 v198, s[44:45]
	s_nop 0
	s_mov_b32 m0, s22
	s_nop 0
	global_load_lds_dwordx4 v199, s[44:45]
	s_barrier
	s_waitcnt lgkmcnt(0)
	s_setprio 1
	s_waitcnt lgkmcnt(7)
	v_mfma_f32_16x16x32_bf16 v[62:65], v[146:149], v[130:133], v[62:65]
	v_mfma_f32_16x16x32_bf16 v[58:61], v[146:149], v[138:141], v[58:61]
	s_waitcnt lgkmcnt(5)
	v_mfma_f32_16x16x32_bf16 v[54:57], v[154:157], v[130:133], v[54:57]
	v_mfma_f32_16x16x32_bf16 v[50:53], v[154:157], v[138:141], v[50:53]
	s_waitcnt lgkmcnt(3)
	v_mfma_f32_16x16x32_bf16 v[46:49], v[162:165], v[130:133], v[46:49]
	v_mfma_f32_16x16x32_bf16 v[42:45], v[162:165], v[138:141], v[42:45]
	s_waitcnt lgkmcnt(1)
	v_mfma_f32_16x16x32_bf16 v[38:41], v[170:173], v[130:133], v[38:41]
	v_mfma_f32_16x16x32_bf16 v[34:37], v[170:173], v[138:141], v[34:37]
	v_mfma_f32_16x16x32_bf16 v[62:65], v[150:153], v[134:137], v[62:65]
	v_mfma_f32_16x16x32_bf16 v[58:61], v[150:153], v[142:145], v[58:61]
	v_mfma_f32_16x16x32_bf16 v[54:57], v[158:161], v[134:137], v[54:57]
	v_mfma_f32_16x16x32_bf16 v[50:53], v[158:161], v[142:145], v[50:53]
	v_mfma_f32_16x16x32_bf16 v[46:49], v[166:169], v[134:137], v[46:49]
	v_mfma_f32_16x16x32_bf16 v[42:45], v[166:169], v[142:145], v[42:45]
	s_waitcnt lgkmcnt(0)
	v_mfma_f32_16x16x32_bf16 v[38:41], v[174:177], v[134:137], v[38:41]
	v_mfma_f32_16x16x32_bf16 v[34:37], v[174:177], v[142:145], v[34:37]
	s_setprio 0
	s_barrier
	s_add_u32 s44, s50, 0x180
	s_addc_u32 s45, s51, 0
	s_mov_b32 m0, s23
	s_nop 0
	global_load_lds_dwordx4 v198, s[44:45]
	s_nop 0
	s_mov_b32 m0, s24
	s_nop 0
	global_load_lds_dwordx4 v199, s[44:45]
	s_waitcnt vmcnt(6)
	s_barrier
	s_setprio 1
	v_mfma_f32_16x16x32_bf16 v[30:33], v[146:149], v[178:181], v[30:33]
	v_mfma_f32_16x16x32_bf16 v[26:29], v[146:149], v[186:189], v[26:29]
	v_mfma_f32_16x16x32_bf16 v[22:25], v[154:157], v[178:181], v[22:25]
	v_mfma_f32_16x16x32_bf16 v[18:21], v[154:157], v[186:189], v[18:21]
	v_mfma_f32_16x16x32_bf16 v[14:17], v[162:165], v[178:181], v[14:17]
	v_mfma_f32_16x16x32_bf16 v[10:13], v[162:165], v[186:189], v[10:13]
	v_mfma_f32_16x16x32_bf16 v[6:9], v[170:173], v[178:181], v[6:9]
	v_mfma_f32_16x16x32_bf16 v[2:5], v[170:173], v[186:189], v[2:5]
	v_mfma_f32_16x16x32_bf16 v[30:33], v[150:153], v[182:185], v[30:33]
	v_mfma_f32_16x16x32_bf16 v[26:29], v[150:153], v[190:193], v[26:29]
	v_mfma_f32_16x16x32_bf16 v[22:25], v[158:161], v[182:185], v[22:25]
	v_mfma_f32_16x16x32_bf16 v[18:21], v[158:161], v[190:193], v[18:21]
	v_mfma_f32_16x16x32_bf16 v[14:17], v[166:169], v[182:185], v[14:17]
	v_mfma_f32_16x16x32_bf16 v[10:13], v[166:169], v[190:193], v[10:13]
	v_mfma_f32_16x16x32_bf16 v[6:9], v[174:177], v[182:185], v[6:9]
	v_mfma_f32_16x16x32_bf16 v[2:5], v[174:177], v[190:193], v[2:5]
	s_setprio 0
	s_add_u32 s14, s14, 0x100
	s_addc_u32 s15, s15, 0
	s_add_i32 s43, s43, 2
	s_cmp_lt_u32 s43, 12
	s_barrier
; #define STAGE(P, BASE, br, kt) do { const u16* _gb = (BASE) + (long)(br)*K + (long)(kt)*BK; \
;     unsigned _ld = lds0 + (unsigned)((char*)(P) - (char*)shm) + wv * 1024u; \
;     glds_s(_gb, voff0, _ld); glds_s(_gb, voff1, _ld + 8192u); } while (0)
; #define LDA(dst, b, h) for (int m = 0; m < 4; ++m) for (int k = 0; k < 2; ++k) \
;     dst[m][k] = *reinterpret_cast<const bf16x8*>((char*)SA(b, h) + lds_byte(wr * 64 + m * 16 + fr, k * 32 + fq * 8))
; #define LDB(dst, b, h) for (int n = 0; n < 2; ++n) for (int k = 0; k < 2; ++k) \
;     dst[n][k] = *reinterpret_cast<const bf16x8*>((char*)SB(b, h) + lds_byte(wc * 32 + n * 16 + fr, k * 32 + fq * 8))
; #define WAIT_V(n) asm volatile("s_waitcnt vmcnt(" #n ")" ::: "memory")
; #define WAIT_L(n) asm volatile("s_waitcnt lgkmcnt(" #n ")" ::: "memory")
; #define BAR __builtin_amdgcn_s_barrier()
;     ...
;     }
;     { LDB(B0, 0, 0); LDA(At, 0, 0); STAGE(SA(1, 1), WtK, brow + HALF, nt - 1);
;       BAR; WAIT_L(0); MMA(0, 0, At, B0); BAR;
;       LDB(B1, 0, 1); BAR; WAIT_L(0); MMA(0, 1, At, B1); BAR;
;       LDA(At, 0, 1); WAIT_V(4); BAR; WAIT_L(0); MMA(1, 0, At, B0); MMA(1, 1, At, B1); BAR; }
;     { LDB(B0, 1, 0); LDA(At, 1, 0); WAIT_V(2); BAR; WAIT_L(0); MMA(0, 0, At, B0); BAR;
	s_cbranch_scc1 .LBB0_648
	ds_read_b128 v[130:133], v202
	ds_read_b128 v[134:137], v202 offset:1024
	ds_read_b128 v[138:141], v202 offset:2048
	ds_read_b128 v[142:145], v202 offset:3072
	ds_read_b128 v[146:149], v203
	ds_read_b128 v[150:153], v203 offset:1024
	ds_read_b128 v[154:157], v204
	ds_read_b128 v[166:169], v204 offset:1024
	ds_read_b128 v[158:161], v205
	ds_read_b128 v[174:177], v205 offset:1024
	ds_read_b128 v[162:165], v206
	ds_read_b128 v[182:185], v206 offset:1024
	s_add_u32 s14, s18, 0x780
	s_addc_u32 s15, s19, 0
	s_mov_b32 m0, s25
	s_nop 0
	global_load_lds_dwordx4 v198, s[14:15]
	s_nop 0
	s_mov_b32 m0, s26
	s_nop 0
	global_load_lds_dwordx4 v199, s[14:15]
	s_barrier
	s_waitcnt lgkmcnt(0)
	s_setprio 1
	s_waitcnt lgkmcnt(7)
	v_mfma_f32_16x16x32_bf16 v[126:129], v[146:149], v[130:133], v[126:129]
	v_mfma_f32_16x16x32_bf16 v[122:125], v[146:149], v[138:141], v[122:125]
	s_waitcnt lgkmcnt(5)
	v_mfma_f32_16x16x32_bf16 v[118:121], v[154:157], v[130:133], v[118:121]
	v_mfma_f32_16x16x32_bf16 v[114:117], v[154:157], v[138:141], v[114:117]
	s_waitcnt lgkmcnt(3)
	v_mfma_f32_16x16x32_bf16 v[110:113], v[158:161], v[130:133], v[110:113]
	v_mfma_f32_16x16x32_bf16 v[106:109], v[158:161], v[138:141], v[106:109]
	s_waitcnt lgkmcnt(1)
	v_mfma_f32_16x16x32_bf16 v[102:105], v[162:165], v[130:133], v[102:105]
	v_mfma_f32_16x16x32_bf16 v[98:101], v[162:165], v[138:141], v[98:101]
	v_mfma_f32_16x16x32_bf16 v[126:129], v[150:153], v[134:137], v[126:129]
	v_mfma_f32_16x16x32_bf16 v[122:125], v[150:153], v[142:145], v[122:125]
	v_mfma_f32_16x16x32_bf16 v[118:121], v[166:169], v[134:137], v[118:121]
	v_mfma_f32_16x16x32_bf16 v[114:117], v[166:169], v[142:145], v[114:117]
	v_mfma_f32_16x16x32_bf16 v[186:189], v[174:177], v[134:137], v[110:113]
	v_mfma_f32_16x16x32_bf16 v[190:193], v[174:177], v[142:145], v[106:109]
	s_waitcnt lgkmcnt(0)
	v_mfma_f32_16x16x32_bf16 v[210:213], v[182:185], v[134:137], v[102:105]
	v_mfma_f32_16x16x32_bf16 v[214:217], v[182:185], v[142:145], v[98:101]
	s_setprio 0
	s_barrier
	s_nop 0
	ds_read_b128 v[98:101], v207
	ds_read_b128 v[102:105], v207 offset:1024
	ds_read_b128 v[106:109], v207 offset:2048
	ds_read_b128 v[194:197], v207 offset:3072
	s_barrier
	s_waitcnt lgkmcnt(0)
	s_setprio 1
	s_waitcnt lgkmcnt(3)
	v_mfma_f32_16x16x32_bf16 v[94:97], v[146:149], v[98:101], v[94:97]
	s_waitcnt lgkmcnt(1)
	v_mfma_f32_16x16x32_bf16 v[90:93], v[146:149], v[106:109], v[90:93]
	v_mfma_f32_16x16x32_bf16 v[86:89], v[154:157], v[98:101], v[86:89]
	v_mfma_f32_16x16x32_bf16 v[82:85], v[154:157], v[106:109], v[82:85]
	v_mfma_f32_16x16x32_bf16 v[78:81], v[158:161], v[98:101], v[78:81]
	v_mfma_f32_16x16x32_bf16 v[74:77], v[158:161], v[106:109], v[74:77]
	v_mfma_f32_16x16x32_bf16 v[70:73], v[162:165], v[98:101], v[70:73]
	v_mfma_f32_16x16x32_bf16 v[66:69], v[162:165], v[106:109], v[66:69]
	v_mfma_f32_16x16x32_bf16 v[110:113], v[150:153], v[102:105], v[94:97]
	s_waitcnt lgkmcnt(0)
	v_mfma_f32_16x16x32_bf16 v[158:161], v[150:153], v[194:197], v[90:93]
	v_mfma_f32_16x16x32_bf16 v[162:165], v[166:169], v[102:105], v[86:89]
	v_mfma_f32_16x16x32_bf16 v[166:169], v[166:169], v[194:197], v[82:85]
	v_mfma_f32_16x16x32_bf16 v[170:173], v[174:177], v[102:105], v[78:81]
	v_mfma_f32_16x16x32_bf16 v[174:177], v[174:177], v[194:197], v[74:77]
	v_mfma_f32_16x16x32_bf16 v[178:181], v[182:185], v[102:105], v[70:73]
	v_mfma_f32_16x16x32_bf16 v[182:185], v[182:185], v[194:197], v[66:69]
	s_setprio 0
	s_barrier
	ds_read_b128 v[82:85], v203 offset:16384
	ds_read_b128 v[86:89], v203 offset:17408
	ds_read_b128 v[90:93], v204 offset:16384
	ds_read_b128 v[94:97], v204 offset:17408
	ds_read_b128 v[146:149], v205 offset:16384
	ds_read_b128 v[150:153], v205 offset:17408
	ds_read_b128 v[154:157], v206 offset:16384
	ds_read_b128 v[218:221], v206 offset:17408
	s_waitcnt vmcnt(4)
	s_barrier
	s_waitcnt lgkmcnt(0)
	s_setprio 1
	s_waitcnt lgkmcnt(7)
	v_mfma_f32_16x16x32_bf16 v[58:61], v[82:85], v[138:141], v[58:61]
	s_waitcnt lgkmcnt(5)
	v_mfma_f32_16x16x32_bf16 v[54:57], v[90:93], v[130:133], v[54:57]
	v_mfma_f32_16x16x32_bf16 v[50:53], v[90:93], v[138:141], v[50:53]
	s_waitcnt lgkmcnt(3)
	v_mfma_f32_16x16x32_bf16 v[66:69], v[146:149], v[130:133], v[46:49]
	v_mfma_f32_16x16x32_bf16 v[70:73], v[146:149], v[138:141], v[42:45]
	s_waitcnt lgkmcnt(1)
	v_mfma_f32_16x16x32_bf16 v[74:77], v[154:157], v[130:133], v[38:41]
	v_mfma_f32_16x16x32_bf16 v[78:81], v[154:157], v[138:141], v[34:37]
	v_mfma_f32_16x16x32_bf16 v[62:65], v[82:85], v[130:133], v[62:65]
	v_mfma_f32_16x16x32_bf16 v[34:37], v[86:89], v[134:137], v[62:65]
	v_mfma_f32_16x16x32_bf16 v[38:41], v[86:89], v[142:145], v[58:61]
	v_mfma_f32_16x16x32_bf16 v[42:45], v[94:97], v[134:137], v[54:57]
	v_mfma_f32_16x16x32_bf16 v[46:49], v[94:97], v[142:145], v[50:53]
	v_mfma_f32_16x16x32_bf16 v[66:69], v[150:153], v[134:137], v[66:69]
	v_mfma_f32_16x16x32_bf16 v[70:73], v[150:153], v[142:145], v[70:73]
	s_waitcnt lgkmcnt(0)
	v_mfma_f32_16x16x32_bf16 v[74:77], v[218:221], v[134:137], v[74:77]
	v_mfma_f32_16x16x32_bf16 v[78:81], v[218:221], v[142:145], v[78:81]
	s_setprio 0
	s_setprio 1
	v_mfma_f32_16x16x32_bf16 v[30:33], v[82:85], v[98:101], v[30:33]
	v_mfma_f32_16x16x32_bf16 v[26:29], v[82:85], v[106:109], v[26:29]
	v_mfma_f32_16x16x32_bf16 v[22:25], v[90:93], v[98:101], v[22:25]
	v_mfma_f32_16x16x32_bf16 v[18:21], v[90:93], v[106:109], v[18:21]
	v_mfma_f32_16x16x32_bf16 v[50:53], v[146:149], v[98:101], v[14:17]
	v_mfma_f32_16x16x32_bf16 v[54:57], v[146:149], v[106:109], v[10:13]
	v_mfma_f32_16x16x32_bf16 v[58:61], v[154:157], v[98:101], v[6:9]
	v_mfma_f32_16x16x32_bf16 v[62:65], v[154:157], v[106:109], v[2:5]
	v_mfma_f32_16x16x32_bf16 v[2:5], v[86:89], v[102:105], v[30:33]
	v_mfma_f32_16x16x32_bf16 v[6:9], v[86:89], v[194:197], v[26:29]
	v_mfma_f32_16x16x32_bf16 v[10:13], v[94:97], v[102:105], v[22:25]
	v_mfma_f32_16x16x32_bf16 v[14:17], v[94:97], v[194:197], v[18:21]
	v_mfma_f32_16x16x32_bf16 v[130:133], v[150:153], v[102:105], v[50:53]
	v_mfma_f32_16x16x32_bf16 v[134:137], v[150:153], v[194:197], v[54:57]
	v_mfma_f32_16x16x32_bf16 v[138:141], v[218:221], v[102:105], v[58:61]
	v_mfma_f32_16x16x32_bf16 v[142:145], v[218:221], v[194:197], v[62:65]
	s_setprio 0
	s_barrier
; #define STAGE(P, BASE, br, kt) do { const u16* _gb = (BASE) + (long)(br)*K + (long)(kt)*BK; \
;     unsigned _ld = lds0 + (unsigned)((char*)(P) - (char*)shm) + wv * 1024u; \
;     glds_s(_gb, voff0, _ld); glds_s(_gb, voff1, _ld + 8192u); } while (0)
; #define LDA(dst, b, h) for (int m = 0; m < 4; ++m) for (int k = 0; k < 2; ++k) \
;     dst[m][k] = *reinterpret_cast<const bf16x8*>((char*)SA(b, h) + lds_byte(wr * 64 + m * 16 + fr, k * 32 + fq * 8))
; #define LDB(dst, b, h) for (int n = 0; n < 2; ++n) for (int k = 0; k < 2; ++k) \
;     dst[n][k] = *reinterpret_cast<const bf16x8*>((char*)SB(b, h) + lds_byte(wc * 32 + n * 16 + fr, k * 32 + fq * 8))
; #define WAIT_V(n) asm volatile("s_waitcnt vmcnt(" #n ")" ::: "memory")
; #define WAIT_L(n) asm volatile("s_waitcnt lgkmcnt(" #n ")" ::: "memory")
; #define BAR __builtin_amdgcn_s_barrier()
;     ...
;     { LDB(B0, 1, 0); LDA(At, 1, 0); WAIT_V(2); BAR; WAIT_L(0); MMA(0, 0, At, B0); BAR;
;       LDB(B1, 1, 1);
;       if (has_next) { STAGE(SB(0, 0), ActN, nbcol, 0); STAGE(SA(0, 0), WtN, nbrow, 0); WAIT_V(4); } else { WAIT_V(0); }
;       BAR; WAIT_L(0); MMA(0, 1, At, B1); BAR;
;       LDA(At, 1, 1);
;       if (has_next) { STAGE(SB(0, 1), ActN, nbcol + HALF, 0); STAGE(SA(0, 1), WtN, nbrow + HALF, 0); }
;       BAR; WAIT_L(0); MMA(1, 0, At, B0); MMA(1, 1, At, B1); BAR; }
	ds_read_b128 v[102:105], v208
	ds_read_b128 v[98:101], v208 offset:1024
	ds_read_b128 v[106:109], v208 offset:2048
	ds_read_b128 v[146:149], v208 offset:3072
	ds_read_b128 v[26:29], v203 offset:32768
	ds_read_b128 v[18:21], v203 offset:33792
	ds_read_b128 v[30:33], v204 offset:32768
	ds_read_b128 v[22:25], v204 offset:33792
	ds_read_b128 v[54:57], v205 offset:32768
	ds_read_b128 v[50:53], v205 offset:33792
	ds_read_b128 v[58:61], v206 offset:32768
	ds_read_b128 v[194:197], v206 offset:33792
	s_waitcnt vmcnt(2)
	s_barrier
	s_waitcnt lgkmcnt(0)
	s_setprio 1
	s_waitcnt lgkmcnt(7)
	v_mfma_f32_16x16x32_bf16 v[82:85], v[26:29], v[106:109], v[122:125]
	s_waitcnt lgkmcnt(5)
	v_mfma_f32_16x16x32_bf16 v[86:89], v[30:33], v[102:105], v[118:121]
	v_mfma_f32_16x16x32_bf16 v[90:93], v[30:33], v[106:109], v[114:117]
	s_waitcnt lgkmcnt(3)
	v_mfma_f32_16x16x32_bf16 v[114:117], v[54:57], v[102:105], v[186:189]
	v_mfma_f32_16x16x32_bf16 v[150:153], v[54:57], v[106:109], v[190:193]
	s_waitcnt lgkmcnt(1)
	v_mfma_f32_16x16x32_bf16 v[154:157], v[58:61], v[102:105], v[210:213]
	v_mfma_f32_16x16x32_bf16 v[186:189], v[58:61], v[106:109], v[214:217]
	v_mfma_f32_16x16x32_bf16 v[62:65], v[26:29], v[102:105], v[126:129]
	v_mfma_f32_16x16x32_bf16 v[126:129], v[18:21], v[98:101], v[62:65]
	v_mfma_f32_16x16x32_bf16 v[94:97], v[18:21], v[146:149], v[82:85]
	v_mfma_f32_16x16x32_bf16 v[122:125], v[22:25], v[98:101], v[86:89]
	v_mfma_f32_16x16x32_bf16 v[90:93], v[22:25], v[146:149], v[90:93]
	v_mfma_f32_16x16x32_bf16 v[118:121], v[50:53], v[98:101], v[114:117]
	v_mfma_f32_16x16x32_bf16 v[86:89], v[50:53], v[146:149], v[150:153]
	s_waitcnt lgkmcnt(0)
	v_mfma_f32_16x16x32_bf16 v[114:117], v[194:197], v[98:101], v[154:157]
	v_mfma_f32_16x16x32_bf16 v[82:85], v[194:197], v[146:149], v[186:189]
	s_setprio 0
	s_barrier
	s_nop 0
	ds_read_b128 v[186:189], v209
	ds_read_b128 v[150:153], v209 offset:1024
	ds_read_b128 v[190:193], v209 offset:2048
	ds_read_b128 v[154:157], v209 offset:3072
	v_readlane_b32 s16, v255, 27
	v_readlane_b32 s17, v255, 28
	s_mov_b64 s[14:15], -1
	s_and_b64 vcc, exec, s[16:17]
	s_cbranch_vccz .LBB0_651
	s_waitcnt vmcnt(0)
	s_mov_b64 s[14:15], 0
.LBB0_651:
	s_mov_b32 s44, 0xffff0000
	s_andn2_b64 vcc, exec, s[14:15]
	s_mov_b32 s46, 0x800000
	s_movk_i32 s27, 0x420
	s_mov_b32 s45, -1
	s_mov_b64 s[48:49], 0x200000
	s_mov_b64 s[50:51], 0x60
	s_cbranch_vccnz .LBB0_653
	s_mov_b32 s5, s93
	s_ashr_i32 s93, s92, 31
	s_lshl_b64 s[14:15], s[92:93], 11
	s_add_u32 s14, s78, s14
	s_mov_b32 s93, s5
	s_addc_u32 s15, s79, s15
	s_mov_b32 m0, s8
	s_nop 0
	global_load_lds_dwordx4 v198, s[14:15]
	s_nop 0
	s_mov_b32 m0, s40
	s_nop 0
	global_load_lds_dwordx4 v199, s[14:15]
	s_mov_b32 s5, s91
	s_ashr_i32 s91, s90, 31
	s_lshl_b64 s[14:15], s[90:91], 11
	s_add_u32 s14, s5, s14
	s_mov_b32 s91, s5
	s_addc_u32 s15, s93, s15
	s_mov_b32 m0, s9
	s_nop 0
	global_load_lds_dwordx4 v198, s[14:15]
	s_nop 0
	s_mov_b32 m0, s41
	s_nop 0
	global_load_lds_dwordx4 v199, s[14:15]
	s_waitcnt vmcnt(4)
.LBB0_653:
	s_barrier
	s_waitcnt lgkmcnt(0)
	s_setprio 1
	s_waitcnt lgkmcnt(3)
	v_mfma_f32_16x16x32_bf16 v[62:65], v[26:29], v[186:189], v[110:113]
	s_waitcnt lgkmcnt(1)
	v_mfma_f32_16x16x32_bf16 v[26:29], v[26:29], v[190:193], v[158:161]
	v_mfma_f32_16x16x32_bf16 v[110:113], v[30:33], v[186:189], v[162:165]
	v_mfma_f32_16x16x32_bf16 v[158:161], v[30:33], v[190:193], v[166:169]
	v_mfma_f32_16x16x32_bf16 v[162:165], v[54:57], v[186:189], v[170:173]
	v_mfma_f32_16x16x32_bf16 v[166:169], v[54:57], v[190:193], v[174:177]
	v_mfma_f32_16x16x32_bf16 v[170:173], v[58:61], v[186:189], v[178:181]
	v_mfma_f32_16x16x32_bf16 v[174:177], v[58:61], v[190:193], v[182:185]
	v_mfma_f32_16x16x32_bf16 v[62:65], v[18:21], v[150:153], v[62:65]
	s_waitcnt lgkmcnt(0)
	v_mfma_f32_16x16x32_bf16 v[30:33], v[18:21], v[154:157], v[26:29]
	v_mfma_f32_16x16x32_bf16 v[58:61], v[22:25], v[150:153], v[110:113]
	v_mfma_f32_16x16x32_bf16 v[26:29], v[22:25], v[154:157], v[158:161]
	v_mfma_f32_16x16x32_bf16 v[54:57], v[50:53], v[150:153], v[162:165]
	v_mfma_f32_16x16x32_bf16 v[22:25], v[50:53], v[154:157], v[166:169]
	v_mfma_f32_16x16x32_bf16 v[50:53], v[194:197], v[150:153], v[170:173]
	v_mfma_f32_16x16x32_bf16 v[18:21], v[194:197], v[154:157], v[174:177]
	s_setprio 0
	s_barrier
	s_nop 0
	ds_read_b128 v[174:177], v203 offset:49152
	ds_read_b128 v[158:161], v203 offset:50176
	ds_read_b128 v[178:181], v204 offset:49152
	ds_read_b128 v[162:165], v204 offset:50176
	ds_read_b128 v[182:185], v205 offset:49152
	ds_read_b128 v[166:169], v205 offset:50176
	ds_read_b128 v[194:197], v206 offset:49152
	ds_read_b128 v[170:173], v206 offset:50176
	s_andn2_b64 vcc, exec, s[12:13]
	s_cbranch_vccnz .LBB0_655
	s_or_b32 s12, s92, 0x80
	s_ashr_i32 s13, s12, 31
	s_lshl_b64 s[12:13], s[12:13], 11
	s_add_u32 s12, s78, s12
	s_addc_u32 s13, s79, s13
	s_mov_b32 m0, s97
	s_nop 0
	global_load_lds_dwordx4 v198, s[12:13]
	s_nop 0
	s_mov_b32 m0, s6
	s_nop 0
	global_load_lds_dwordx4 v199, s[12:13]
	s_or_b32 s12, s90, 0x80
	s_ashr_i32 s13, s12, 31
	s_lshl_b64 s[12:13], s[12:13], 11
	s_add_u32 s12, s91, s12
	s_addc_u32 s13, s93, s13
	s_mov_b32 m0, s7
	s_nop 0
	global_load_lds_dwordx4 v198, s[12:13]
	s_nop 0
	s_mov_b32 m0, s34
	s_nop 0
	global_load_lds_dwordx4 v199, s[12:13]

; #define STAGE(P, BASE, br, kt) do { const u16* _gb = (BASE) + (long)(br)*K + (long)(kt)*BK; \
;     unsigned _ld = lds0 + (unsigned)((char*)(P) - (char*)shm) + wv * 1024u; \
;     glds_s(_gb, voff0, _ld); glds_s(_gb, voff1, _ld + 8192u); } while (0)
; #define WAIT_V(n) asm volatile("s_waitcnt vmcnt(" #n ")" ::: "memory")
; #define BAR __builtin_amdgcn_s_barrier()
;     ...
;     if (!staged) {
;       STAGE(SB(0, 0), ActK, bcol, 0); STAGE(SA(0, 0), WtK, brow, 0);
;       STAGE(SB(0, 1), ActK, bcol + HALF, 0); STAGE(SA(0, 1), WtK, brow + HALF, 0);
;       if (wr == 1) BAR;
;       WAIT_V(4); BAR;
.LBB0_1107:
	s_xor_b64 s[22:23], s[22:23], -1
	s_andn2_b64 vcc, exec, s[22:23]
	s_mov_b64 s[34:35], -1
	s_cbranch_vccnz .LBB0_1111
	s_ashr_i32 s11, s10, 31
	s_lshl_b64 s[22:23], s[10:11], 11
	s_add_u32 s24, s78, s22
	s_addc_u32 s25, s79, s23
	s_mov_b32 m0, s38
	s_nop 0
	global_load_lds_dwordx4 v198, s[24:25]
	s_ashr_i32 s13, s12, 31
	s_mov_b32 m0, s40
	s_nop 0
	global_load_lds_dwordx4 v199, s[24:25]
	s_lshl_b64 s[24:25], s[12:13], 11
	s_add_u32 s26, s36, s24
	s_addc_u32 s27, s37, s25
	s_mov_b32 m0, s39
	s_nop 0
	global_load_lds_dwordx4 v198, s[26:27]
	s_nop 0
	s_mov_b32 m0, s41
	s_nop 0
	global_load_lds_dwordx4 v199, s[26:27]
	s_add_u32 s26, s22, 0x40000
	s_addc_u32 s27, s23, 0
	s_add_u32 s30, s78, s26
	s_addc_u32 s31, s79, s27
	s_mov_b32 m0, s42
	s_nop 0
	global_load_lds_dwordx4 v198, s[30:31]
	s_nop 0
	s_mov_b32 m0, s43
	s_nop 0
	global_load_lds_dwordx4 v199, s[30:31]
	s_add_u32 s30, s24, 0x40000
	s_addc_u32 s31, s25, 0
	s_add_u32 s34, s36, s30
	s_addc_u32 s35, s37, s31
	s_mov_b32 m0, s44
	s_nop 0
	global_load_lds_dwordx4 v198, s[34:35]
	s_nop 0
	s_mov_b32 m0, s45
	s_nop 0
	global_load_lds_dwordx4 v199, s[34:35]
	s_and_saveexec_b64 s[34:35], s[54:55]
	s_cbranch_execz .LBB0_1110
	s_barrier

; #define STAGE(P, BASE, br, kt) do { const u16* _gb = (BASE) + (long)(br)*K + (long)(kt)*BK; \
;     unsigned _ld = lds0 + (unsigned)((char*)(P) - (char*)shm) + wv * 1024u; \
;     glds_s(_gb, voff0, _ld); glds_s(_gb, voff1, _ld + 8192u); } while (0)
; #define LDA(dst, b, h) for (int m = 0; m < 4; ++m) for (int k = 0; k < 2; ++k) \
;     dst[m][k] = *reinterpret_cast<const bf16x8*>((char*)SA(b, h) + lds_byte(wr * 64 + m * 16 + fr, k * 32 + fq * 8))
; #define LDB(dst, b, h) for (int n = 0; n < 2; ++n) for (int k = 0; k < 2; ++k) \
;     dst[n][k] = *reinterpret_cast<const bf16x8*>((char*)SB(b, h) + lds_byte(wc * 32 + n * 16 + fr, k * 32 + fq * 8))
; #define WAIT_V(n) asm volatile("s_waitcnt vmcnt(" #n ")" ::: "memory")
; #define WAIT_L(n) asm volatile("s_waitcnt lgkmcnt(" #n ")" ::: "memory")
; #define BAR __builtin_amdgcn_s_barrier()
; #define SCHED __builtin_amdgcn_sched_barrier(0)
;     ...
;     f32x4 acc[2][2][4][2] = {};
;     bf16x8 At[4][2], B0[2][2], B1[2][2];
;     if (!staged) {
;       STAGE(SB(0, 0), ActK, bcol, 0); STAGE(SA(0, 0), WtK, brow, 0);
;       STAGE(SB(0, 1), ActK, bcol + HALF, 0); STAGE(SA(0, 1), WtK, brow + HALF, 0);
;       if (wr == 1) BAR;
;       WAIT_V(4); BAR;
;     } else {
;       if (wr == 1) BAR;
;       WAIT_V(0); BAR;
;     }
;     STAGE(SB(1, 0), ActK, bcol, 1); STAGE(SA(1, 0), WtK, brow, 1); STAGE(SB(1, 1), ActK, bcol + HALF, 1);
;     WAIT_V(6); BAR;
;     for (int t = 0; t < nt - 2; t += 2) {
;       LDB(B0, 0, 0); SCHED; LDA(At, 0, 0); STAGE(SA(1, 1), WtK, brow + HALF, t + 1);
;       WAIT_L(8); BAR; WAIT_L(0); MMA(0, 0, At, B0); BAR; SCHED;
.LBB0_1115:
	s_add_u32 s11, s78, s22
	s_addc_u32 s13, s79, s23
	s_add_u32 s22, s11, 0x80
	s_addc_u32 s23, s13, 0
	s_mov_b32 m0, s46
	s_nop 0
	global_load_lds_dwordx4 v198, s[22:23]
	v_mov_b32_e32 v2, 0
	s_mov_b32 m0, s47
	s_nop 0
	global_load_lds_dwordx4 v199, s[22:23]
	s_add_u32 s15, s36, s24
	s_addc_u32 s17, s37, s25
	s_add_u32 s22, s15, 0x80
	s_addc_u32 s23, s17, 0
	s_add_u32 s26, s78, s26
	s_mov_b32 m0, s48
	s_nop 0
	global_load_lds_dwordx4 v198, s[22:23]
	s_addc_u32 s27, s79, s27
	s_mov_b32 m0, s49
	s_nop 0
	global_load_lds_dwordx4 v199, s[22:23]
	s_add_u32 s22, s26, 0x80
	s_addc_u32 s23, s27, 0
	s_mov_b32 m0, s50
	s_nop 0
	global_load_lds_dwordx4 v198, s[22:23]
	s_mov_b32 s34, -2
	s_mov_b32 m0, s51
	s_nop 0
	global_load_lds_dwordx4 v199, s[22:23]
	s_add_u32 s24, s36, s30
	s_addc_u32 s25, s37, s31
	s_add_u32 s30, s24, 0x100
	s_addc_u32 s31, s25, 0
	s_mov_b64 s[22:23], 0
	v_mov_b32_e32 v3, v2
	v_mov_b32_e32 v4, v2
	v_mov_b32_e32 v5, v2
	v_mov_b32_e32 v6, v2
	v_mov_b32_e32 v7, v2
	v_mov_b32_e32 v8, v2
	v_mov_b32_e32 v9, v2
	v_mov_b32_e32 v10, v2
	v_mov_b32_e32 v11, v2
	v_mov_b32_e32 v12, v2
	v_mov_b32_e32 v13, v2
	v_mov_b32_e32 v14, v2
	v_mov_b32_e32 v15, v2
	v_mov_b32_e32 v16, v2
	v_mov_b32_e32 v17, v2
	v_mov_b32_e32 v18, v2
	v_mov_b32_e32 v19, v2
	v_mov_b32_e32 v20, v2
	v_mov_b32_e32 v21, v2
	v_mov_b32_e32 v22, v2
	v_mov_b32_e32 v23, v2
	v_mov_b32_e32 v24, v2
	v_mov_b32_e32 v25, v2
	v_mov_b32_e32 v26, v2
	v_mov_b32_e32 v27, v2
	v_mov_b32_e32 v28, v2
	v_mov_b32_e32 v29, v2
	v_mov_b32_e32 v30, v2
	v_mov_b32_e32 v31, v2
	v_mov_b32_e32 v32, v2
	v_mov_b32_e32 v33, v2
	v_mov_b32_e32 v34, v2
	v_mov_b32_e32 v35, v2
	v_mov_b32_e32 v36, v2
	v_mov_b32_e32 v37, v2
	v_mov_b32_e32 v38, v2
	v_mov_b32_e32 v39, v2
	v_mov_b32_e32 v40, v2
	v_mov_b32_e32 v41, v2
	v_mov_b32_e32 v42, v2
	v_mov_b32_e32 v43, v2
	v_mov_b32_e32 v44, v2
	v_mov_b32_e32 v45, v2
	v_mov_b32_e32 v46, v2
	v_mov_b32_e32 v47, v2
	v_mov_b32_e32 v48, v2
	v_mov_b32_e32 v49, v2
	v_mov_b32_e32 v50, v2
	v_mov_b32_e32 v51, v2
	v_mov_b32_e32 v52, v2
	v_mov_b32_e32 v53, v2
	v_mov_b32_e32 v54, v2
	v_mov_b32_e32 v55, v2
	v_mov_b32_e32 v56, v2
	v_mov_b32_e32 v57, v2
	v_mov_b32_e32 v58, v2
	v_mov_b32_e32 v59, v2
	v_mov_b32_e32 v60, v2
	v_mov_b32_e32 v61, v2
	v_mov_b32_e32 v62, v2
	v_mov_b32_e32 v63, v2
	v_mov_b32_e32 v64, v2
	v_mov_b32_e32 v65, v2
	v_mov_b32_e32 v66, v2
	v_mov_b32_e32 v67, v2
	v_mov_b32_e32 v68, v2
	v_mov_b32_e32 v69, v2
	v_mov_b32_e32 v70, v2
	v_mov_b32_e32 v71, v2
	v_mov_b32_e32 v72, v2
	v_mov_b32_e32 v73, v2
	v_mov_b32_e32 v74, v2
	v_mov_b32_e32 v75, v2
	v_mov_b32_e32 v76, v2
	v_mov_b32_e32 v77, v2
	v_mov_b32_e32 v78, v2
	v_mov_b32_e32 v79, v2
	v_mov_b32_e32 v80, v2
	v_mov_b32_e32 v81, v2
	v_mov_b32_e32 v82, v2
	v_mov_b32_e32 v83, v2
	v_mov_b32_e32 v84, v2
	v_mov_b32_e32 v85, v2
	v_mov_b32_e32 v86, v2
	v_mov_b32_e32 v87, v2
	v_mov_b32_e32 v88, v2
	v_mov_b32_e32 v89, v2
	v_mov_b32_e32 v90, v2
	v_mov_b32_e32 v91, v2
	v_mov_b32_e32 v92, v2
	v_mov_b32_e32 v93, v2
	v_mov_b32_e32 v94, v2
	v_mov_b32_e32 v95, v2
	v_mov_b32_e32 v96, v2
	v_mov_b32_e32 v97, v2
	v_mov_b32_e32 v98, v2
	v_mov_b32_e32 v99, v2
	v_mov_b32_e32 v100, v2
	v_mov_b32_e32 v101, v2
	v_mov_b32_e32 v102, v2
	v_mov_b32_e32 v103, v2
	v_mov_b32_e32 v104, v2
	v_mov_b32_e32 v105, v2
	v_mov_b32_e32 v106, v2
	v_mov_b32_e32 v107, v2
	v_mov_b32_e32 v108, v2
	v_mov_b32_e32 v109, v2
	v_mov_b32_e32 v110, v2
	v_mov_b32_e32 v111, v2
	v_mov_b32_e32 v112, v2
	v_mov_b32_e32 v113, v2
	v_mov_b32_e32 v114, v2
	v_mov_b32_e32 v115, v2
	v_mov_b32_e32 v116, v2
	v_mov_b32_e32 v117, v2
	v_mov_b32_e32 v118, v2
	v_mov_b32_e32 v119, v2
	v_mov_b32_e32 v120, v2
	v_mov_b32_e32 v121, v2
	v_mov_b32_e32 v122, v2
	v_mov_b32_e32 v123, v2
	v_mov_b32_e32 v124, v2
	v_mov_b32_e32 v125, v2
	v_mov_b32_e32 v126, v2
	v_mov_b32_e32 v127, v2
	v_mov_b32_e32 v128, v2
	v_mov_b32_e32 v129, v2
	s_waitcnt vmcnt(6)
	s_barrier
.LBB0_1116:
	ds_read_b128 v[130:133], v202
	ds_read_b128 v[134:137], v202 offset:1024
	ds_read_b128 v[138:141], v202 offset:2048
	ds_read_b128 v[142:145], v202 offset:3072
	ds_read_b128 v[146:149], v203
	ds_read_b128 v[150:153], v203 offset:1024
	ds_read_b128 v[154:157], v204
	ds_read_b128 v[158:161], v204 offset:1024
	ds_read_b128 v[162:165], v205
	ds_read_b128 v[166:169], v205 offset:1024
	ds_read_b128 v[170:173], v206
	ds_read_b128 v[174:177], v206 offset:1024
	s_add_u32 s35, s24, s22
	s_addc_u32 s89, s25, s23
	s_add_u32 s88, s35, 0x80
	s_addc_u32 s89, s89, 0
	s_mov_b32 m0, s86
	s_nop 0
	global_load_lds_dwordx4 v198, s[88:89]
	s_nop 0
	s_mov_b32 m0, s87
	s_nop 0
	global_load_lds_dwordx4 v199, s[88:89]
	s_waitcnt lgkmcnt(8)
	s_barrier
	s_waitcnt lgkmcnt(0)
	s_setprio 1
	s_waitcnt lgkmcnt(7)
	v_mfma_f32_16x16x32_bf16 v[126:129], v[146:149], v[130:133], v[126:129]
	v_mfma_f32_16x16x32_bf16 v[122:125], v[146:149], v[138:141], v[122:125]
	s_waitcnt lgkmcnt(5)
	v_mfma_f32_16x16x32_bf16 v[118:121], v[154:157], v[130:133], v[118:121]
	v_mfma_f32_16x16x32_bf16 v[114:117], v[154:157], v[138:141], v[114:117]
	s_waitcnt lgkmcnt(3)
	v_mfma_f32_16x16x32_bf16 v[110:113], v[162:165], v[130:133], v[110:113]
	v_mfma_f32_16x16x32_bf16 v[106:109], v[162:165], v[138:141], v[106:109]
	s_waitcnt lgkmcnt(1)
	v_mfma_f32_16x16x32_bf16 v[102:105], v[170:173], v[130:133], v[102:105]
	v_mfma_f32_16x16x32_bf16 v[98:101], v[170:173], v[138:141], v[98:101]
	v_mfma_f32_16x16x32_bf16 v[126:129], v[150:153], v[134:137], v[126:129]
	v_mfma_f32_16x16x32_bf16 v[122:125], v[150:153], v[142:145], v[122:125]
	v_mfma_f32_16x16x32_bf16 v[118:121], v[158:161], v[134:137], v[118:121]
	v_mfma_f32_16x16x32_bf16 v[114:117], v[158:161], v[142:145], v[114:117]
	v_mfma_f32_16x16x32_bf16 v[110:113], v[166:169], v[134:137], v[110:113]
	v_mfma_f32_16x16x32_bf16 v[106:109], v[166:169], v[142:145], v[106:109]
	s_waitcnt lgkmcnt(0)
	v_mfma_f32_16x16x32_bf16 v[102:105], v[174:177], v[134:137], v[102:105]
	v_mfma_f32_16x16x32_bf16 v[98:101], v[174:177], v[142:145], v[98:101]
	s_setprio 0
	s_barrier
; #define STAGE(P, BASE, br, kt) do { const u16* _gb = (BASE) + (long)(br)*K + (long)(kt)*BK; \
;     unsigned _ld = lds0 + (unsigned)((char*)(P) - (char*)shm) + wv * 1024u; \
;     glds_s(_gb, voff0, _ld); glds_s(_gb, voff1, _ld + 8192u); } while (0)
; #define LDA(dst, b, h) for (int m = 0; m < 4; ++m) for (int k = 0; k < 2; ++k) \
;     dst[m][k] = *reinterpret_cast<const bf16x8*>((char*)SA(b, h) + lds_byte(wr * 64 + m * 16 + fr, k * 32 + fq * 8))
; #define LDB(dst, b, h) for (int n = 0; n < 2; ++n) for (int k = 0; k < 2; ++k) \
;     dst[n][k] = *reinterpret_cast<const bf16x8*>((char*)SB(b, h) + lds_byte(wc * 32 + n * 16 + fr, k * 32 + fq * 8))
; #define WAIT_V(n) asm volatile("s_waitcnt vmcnt(" #n ")" ::: "memory")
; #define WAIT_L(n) asm volatile("s_waitcnt lgkmcnt(" #n ")" ::: "memory")
; #define BAR __builtin_amdgcn_s_barrier()
; #define SCHED __builtin_amdgcn_sched_barrier(0)
;     ...
;       WAIT_L(8); BAR; WAIT_L(0); MMA(0, 0, At, B0); BAR; SCHED;
;       LDB(B1, 0, 1); STAGE(SB(0, 0), ActK, bcol, t + 2);
;       BAR; WAIT_L(0); MMA(0, 1, At, B1); BAR;
;       LDA(At, 0, 1); STAGE(SA(0, 0), WtK, brow, t + 2);
;       BAR; WAIT_L(0); MMA(1, 0, At, B0); BAR; SCHED;
;       STAGE(SB(0, 1), ActK, bcol + HALF, t + 2);
;       WAIT_V(6); BAR; MMA(1, 1, At, B1); BAR;
;       LDB(B0, 1, 0); SCHED; LDA(At, 1, 0); STAGE(SA(0, 1), WtK, brow + HALF, t + 2);
;       WAIT_L(8); BAR; WAIT_L(0); MMA(0, 0, At, B0); BAR; SCHED;
	ds_read_b128 v[178:181], v207
	ds_read_b128 v[182:185], v207 offset:1024
	ds_read_b128 v[186:189], v207 offset:2048
	ds_read_b128 v[190:193], v207 offset:3072
	s_add_u32 s35, s11, s22
	s_addc_u32 s90, s13, s23
	s_add_u32 s88, s35, 0x100
	s_addc_u32 s89, s90, 0
	s_mov_b32 m0, s38
	s_nop 0
	global_load_lds_dwordx4 v198, s[88:89]
	s_nop 0
	s_mov_b32 m0, s40
	s_nop 0
	global_load_lds_dwordx4 v199, s[88:89]
	s_barrier
	s_waitcnt lgkmcnt(0)
	s_setprio 1
	s_waitcnt lgkmcnt(3)
	v_mfma_f32_16x16x32_bf16 v[94:97], v[146:149], v[178:181], v[94:97]
	s_waitcnt lgkmcnt(1)
	v_mfma_f32_16x16x32_bf16 v[90:93], v[146:149], v[186:189], v[90:93]
	v_mfma_f32_16x16x32_bf16 v[86:89], v[154:157], v[178:181], v[86:89]
	v_mfma_f32_16x16x32_bf16 v[82:85], v[154:157], v[186:189], v[82:85]
	v_mfma_f32_16x16x32_bf16 v[78:81], v[162:165], v[178:181], v[78:81]
	v_mfma_f32_16x16x32_bf16 v[74:77], v[162:165], v[186:189], v[74:77]
	v_mfma_f32_16x16x32_bf16 v[70:73], v[170:173], v[178:181], v[70:73]
	v_mfma_f32_16x16x32_bf16 v[66:69], v[170:173], v[186:189], v[66:69]
	v_mfma_f32_16x16x32_bf16 v[94:97], v[150:153], v[182:185], v[94:97]
	s_waitcnt lgkmcnt(0)
	v_mfma_f32_16x16x32_bf16 v[90:93], v[150:153], v[190:193], v[90:93]
	v_mfma_f32_16x16x32_bf16 v[86:89], v[158:161], v[182:185], v[86:89]
	v_mfma_f32_16x16x32_bf16 v[82:85], v[158:161], v[190:193], v[82:85]
	v_mfma_f32_16x16x32_bf16 v[78:81], v[166:169], v[182:185], v[78:81]
	v_mfma_f32_16x16x32_bf16 v[74:77], v[166:169], v[190:193], v[74:77]
	v_mfma_f32_16x16x32_bf16 v[70:73], v[174:177], v[182:185], v[70:73]
	v_mfma_f32_16x16x32_bf16 v[66:69], v[174:177], v[190:193], v[66:69]
	s_setprio 0
	s_barrier
	ds_read_b128 v[146:149], v203 offset:16384
	ds_read_b128 v[150:153], v203 offset:17408
	ds_read_b128 v[154:157], v204 offset:16384
	ds_read_b128 v[158:161], v204 offset:17408
	ds_read_b128 v[162:165], v205 offset:16384
	ds_read_b128 v[166:169], v205 offset:17408
	ds_read_b128 v[170:173], v206 offset:16384
	ds_read_b128 v[174:177], v206 offset:17408
	s_add_u32 s91, s15, s22
	s_addc_u32 s92, s17, s23
	s_add_u32 s88, s91, 0x100
	s_addc_u32 s89, s92, 0
	s_mov_b32 m0, s39
	s_nop 0
	global_load_lds_dwordx4 v198, s[88:89]
	s_nop 0
	s_mov_b32 m0, s41
	s_nop 0
	global_load_lds_dwordx4 v199, s[88:89]
	s_barrier
	s_waitcnt lgkmcnt(0)
	s_setprio 1
	s_waitcnt lgkmcnt(7)
	v_mfma_f32_16x16x32_bf16 v[62:65], v[146:149], v[130:133], v[62:65]
	v_mfma_f32_16x16x32_bf16 v[58:61], v[146:149], v[138:141], v[58:61]
	s_waitcnt lgkmcnt(5)
	v_mfma_f32_16x16x32_bf16 v[54:57], v[154:157], v[130:133], v[54:57]
	v_mfma_f32_16x16x32_bf16 v[50:53], v[154:157], v[138:141], v[50:53]
	s_waitcnt lgkmcnt(3)
	v_mfma_f32_16x16x32_bf16 v[46:49], v[162:165], v[130:133], v[46:49]
	v_mfma_f32_16x16x32_bf16 v[42:45], v[162:165], v[138:141], v[42:45]
	s_waitcnt lgkmcnt(1)
	v_mfma_f32_16x16x32_bf16 v[38:41], v[170:173], v[130:133], v[38:41]
	v_mfma_f32_16x16x32_bf16 v[34:37], v[170:173], v[138:141], v[34:37]
	v_mfma_f32_16x16x32_bf16 v[62:65], v[150:153], v[134:137], v[62:65]
	v_mfma_f32_16x16x32_bf16 v[58:61], v[150:153], v[142:145], v[58:61]
	v_mfma_f32_16x16x32_bf16 v[54:57], v[158:161], v[134:137], v[54:57]
	v_mfma_f32_16x16x32_bf16 v[50:53], v[158:161], v[142:145], v[50:53]
	v_mfma_f32_16x16x32_bf16 v[46:49], v[166:169], v[134:137], v[46:49]
	v_mfma_f32_16x16x32_bf16 v[42:45], v[166:169], v[142:145], v[42:45]
	s_waitcnt lgkmcnt(0)
	v_mfma_f32_16x16x32_bf16 v[38:41], v[174:177], v[134:137], v[38:41]
	v_mfma_f32_16x16x32_bf16 v[34:37], v[174:177], v[142:145], v[34:37]
	s_setprio 0
	s_barrier
	s_add_u32 s93, s26, s22
	s_addc_u32 s94, s27, s23
	s_add_u32 s88, s93, 0x100
	s_addc_u32 s89, s94, 0
	s_mov_b32 m0, s42
	s_nop 0
	global_load_lds_dwordx4 v198, s[88:89]
	s_nop 0
	s_mov_b32 m0, s43
	s_nop 0
	global_load_lds_dwordx4 v199, s[88:89]
	s_waitcnt vmcnt(6)
	s_barrier
	s_setprio 1
	v_mfma_f32_16x16x32_bf16 v[30:33], v[146:149], v[178:181], v[30:33]
	v_mfma_f32_16x16x32_bf16 v[26:29], v[146:149], v[186:189], v[26:29]
	v_mfma_f32_16x16x32_bf16 v[22:25], v[154:157], v[178:181], v[22:25]
	v_mfma_f32_16x16x32_bf16 v[18:21], v[154:157], v[186:189], v[18:21]
	v_mfma_f32_16x16x32_bf16 v[14:17], v[162:165], v[178:181], v[14:17]
	v_mfma_f32_16x16x32_bf16 v[10:13], v[162:165], v[186:189], v[10:13]
	v_mfma_f32_16x16x32_bf16 v[6:9], v[170:173], v[178:181], v[6:9]
	v_mfma_f32_16x16x32_bf16 v[2:5], v[170:173], v[186:189], v[2:5]
	v_mfma_f32_16x16x32_bf16 v[30:33], v[150:153], v[182:185], v[30:33]
	v_mfma_f32_16x16x32_bf16 v[26:29], v[150:153], v[190:193], v[26:29]
	v_mfma_f32_16x16x32_bf16 v[22:25], v[158:161], v[182:185], v[22:25]
	v_mfma_f32_16x16x32_bf16 v[18:21], v[158:161], v[190:193], v[18:21]
	v_mfma_f32_16x16x32_bf16 v[14:17], v[166:169], v[182:185], v[14:17]
	v_mfma_f32_16x16x32_bf16 v[10:13], v[166:169], v[190:193], v[10:13]
	v_mfma_f32_16x16x32_bf16 v[6:9], v[174:177], v[182:185], v[6:9]
	v_mfma_f32_16x16x32_bf16 v[2:5], v[174:177], v[190:193], v[2:5]
	s_setprio 0
	s_barrier
	ds_read_b128 v[130:133], v208
	ds_read_b128 v[134:137], v208 offset:1024
	ds_read_b128 v[138:141], v208 offset:2048
	ds_read_b128 v[142:145], v208 offset:3072
	ds_read_b128 v[146:149], v203 offset:32768
	ds_read_b128 v[150:153], v203 offset:33792
	ds_read_b128 v[154:157], v204 offset:32768
	ds_read_b128 v[158:161], v204 offset:33792
	ds_read_b128 v[162:165], v205 offset:32768
	ds_read_b128 v[166:169], v205 offset:33792
	ds_read_b128 v[170:173], v206 offset:32768
	ds_read_b128 v[174:177], v206 offset:33792
	s_add_u32 s88, s30, s22
	s_addc_u32 s89, s31, s23
	s_mov_b32 m0, s44
	s_nop 0
	global_load_lds_dwordx4 v198, s[88:89]
	s_nop 0
	s_mov_b32 m0, s45
	s_nop 0
	global_load_lds_dwordx4 v199, s[88:89]
	s_waitcnt lgkmcnt(8)
	s_barrier
; #define STAGE(P, BASE, br, kt) do { const u16* _gb = (BASE) + (long)(br)*K + (long)(kt)*BK; \
;     unsigned _ld = lds0 + (unsigned)((char*)(P) - (char*)shm) + wv * 1024u; \
;     glds_s(_gb, voff0, _ld); glds_s(_gb, voff1, _ld + 8192u); } while (0)
; #define LDA(dst, b, h) for (int m = 0; m < 4; ++m) for (int k = 0; k < 2; ++k) \
;     dst[m][k] = *reinterpret_cast<const bf16x8*>((char*)SA(b, h) + lds_byte(wr * 64 + m * 16 + fr, k * 32 + fq * 8))
; #define LDB(dst, b, h) for (int n = 0; n < 2; ++n) for (int k = 0; k < 2; ++k) \
;     dst[n][k] = *reinterpret_cast<const bf16x8*>((char*)SB(b, h) + lds_byte(wc * 32 + n * 16 + fr, k * 32 + fq * 8))
; #define WAIT_V(n) asm volatile("s_waitcnt vmcnt(" #n ")" ::: "memory")
; #define WAIT_L(n) asm volatile("s_waitcnt lgkmcnt(" #n ")" ::: "memory")
; #define BAR __builtin_amdgcn_s_barrier()
; #define SCHED __builtin_amdgcn_sched_barrier(0)
;     ...
;       LDB(B0, 1, 0); SCHED; LDA(At, 1, 0); STAGE(SA(0, 1), WtK, brow + HALF, t + 2);
;       WAIT_L(8); BAR; WAIT_L(0); MMA(0, 0, At, B0); BAR; SCHED;
;       LDB(B1, 1, 1); STAGE(SB(1, 0), ActK, bcol, t + 3);
;       BAR; WAIT_L(0); MMA(0, 1, At, B1); BAR;
;       LDA(At, 1, 1); STAGE(SA(1, 0), WtK, brow, t + 3);
;       BAR; WAIT_L(0); MMA(1, 0, At, B0); BAR; SCHED;
;       STAGE(SB(1, 1), ActK, bcol + HALF, t + 3);
;       WAIT_V(6); BAR; MMA(1, 1, At, B1); BAR;
;     }
	s_waitcnt lgkmcnt(0)
	s_setprio 1
	s_waitcnt lgkmcnt(7)
	v_mfma_f32_16x16x32_bf16 v[126:129], v[146:149], v[130:133], v[126:129]
	v_mfma_f32_16x16x32_bf16 v[122:125], v[146:149], v[138:141], v[122:125]
	s_waitcnt lgkmcnt(5)
	v_mfma_f32_16x16x32_bf16 v[118:121], v[154:157], v[130:133], v[118:121]
	v_mfma_f32_16x16x32_bf16 v[114:117], v[154:157], v[138:141], v[114:117]
	s_waitcnt lgkmcnt(3)
	v_mfma_f32_16x16x32_bf16 v[110:113], v[162:165], v[130:133], v[110:113]
	v_mfma_f32_16x16x32_bf16 v[106:109], v[162:165], v[138:141], v[106:109]
	s_waitcnt lgkmcnt(1)
	v_mfma_f32_16x16x32_bf16 v[102:105], v[170:173], v[130:133], v[102:105]
	v_mfma_f32_16x16x32_bf16 v[98:101], v[170:173], v[138:141], v[98:101]
	v_mfma_f32_16x16x32_bf16 v[126:129], v[150:153], v[134:137], v[126:129]
	v_mfma_f32_16x16x32_bf16 v[122:125], v[150:153], v[142:145], v[122:125]
	v_mfma_f32_16x16x32_bf16 v[118:121], v[158:161], v[134:137], v[118:121]
	v_mfma_f32_16x16x32_bf16 v[114:117], v[158:161], v[142:145], v[114:117]
	v_mfma_f32_16x16x32_bf16 v[110:113], v[166:169], v[134:137], v[110:113]
	v_mfma_f32_16x16x32_bf16 v[106:109], v[166:169], v[142:145], v[106:109]
	s_waitcnt lgkmcnt(0)
	v_mfma_f32_16x16x32_bf16 v[102:105], v[174:177], v[134:137], v[102:105]
	v_mfma_f32_16x16x32_bf16 v[98:101], v[174:177], v[142:145], v[98:101]
	s_setprio 0
	s_barrier
	ds_read_b128 v[178:181], v209
	ds_read_b128 v[182:185], v209 offset:1024
	ds_read_b128 v[186:189], v209 offset:2048
	ds_read_b128 v[190:193], v209 offset:3072
	s_add_u32 s88, s35, 0x180
	s_addc_u32 s89, s90, 0
	s_mov_b32 m0, s46
	s_nop 0
	global_load_lds_dwordx4 v198, s[88:89]
	s_nop 0
	s_mov_b32 m0, s47
	s_nop 0
	global_load_lds_dwordx4 v199, s[88:89]
	s_barrier
	s_waitcnt lgkmcnt(0)
	s_setprio 1
	s_waitcnt lgkmcnt(3)
	v_mfma_f32_16x16x32_bf16 v[94:97], v[146:149], v[178:181], v[94:97]
	s_waitcnt lgkmcnt(1)
	v_mfma_f32_16x16x32_bf16 v[90:93], v[146:149], v[186:189], v[90:93]
	v_mfma_f32_16x16x32_bf16 v[86:89], v[154:157], v[178:181], v[86:89]
	v_mfma_f32_16x16x32_bf16 v[82:85], v[154:157], v[186:189], v[82:85]
	v_mfma_f32_16x16x32_bf16 v[78:81], v[162:165], v[178:181], v[78:81]
	v_mfma_f32_16x16x32_bf16 v[74:77], v[162:165], v[186:189], v[74:77]
	v_mfma_f32_16x16x32_bf16 v[70:73], v[170:173], v[178:181], v[70:73]
	v_mfma_f32_16x16x32_bf16 v[66:69], v[170:173], v[186:189], v[66:69]
	v_mfma_f32_16x16x32_bf16 v[94:97], v[150:153], v[182:185], v[94:97]
	s_waitcnt lgkmcnt(0)
	v_mfma_f32_16x16x32_bf16 v[90:93], v[150:153], v[190:193], v[90:93]
	v_mfma_f32_16x16x32_bf16 v[86:89], v[158:161], v[182:185], v[86:89]
	v_mfma_f32_16x16x32_bf16 v[82:85], v[158:161], v[190:193], v[82:85]
	v_mfma_f32_16x16x32_bf16 v[78:81], v[166:169], v[182:185], v[78:81]
	v_mfma_f32_16x16x32_bf16 v[74:77], v[166:169], v[190:193], v[74:77]
	v_mfma_f32_16x16x32_bf16 v[70:73], v[174:177], v[182:185], v[70:73]
	v_mfma_f32_16x16x32_bf16 v[66:69], v[174:177], v[190:193], v[66:69]
	s_setprio 0
	s_barrier
	ds_read_b128 v[146:149], v203 offset:49152
	ds_read_b128 v[150:153], v203 offset:50176
	ds_read_b128 v[154:157], v204 offset:49152
	ds_read_b128 v[158:161], v204 offset:50176
	ds_read_b128 v[162:165], v205 offset:49152
	ds_read_b128 v[166:169], v205 offset:50176
	ds_read_b128 v[170:173], v206 offset:49152
	ds_read_b128 v[174:177], v206 offset:50176
	s_add_u32 s88, s91, 0x180
	s_addc_u32 s89, s92, 0
	s_mov_b32 m0, s48
	s_nop 0
	global_load_lds_dwordx4 v198, s[88:89]
	s_nop 0
	s_mov_b32 m0, s49
	s_nop 0
	global_load_lds_dwordx4 v199, s[88:89]
	s_barrier
	s_waitcnt lgkmcnt(0)
	s_setprio 1
	s_waitcnt lgkmcnt(7)
	v_mfma_f32_16x16x32_bf16 v[62:65], v[146:149], v[130:133], v[62:65]
	v_mfma_f32_16x16x32_bf16 v[58:61], v[146:149], v[138:141], v[58:61]
	s_waitcnt lgkmcnt(5)
	v_mfma_f32_16x16x32_bf16 v[54:57], v[154:157], v[130:133], v[54:57]
	v_mfma_f32_16x16x32_bf16 v[50:53], v[154:157], v[138:141], v[50:53]
	s_waitcnt lgkmcnt(3)
	v_mfma_f32_16x16x32_bf16 v[46:49], v[162:165], v[130:133], v[46:49]
	v_mfma_f32_16x16x32_bf16 v[42:45], v[162:165], v[138:141], v[42:45]
	s_waitcnt lgkmcnt(1)
	v_mfma_f32_16x16x32_bf16 v[38:41], v[170:173], v[130:133], v[38:41]
	v_mfma_f32_16x16x32_bf16 v[34:37], v[170:173], v[138:141], v[34:37]
	v_mfma_f32_16x16x32_bf16 v[62:65], v[150:153], v[134:137], v[62:65]
	v_mfma_f32_16x16x32_bf16 v[58:61], v[150:153], v[142:145], v[58:61]
	v_mfma_f32_16x16x32_bf16 v[54:57], v[158:161], v[134:137], v[54:57]
	v_mfma_f32_16x16x32_bf16 v[50:53], v[158:161], v[142:145], v[50:53]
	v_mfma_f32_16x16x32_bf16 v[46:49], v[166:169], v[134:137], v[46:49]
	v_mfma_f32_16x16x32_bf16 v[42:45], v[166:169], v[142:145], v[42:45]
	s_waitcnt lgkmcnt(0)
	v_mfma_f32_16x16x32_bf16 v[38:41], v[174:177], v[134:137], v[38:41]
	v_mfma_f32_16x16x32_bf16 v[34:37], v[174:177], v[142:145], v[34:37]
	s_setprio 0
	s_barrier
	s_add_u32 s88, s93, 0x180
	s_addc_u32 s89, s94, 0
	s_mov_b32 m0, s50
	s_nop 0
	global_load_lds_dwordx4 v198, s[88:89]
	s_nop 0
	s_mov_b32 m0, s51
	s_nop 0
	global_load_lds_dwordx4 v199, s[88:89]
	s_waitcnt vmcnt(6)
	s_barrier
	s_setprio 1
	v_mfma_f32_16x16x32_bf16 v[30:33], v[146:149], v[178:181], v[30:33]
	v_mfma_f32_16x16x32_bf16 v[26:29], v[146:149], v[186:189], v[26:29]
	v_mfma_f32_16x16x32_bf16 v[22:25], v[154:157], v[178:181], v[22:25]
	v_mfma_f32_16x16x32_bf16 v[18:21], v[154:157], v[186:189], v[18:21]
	v_mfma_f32_16x16x32_bf16 v[14:17], v[162:165], v[178:181], v[14:17]
	v_mfma_f32_16x16x32_bf16 v[10:13], v[162:165], v[186:189], v[10:13]
	v_mfma_f32_16x16x32_bf16 v[6:9], v[170:173], v[178:181], v[6:9]
	v_mfma_f32_16x16x32_bf16 v[2:5], v[170:173], v[186:189], v[2:5]
	v_mfma_f32_16x16x32_bf16 v[30:33], v[150:153], v[182:185], v[30:33]
	v_mfma_f32_16x16x32_bf16 v[26:29], v[150:153], v[190:193], v[26:29]
	v_mfma_f32_16x16x32_bf16 v[22:25], v[158:161], v[182:185], v[22:25]
	v_mfma_f32_16x16x32_bf16 v[18:21], v[158:161], v[190:193], v[18:21]
	v_mfma_f32_16x16x32_bf16 v[14:17], v[166:169], v[182:185], v[14:17]
	v_mfma_f32_16x16x32_bf16 v[10:13], v[166:169], v[190:193], v[10:13]
	v_mfma_f32_16x16x32_bf16 v[6:9], v[174:177], v[182:185], v[6:9]
	v_mfma_f32_16x16x32_bf16 v[2:5], v[174:177], v[190:193], v[2:5]
	s_setprio 0
	s_add_u32 s22, s22, 0x100
	s_addc_u32 s23, s23, 0
	s_add_i32 s34, s34, 2
	s_cmp_lt_u32 s34, 12
	s_barrier
; #define STAGE(P, BASE, br, kt) do { const u16* _gb = (BASE) + (long)(br)*K + (long)(kt)*BK; \
;     unsigned _ld = lds0 + (unsigned)((char*)(P) - (char*)shm) + wv * 1024u; \
;     glds_s(_gb, voff0, _ld); glds_s(_gb, voff1, _ld + 8192u); } while (0)
; #define LDA(dst, b, h) for (int m = 0; m < 4; ++m) for (int k = 0; k < 2; ++k) \
;     dst[m][k] = *reinterpret_cast<const bf16x8*>((char*)SA(b, h) + lds_byte(wr * 64 + m * 16 + fr, k * 32 + fq * 8))
; #define LDB(dst, b, h) for (int n = 0; n < 2; ++n) for (int k = 0; k < 2; ++k) \
;     dst[n][k] = *reinterpret_cast<const bf16x8*>((char*)SB(b, h) + lds_byte(wc * 32 + n * 16 + fr, k * 32 + fq * 8))
; #define WAIT_V(n) asm volatile("s_waitcnt vmcnt(" #n ")" ::: "memory")
; #define WAIT_L(n) asm volatile("s_waitcnt lgkmcnt(" #n ")" ::: "memory")
; #define BAR __builtin_amdgcn_s_barrier()
;     ...
;     for (int t = 0; t < nt - 2; t += 2) {
;     ...
;     { LDB(B0, 0, 0); LDA(At, 0, 0); STAGE(SA(1, 1), WtK, brow + HALF, nt - 1);
;       BAR; WAIT_L(0); MMA(0, 0, At, B0); BAR;
;       LDB(B1, 0, 1); BAR; WAIT_L(0); MMA(0, 1, At, B1); BAR;
;       LDA(At, 0, 1); WAIT_V(4); BAR; WAIT_L(0); MMA(1, 0, At, B0); MMA(1, 1, At, B1); BAR; }
	s_cbranch_scc1 .LBB0_1116
	ds_read_b128 v[130:133], v202
	ds_read_b128 v[134:137], v202 offset:1024
	ds_read_b128 v[138:141], v202 offset:2048
	ds_read_b128 v[142:145], v202 offset:3072
	ds_read_b128 v[146:149], v203
	ds_read_b128 v[150:153], v203 offset:1024
	ds_read_b128 v[154:157], v204
	ds_read_b128 v[166:169], v204 offset:1024
	ds_read_b128 v[158:161], v205
	ds_read_b128 v[174:177], v205 offset:1024
	ds_read_b128 v[162:165], v206
	ds_read_b128 v[182:185], v206 offset:1024
	s_add_u32 s22, s24, 0x780
	s_addc_u32 s23, s25, 0
	s_mov_b32 m0, s86
	s_nop 0
	global_load_lds_dwordx4 v198, s[22:23]
	s_nop 0
	s_mov_b32 m0, s87
	s_nop 0
	global_load_lds_dwordx4 v199, s[22:23]
	s_barrier
	s_waitcnt lgkmcnt(0)
	s_setprio 1
	s_waitcnt lgkmcnt(7)
	v_mfma_f32_16x16x32_bf16 v[126:129], v[146:149], v[130:133], v[126:129]
	v_mfma_f32_16x16x32_bf16 v[122:125], v[146:149], v[138:141], v[122:125]
	s_waitcnt lgkmcnt(5)
	v_mfma_f32_16x16x32_bf16 v[118:121], v[154:157], v[130:133], v[118:121]
	v_mfma_f32_16x16x32_bf16 v[114:117], v[154:157], v[138:141], v[114:117]
	s_waitcnt lgkmcnt(3)
	v_mfma_f32_16x16x32_bf16 v[110:113], v[158:161], v[130:133], v[110:113]
	v_mfma_f32_16x16x32_bf16 v[106:109], v[158:161], v[138:141], v[106:109]
	s_waitcnt lgkmcnt(1)
	v_mfma_f32_16x16x32_bf16 v[102:105], v[162:165], v[130:133], v[102:105]
	v_mfma_f32_16x16x32_bf16 v[98:101], v[162:165], v[138:141], v[98:101]
	v_mfma_f32_16x16x32_bf16 v[126:129], v[150:153], v[134:137], v[126:129]
	v_mfma_f32_16x16x32_bf16 v[122:125], v[150:153], v[142:145], v[122:125]
	v_mfma_f32_16x16x32_bf16 v[186:189], v[166:169], v[134:137], v[118:121]
	v_mfma_f32_16x16x32_bf16 v[114:117], v[166:169], v[142:145], v[114:117]
	v_mfma_f32_16x16x32_bf16 v[190:193], v[174:177], v[134:137], v[110:113]
	v_mfma_f32_16x16x32_bf16 v[106:109], v[174:177], v[142:145], v[106:109]
	s_waitcnt lgkmcnt(0)
	v_mfma_f32_16x16x32_bf16 v[210:213], v[182:185], v[134:137], v[102:105]
	v_mfma_f32_16x16x32_bf16 v[214:217], v[182:185], v[142:145], v[98:101]
	s_setprio 0
	s_barrier
	s_nop 0
	ds_read_b128 v[98:101], v207
	ds_read_b128 v[102:105], v207 offset:1024
	ds_read_b128 v[110:113], v207 offset:2048
	ds_read_b128 v[194:197], v207 offset:3072
	s_barrier
	s_waitcnt lgkmcnt(0)
	s_setprio 1
	s_waitcnt lgkmcnt(3)
	v_mfma_f32_16x16x32_bf16 v[94:97], v[146:149], v[98:101], v[94:97]
	s_waitcnt lgkmcnt(1)
	v_mfma_f32_16x16x32_bf16 v[90:93], v[146:149], v[110:113], v[90:93]
	v_mfma_f32_16x16x32_bf16 v[86:89], v[154:157], v[98:101], v[86:89]
	v_mfma_f32_16x16x32_bf16 v[82:85], v[154:157], v[110:113], v[82:85]
	v_mfma_f32_16x16x32_bf16 v[78:81], v[158:161], v[98:101], v[78:81]
	v_mfma_f32_16x16x32_bf16 v[74:77], v[158:161], v[110:113], v[74:77]
	v_mfma_f32_16x16x32_bf16 v[70:73], v[162:165], v[98:101], v[70:73]
	v_mfma_f32_16x16x32_bf16 v[66:69], v[162:165], v[110:113], v[66:69]
	v_mfma_f32_16x16x32_bf16 v[118:121], v[150:153], v[102:105], v[94:97]
	s_waitcnt lgkmcnt(0)
	v_mfma_f32_16x16x32_bf16 v[158:161], v[150:153], v[194:197], v[90:93]
	v_mfma_f32_16x16x32_bf16 v[162:165], v[166:169], v[102:105], v[86:89]
	v_mfma_f32_16x16x32_bf16 v[166:169], v[166:169], v[194:197], v[82:85]
	v_mfma_f32_16x16x32_bf16 v[170:173], v[174:177], v[102:105], v[78:81]
	v_mfma_f32_16x16x32_bf16 v[174:177], v[174:177], v[194:197], v[74:77]
	v_mfma_f32_16x16x32_bf16 v[178:181], v[182:185], v[102:105], v[70:73]
	v_mfma_f32_16x16x32_bf16 v[182:185], v[182:185], v[194:197], v[66:69]
	s_setprio 0
	s_barrier
	ds_read_b128 v[74:77], v203 offset:16384
	ds_read_b128 v[82:85], v203 offset:17408
	ds_read_b128 v[90:93], v204 offset:16384
	ds_read_b128 v[94:97], v204 offset:17408
	ds_read_b128 v[146:149], v205 offset:16384
	ds_read_b128 v[150:153], v205 offset:17408
	ds_read_b128 v[154:157], v206 offset:16384
	ds_read_b128 v[218:221], v206 offset:17408
	s_waitcnt vmcnt(4)
	s_barrier
	s_waitcnt lgkmcnt(0)
	s_setprio 1
	s_waitcnt lgkmcnt(7)
	v_mfma_f32_16x16x32_bf16 v[58:61], v[74:77], v[138:141], v[58:61]
	s_waitcnt lgkmcnt(5)
	v_mfma_f32_16x16x32_bf16 v[54:57], v[90:93], v[130:133], v[54:57]
	v_mfma_f32_16x16x32_bf16 v[50:53], v[90:93], v[138:141], v[50:53]
	s_waitcnt lgkmcnt(3)
	v_mfma_f32_16x16x32_bf16 v[46:49], v[146:149], v[130:133], v[46:49]
	v_mfma_f32_16x16x32_bf16 v[70:73], v[146:149], v[138:141], v[42:45]
	s_waitcnt lgkmcnt(1)
	v_mfma_f32_16x16x32_bf16 v[78:81], v[154:157], v[130:133], v[38:41]
	v_mfma_f32_16x16x32_bf16 v[86:89], v[154:157], v[138:141], v[34:37]
	v_mfma_f32_16x16x32_bf16 v[62:65], v[74:77], v[130:133], v[62:65]
	v_mfma_f32_16x16x32_bf16 v[34:37], v[82:85], v[134:137], v[62:65]
	v_mfma_f32_16x16x32_bf16 v[38:41], v[82:85], v[142:145], v[58:61]
	v_mfma_f32_16x16x32_bf16 v[42:45], v[94:97], v[134:137], v[54:57]
	v_mfma_f32_16x16x32_bf16 v[50:53], v[94:97], v[142:145], v[50:53]
	v_mfma_f32_16x16x32_bf16 v[66:69], v[150:153], v[134:137], v[46:49]
	v_mfma_f32_16x16x32_bf16 v[70:73], v[150:153], v[142:145], v[70:73]
	s_waitcnt lgkmcnt(0)
	v_mfma_f32_16x16x32_bf16 v[78:81], v[218:221], v[134:137], v[78:81]
	v_mfma_f32_16x16x32_bf16 v[86:89], v[218:221], v[142:145], v[86:89]
	s_setprio 0
	s_setprio 1
	v_mfma_f32_16x16x32_bf16 v[30:33], v[74:77], v[98:101], v[30:33]
	v_mfma_f32_16x16x32_bf16 v[26:29], v[74:77], v[110:113], v[26:29]
	v_mfma_f32_16x16x32_bf16 v[22:25], v[90:93], v[98:101], v[22:25]
	v_mfma_f32_16x16x32_bf16 v[18:21], v[90:93], v[110:113], v[18:21]
	v_mfma_f32_16x16x32_bf16 v[14:17], v[146:149], v[98:101], v[14:17]
	v_mfma_f32_16x16x32_bf16 v[46:49], v[146:149], v[110:113], v[10:13]
	v_mfma_f32_16x16x32_bf16 v[54:57], v[154:157], v[98:101], v[6:9]
	v_mfma_f32_16x16x32_bf16 v[58:61], v[154:157], v[110:113], v[2:5]
	v_mfma_f32_16x16x32_bf16 v[2:5], v[82:85], v[102:105], v[30:33]
	v_mfma_f32_16x16x32_bf16 v[6:9], v[82:85], v[194:197], v[26:29]
	v_mfma_f32_16x16x32_bf16 v[10:13], v[94:97], v[102:105], v[22:25]
	v_mfma_f32_16x16x32_bf16 v[18:21], v[94:97], v[194:197], v[18:21]
	v_mfma_f32_16x16x32_bf16 v[130:133], v[150:153], v[102:105], v[14:17]
	v_mfma_f32_16x16x32_bf16 v[134:137], v[150:153], v[194:197], v[46:49]
	v_mfma_f32_16x16x32_bf16 v[138:141], v[218:221], v[102:105], v[54:57]
	v_mfma_f32_16x16x32_bf16 v[142:145], v[218:221], v[194:197], v[58:61]
	s_setprio 0
	s_barrier
; #define STAGE(P, BASE, br, kt) do { const u16* _gb = (BASE) + (long)(br)*K + (long)(kt)*BK; \
;     unsigned _ld = lds0 + (unsigned)((char*)(P) - (char*)shm) + wv * 1024u; \
;     glds_s(_gb, voff0, _ld); glds_s(_gb, voff1, _ld + 8192u); } while (0)
; #define LDA(dst, b, h) for (int m = 0; m < 4; ++m) for (int k = 0; k < 2; ++k) \
;     dst[m][k] = *reinterpret_cast<const bf16x8*>((char*)SA(b, h) + lds_byte(wr * 64 + m * 16 + fr, k * 32 + fq * 8))
; #define LDB(dst, b, h) for (int n = 0; n < 2; ++n) for (int k = 0; k < 2; ++k) \
;     dst[n][k] = *reinterpret_cast<const bf16x8*>((char*)SB(b, h) + lds_byte(wc * 32 + n * 16 + fr, k * 32 + fq * 8))
; #define WAIT_V(n) asm volatile("s_waitcnt vmcnt(" #n ")" ::: "memory")
; #define WAIT_L(n) asm volatile("s_waitcnt lgkmcnt(" #n ")" ::: "memory")
; #define BAR __builtin_amdgcn_s_barrier()
;     ...
;     { LDB(B0, 1, 0); LDA(At, 1, 0); WAIT_V(2); BAR; WAIT_L(0); MMA(0, 0, At, B0); BAR;
;       LDB(B1, 1, 1);
;       if (has_next) { STAGE(SB(0, 0), ActN, nbcol, 0); STAGE(SA(0, 0), WtN, nbrow, 0); WAIT_V(4); } else { WAIT_V(0); }
;       BAR; WAIT_L(0); MMA(0, 1, At, B1); BAR;
;       LDA(At, 1, 1);
;       if (has_next) { STAGE(SB(0, 1), ActN, nbcol + HALF, 0); STAGE(SA(0, 1), WtN, nbrow + HALF, 0); }
	ds_read_b128 v[102:105], v208
	ds_read_b128 v[98:101], v208 offset:1024
	ds_read_b128 v[110:113], v208 offset:2048
	ds_read_b128 v[146:149], v208 offset:3072
	ds_read_b128 v[26:29], v203 offset:32768
	ds_read_b128 v[14:17], v203 offset:33792
	ds_read_b128 v[30:33], v204 offset:32768
	ds_read_b128 v[22:25], v204 offset:33792
	ds_read_b128 v[54:57], v205 offset:32768
	ds_read_b128 v[46:49], v205 offset:33792
	ds_read_b128 v[58:61], v206 offset:32768
	ds_read_b128 v[194:197], v206 offset:33792
	s_waitcnt vmcnt(2)
	s_barrier
	s_waitcnt lgkmcnt(0)
	s_setprio 1
	s_waitcnt lgkmcnt(7)
	v_mfma_f32_16x16x32_bf16 v[74:77], v[26:29], v[110:113], v[122:125]
	s_waitcnt lgkmcnt(5)
	v_mfma_f32_16x16x32_bf16 v[82:85], v[30:33], v[102:105], v[186:189]
	v_mfma_f32_16x16x32_bf16 v[90:93], v[30:33], v[110:113], v[114:117]
	s_waitcnt lgkmcnt(3)
	v_mfma_f32_16x16x32_bf16 v[114:117], v[54:57], v[102:105], v[190:193]
	v_mfma_f32_16x16x32_bf16 v[106:109], v[54:57], v[110:113], v[106:109]
	s_waitcnt lgkmcnt(1)
	v_mfma_f32_16x16x32_bf16 v[150:153], v[58:61], v[102:105], v[210:213]
	v_mfma_f32_16x16x32_bf16 v[154:157], v[58:61], v[110:113], v[214:217]
	v_mfma_f32_16x16x32_bf16 v[62:65], v[26:29], v[102:105], v[126:129]
	v_mfma_f32_16x16x32_bf16 v[126:129], v[14:17], v[98:101], v[62:65]
	v_mfma_f32_16x16x32_bf16 v[94:97], v[14:17], v[146:149], v[74:77]
	v_mfma_f32_16x16x32_bf16 v[122:125], v[22:25], v[98:101], v[82:85]
	v_mfma_f32_16x16x32_bf16 v[90:93], v[22:25], v[146:149], v[90:93]
	v_mfma_f32_16x16x32_bf16 v[114:117], v[46:49], v[98:101], v[114:117]
	v_mfma_f32_16x16x32_bf16 v[82:85], v[46:49], v[146:149], v[106:109]
	s_waitcnt lgkmcnt(0)
	v_mfma_f32_16x16x32_bf16 v[106:109], v[194:197], v[98:101], v[150:153]
	v_mfma_f32_16x16x32_bf16 v[74:77], v[194:197], v[146:149], v[154:157]
	s_setprio 0
	s_barrier
	ds_read_b128 v[186:189], v209
	ds_read_b128 v[150:153], v209 offset:1024
	ds_read_b128 v[190:193], v209 offset:2048
	ds_read_b128 v[154:157], v209 offset:3072
	s_mov_b64 s[22:23], -1
	s_and_b64 vcc, exec, s[4:5]
	s_cbranch_vccz .LBB0_1119
	s_waitcnt vmcnt(0)
	s_mov_b64 s[22:23], 0
.LBB0_1119:
	s_andn2_b64 vcc, exec, s[22:23]
	s_cbranch_vccnz .LBB0_1121
	s_ashr_i32 s15, s14, 31
	s_lshl_b64 s[22:23], s[14:15], 11
	s_add_u32 s22, s78, s22
	s_addc_u32 s23, s79, s23
	s_mov_b32 m0, s38
	s_nop 0
	global_load_lds_dwordx4 v198, s[22:23]
	s_ashr_i32 s17, s16, 31
	s_mov_b32 m0, s40
	s_nop 0
	global_load_lds_dwordx4 v199, s[22:23]
	s_lshl_b64 s[22:23], s[16:17], 11
	s_add_u32 s22, s36, s22
	s_addc_u32 s23, s37, s23
	s_mov_b32 m0, s39
	s_nop 0
	global_load_lds_dwordx4 v198, s[22:23]
	s_nop 0
	s_mov_b32 m0, s41
	s_nop 0
	global_load_lds_dwordx4 v199, s[22:23]
	s_waitcnt vmcnt(4)
.LBB0_1121:
	s_barrier
	s_waitcnt lgkmcnt(0)
	s_setprio 1
	s_waitcnt lgkmcnt(3)
	v_mfma_f32_16x16x32_bf16 v[62:65], v[26:29], v[186:189], v[118:121]
	s_waitcnt lgkmcnt(1)
	v_mfma_f32_16x16x32_bf16 v[26:29], v[26:29], v[190:193], v[158:161]
	v_mfma_f32_16x16x32_bf16 v[118:121], v[30:33], v[186:189], v[162:165]
	v_mfma_f32_16x16x32_bf16 v[158:161], v[30:33], v[190:193], v[166:169]
	v_mfma_f32_16x16x32_bf16 v[162:165], v[54:57], v[186:189], v[170:173]
	v_mfma_f32_16x16x32_bf16 v[166:169], v[54:57], v[190:193], v[174:177]
	v_mfma_f32_16x16x32_bf16 v[170:173], v[58:61], v[186:189], v[178:181]
	v_mfma_f32_16x16x32_bf16 v[174:177], v[58:61], v[190:193], v[182:185]
	v_mfma_f32_16x16x32_bf16 v[62:65], v[14:17], v[150:153], v[62:65]
	s_waitcnt lgkmcnt(0)
	v_mfma_f32_16x16x32_bf16 v[30:33], v[14:17], v[154:157], v[26:29]
	v_mfma_f32_16x16x32_bf16 v[58:61], v[22:25], v[150:153], v[118:121]
	v_mfma_f32_16x16x32_bf16 v[26:29], v[22:25], v[154:157], v[158:161]
	v_mfma_f32_16x16x32_bf16 v[54:57], v[46:49], v[150:153], v[162:165]
	v_mfma_f32_16x16x32_bf16 v[22:25], v[46:49], v[154:157], v[166:169]
	v_mfma_f32_16x16x32_bf16 v[46:49], v[194:197], v[150:153], v[170:173]
	v_mfma_f32_16x16x32_bf16 v[14:17], v[194:197], v[154:157], v[174:177]
	s_setprio 0
	s_barrier
	s_nop 0
	ds_read_b128 v[174:177], v203 offset:49152
	ds_read_b128 v[158:161], v203 offset:50176
	ds_read_b128 v[178:181], v204 offset:49152
	ds_read_b128 v[162:165], v204 offset:50176
	ds_read_b128 v[182:185], v205 offset:49152
	ds_read_b128 v[166:169], v205 offset:50176
	ds_read_b128 v[194:197], v206 offset:49152
	ds_read_b128 v[170:173], v206 offset:50176
	s_andn2_b64 vcc, exec, s[18:19]
	s_cbranch_vccnz .LBB0_1123
	s_or_b32 s18, s14, 0x80
	s_ashr_i32 s19, s18, 31
	s_lshl_b64 s[18:19], s[18:19], 11
	s_add_u32 s18, s78, s18
	s_addc_u32 s19, s79, s19
	s_mov_b32 m0, s42
	s_nop 0
	global_load_lds_dwordx4 v198, s[18:19]
	s_nop 0
	s_mov_b32 m0, s43
	s_nop 0
	global_load_lds_dwordx4 v199, s[18:19]
	s_or_b32 s18, s16, 0x80
	s_ashr_i32 s19, s18, 31
	s_lshl_b64 s[18:19], s[18:19], 11
	s_add_u32 s18, s36, s18
	s_addc_u32 s19, s37, s19
	s_mov_b32 m0, s44
	s_nop 0
	global_load_lds_dwordx4 v198, s[18:19]
	s_nop 0
	s_mov_b32 m0, s45
	s_nop 0
	global_load_lds_dwordx4 v199, s[18:19]
